# GEMM k-loops: 4 of the 16 held-back MFMAs run before the DMA-landing wait and barrier (rest after, with the pieces)
# baseline (speedup 1.0000x reference)
.Lg0_top:
	s_waitcnt lgkmcnt(0)
	v_mfma_f32_16x16x32_bf16 v[60:63], v[172:175], v[206:209], v[60:63]
	v_mfma_f32_16x16x32_bf16 v[52:55], v[172:175], v[210:213], v[52:55]
	v_mfma_f32_16x16x32_bf16 v[56:59], v[172:175], v[214:217], v[56:59]
	v_mfma_f32_16x16x32_bf16 v[48:51], v[172:175], v[218:221], v[48:51]
	s_waitcnt vmcnt(0)
	s_barrier
	s_xor_b32 s87, s87, 0x10000
	s_mov_b32 m0, s87
	s_add_u32 s88, s60, s16
	s_addc_u32 s89, s61, s17
	global_load_lds_dwordx4 v144, s[88:89]
	ds_read_b128 v[156:159], v143
	ds_read_b128 v[160:163], v143 offset:2048
	ds_read_b128 v[164:167], v143 offset:4096
	ds_read_b128 v[168:171], v143 offset:6144
	ds_read_b128 v[190:193], v180 offset:32768
	ds_read_b128 v[194:197], v180 offset:34816
	ds_read_b128 v[198:201], v180 offset:36864
	ds_read_b128 v[202:205], v180 offset:38912
	v_mfma_f32_16x16x32_bf16 v[44:47], v[176:179], v[206:209], v[44:47]
	v_mfma_f32_16x16x32_bf16 v[36:39], v[176:179], v[210:213], v[36:39]
	s_add_u32 m0, s87, 0x2000
	s_add_u32 s88, s60, s18
	s_addc_u32 s89, s61, s19
	global_load_lds_dwordx4 v144, s[88:89]
	v_mfma_f32_16x16x32_bf16 v[40:43], v[176:179], v[214:217], v[40:43]
	v_mfma_f32_16x16x32_bf16 v[32:35], v[176:179], v[218:221], v[32:35]
	s_add_u32 m0, s87, 0x4000
	s_add_u32 s88, s60, s22
	s_addc_u32 s89, s61, s23
	global_load_lds_dwordx4 v144, s[88:89]
	v_mfma_f32_16x16x32_bf16 v[28:31], v[182:185], v[206:209], v[28:31]
	v_mfma_f32_16x16x32_bf16 v[16:19], v[182:185], v[210:213], v[16:19]
	s_add_u32 m0, s87, 0x6000
	s_add_u32 s88, s60, s40
	s_addc_u32 s89, s61, s41
	global_load_lds_dwordx4 v144, s[88:89]
	v_mfma_f32_16x16x32_bf16 v[24:27], v[182:185], v[214:217], v[24:27]
	v_mfma_f32_16x16x32_bf16 v[12:15], v[182:185], v[218:221], v[12:15]
	s_add_u32 m0, s87, 0x8000
	s_add_u32 s88, s60, s42
	s_addc_u32 s89, s61, s43
	global_load_lds_dwordx4 v145, s[88:89]
	v_mfma_f32_16x16x32_bf16 v[4:7], v[186:189], v[206:209], v[4:7]
	v_mfma_f32_16x16x32_bf16 v[0:3], v[186:189], v[210:213], v[0:3]
	s_add_u32 m0, s87, 0xa000
	s_add_u32 s88, s60, s52
	s_addc_u32 s89, s61, s53
	global_load_lds_dwordx4 v145, s[88:89]
	v_mfma_f32_16x16x32_bf16 v[20:23], v[186:189], v[214:217], v[20:23]
	v_mfma_f32_16x16x32_bf16 v[8:11], v[186:189], v[218:221], v[8:11]
	s_add_u32 m0, s87, 0xc000
	s_add_u32 s88, s60, s54
	s_addc_u32 s89, s61, s55
	global_load_lds_dwordx4 v145, s[88:89]
.Lg0_entry:
	ds_read_b128 v[172:175], v143 offset:8192
	ds_read_b128 v[176:179], v143 offset:10240
	ds_read_b128 v[182:185], v143 offset:12288
	ds_read_b128 v[186:189], v143 offset:14336
	s_waitcnt lgkmcnt(4)
	v_mfma_f32_16x16x32_bf16 v[124:127], v[156:159], v[190:193], v[124:127]
	v_mfma_f32_16x16x32_bf16 v[116:119], v[156:159], v[194:197], v[116:119]
	s_add_u32 m0, s87, 0xe000
	s_add_u32 s88, s60, s56
	s_addc_u32 s89, s61, s57
	global_load_lds_dwordx4 v145, s[88:89]
	v_mfma_f32_16x16x32_bf16 v[120:123], v[156:159], v[198:201], v[120:123]
	v_mfma_f32_16x16x32_bf16 v[112:115], v[156:159], v[202:205], v[112:115]
	v_mfma_f32_16x16x32_bf16 v[108:111], v[160:163], v[190:193], v[108:111]
	v_mfma_f32_16x16x32_bf16 v[100:103], v[160:163], v[194:197], v[100:103]
	v_mfma_f32_16x16x32_bf16 v[104:107], v[160:163], v[198:201], v[104:107]
	v_mfma_f32_16x16x32_bf16 v[96:99], v[160:163], v[202:205], v[96:99]
	v_mfma_f32_16x16x32_bf16 v[92:95], v[164:167], v[190:193], v[92:95]
	v_mfma_f32_16x16x32_bf16 v[84:87], v[164:167], v[194:197], v[84:87]
	v_mfma_f32_16x16x32_bf16 v[88:91], v[164:167], v[198:201], v[88:91]
	v_mfma_f32_16x16x32_bf16 v[80:83], v[164:167], v[202:205], v[80:83]
	v_mfma_f32_16x16x32_bf16 v[76:79], v[168:171], v[190:193], v[76:79]
	v_mfma_f32_16x16x32_bf16 v[68:71], v[168:171], v[194:197], v[68:71]
	v_mfma_f32_16x16x32_bf16 v[72:75], v[168:171], v[198:201], v[72:75]
	v_mfma_f32_16x16x32_bf16 v[64:67], v[168:171], v[202:205], v[64:67]
	ds_read_b128 v[156:159], v155
	ds_read_b128 v[160:163], v155 offset:2048
	ds_read_b128 v[164:167], v155 offset:4096
	ds_read_b128 v[168:171], v155 offset:6144
	ds_read_b128 v[206:209], v222 offset:32768
	ds_read_b128 v[210:213], v222 offset:34816
	ds_read_b128 v[214:217], v222 offset:36864
	ds_read_b128 v[218:221], v222 offset:38912
	s_waitcnt lgkmcnt(8)
	v_mfma_f32_16x16x32_bf16 v[60:63], v[172:175], v[190:193], v[60:63]
	v_mfma_f32_16x16x32_bf16 v[52:55], v[172:175], v[194:197], v[52:55]
	v_mfma_f32_16x16x32_bf16 v[56:59], v[172:175], v[198:201], v[56:59]
	v_mfma_f32_16x16x32_bf16 v[48:51], v[172:175], v[202:205], v[48:51]
	v_mfma_f32_16x16x32_bf16 v[44:47], v[176:179], v[190:193], v[44:47]
	v_mfma_f32_16x16x32_bf16 v[36:39], v[176:179], v[194:197], v[36:39]
	v_mfma_f32_16x16x32_bf16 v[40:43], v[176:179], v[198:201], v[40:43]
	v_mfma_f32_16x16x32_bf16 v[32:35], v[176:179], v[202:205], v[32:35]
	v_mfma_f32_16x16x32_bf16 v[28:31], v[182:185], v[190:193], v[28:31]
	v_mfma_f32_16x16x32_bf16 v[16:19], v[182:185], v[194:197], v[16:19]
	v_mfma_f32_16x16x32_bf16 v[24:27], v[182:185], v[198:201], v[24:27]
	v_mfma_f32_16x16x32_bf16 v[12:15], v[182:185], v[202:205], v[12:15]
	v_mfma_f32_16x16x32_bf16 v[4:7], v[186:189], v[190:193], v[4:7]
	v_mfma_f32_16x16x32_bf16 v[0:3], v[186:189], v[194:197], v[0:3]
	v_mfma_f32_16x16x32_bf16 v[20:23], v[186:189], v[198:201], v[20:23]
	v_mfma_f32_16x16x32_bf16 v[8:11], v[186:189], v[202:205], v[8:11]
	ds_read_b128 v[172:175], v155 offset:8192
	ds_read_b128 v[176:179], v155 offset:10240
	ds_read_b128 v[182:185], v155 offset:12288
	ds_read_b128 v[186:189], v155 offset:14336
	s_waitcnt lgkmcnt(4)
	v_mfma_f32_16x16x32_bf16 v[124:127], v[156:159], v[206:209], v[124:127]
	v_mfma_f32_16x16x32_bf16 v[116:119], v[156:159], v[210:213], v[116:119]
	v_mfma_f32_16x16x32_bf16 v[120:123], v[156:159], v[214:217], v[120:123]
	v_mfma_f32_16x16x32_bf16 v[112:115], v[156:159], v[218:221], v[112:115]
	v_mfma_f32_16x16x32_bf16 v[108:111], v[160:163], v[206:209], v[108:111]
	v_mfma_f32_16x16x32_bf16 v[100:103], v[160:163], v[210:213], v[100:103]
	v_mfma_f32_16x16x32_bf16 v[104:107], v[160:163], v[214:217], v[104:107]
	v_mfma_f32_16x16x32_bf16 v[96:99], v[160:163], v[218:221], v[96:99]
	v_mfma_f32_16x16x32_bf16 v[92:95], v[164:167], v[206:209], v[92:95]
	v_mfma_f32_16x16x32_bf16 v[84:87], v[164:167], v[210:213], v[84:87]
	v_mfma_f32_16x16x32_bf16 v[88:91], v[164:167], v[214:217], v[88:91]
	v_mfma_f32_16x16x32_bf16 v[80:83], v[164:167], v[218:221], v[80:83]
	v_mfma_f32_16x16x32_bf16 v[76:79], v[168:171], v[206:209], v[76:79]
	v_mfma_f32_16x16x32_bf16 v[68:71], v[168:171], v[210:213], v[68:71]
	v_mfma_f32_16x16x32_bf16 v[72:75], v[168:171], v[214:217], v[72:75]
	v_mfma_f32_16x16x32_bf16 v[64:67], v[168:171], v[218:221], v[64:67]
	s_add_u32 s60, s60, 0x80
	s_addc_u32 s61, s61, 0
	s_add_i32 s59, s59, 1
	s_cmp_lt_u32 s59, 15
	s_cbranch_scc0 .Lg0_last
	s_waitcnt lgkmcnt(0)
	v_mfma_f32_16x16x32_bf16 v[60:63], v[172:175], v[206:209], v[60:63]
	v_mfma_f32_16x16x32_bf16 v[52:55], v[172:175], v[210:213], v[52:55]
	v_mfma_f32_16x16x32_bf16 v[56:59], v[172:175], v[214:217], v[56:59]
	v_mfma_f32_16x16x32_bf16 v[48:51], v[172:175], v[218:221], v[48:51]
	s_waitcnt vmcnt(0)
	s_barrier
	s_xor_b32 s87, s87, 0x10000
	s_mov_b32 m0, s87
	s_add_u32 s88, s60, s16
	s_addc_u32 s89, s61, s17
	global_load_lds_dwordx4 v144, s[88:89]
	ds_read_b128 v[156:159], v223
	ds_read_b128 v[160:163], v223 offset:2048
	ds_read_b128 v[164:167], v223 offset:4096
	ds_read_b128 v[168:171], v223 offset:6144
	ds_read_b128 v[190:193], v225 offset:32768
	ds_read_b128 v[194:197], v225 offset:34816
	ds_read_b128 v[198:201], v225 offset:36864
	ds_read_b128 v[202:205], v225 offset:38912
	v_mfma_f32_16x16x32_bf16 v[44:47], v[176:179], v[206:209], v[44:47]
	v_mfma_f32_16x16x32_bf16 v[36:39], v[176:179], v[210:213], v[36:39]
	s_add_u32 m0, s87, 0x2000
	s_add_u32 s88, s60, s18
	s_addc_u32 s89, s61, s19
	global_load_lds_dwordx4 v144, s[88:89]
	v_mfma_f32_16x16x32_bf16 v[40:43], v[176:179], v[214:217], v[40:43]
	v_mfma_f32_16x16x32_bf16 v[32:35], v[176:179], v[218:221], v[32:35]
	s_add_u32 m0, s87, 0x4000
	s_add_u32 s88, s60, s22
	s_addc_u32 s89, s61, s23
	global_load_lds_dwordx4 v144, s[88:89]
	v_mfma_f32_16x16x32_bf16 v[28:31], v[182:185], v[206:209], v[28:31]
	v_mfma_f32_16x16x32_bf16 v[16:19], v[182:185], v[210:213], v[16:19]
	s_add_u32 m0, s87, 0x6000
	s_add_u32 s88, s60, s40
	s_addc_u32 s89, s61, s41
	global_load_lds_dwordx4 v144, s[88:89]
	v_mfma_f32_16x16x32_bf16 v[24:27], v[182:185], v[214:217], v[24:27]
	v_mfma_f32_16x16x32_bf16 v[12:15], v[182:185], v[218:221], v[12:15]
	s_add_u32 m0, s87, 0x8000
	s_add_u32 s88, s60, s42
	s_addc_u32 s89, s61, s43
	global_load_lds_dwordx4 v145, s[88:89]
	v_mfma_f32_16x16x32_bf16 v[4:7], v[186:189], v[206:209], v[4:7]
	v_mfma_f32_16x16x32_bf16 v[0:3], v[186:189], v[210:213], v[0:3]
	s_add_u32 m0, s87, 0xa000
	s_add_u32 s88, s60, s52
	s_addc_u32 s89, s61, s53
	global_load_lds_dwordx4 v145, s[88:89]
	v_mfma_f32_16x16x32_bf16 v[20:23], v[186:189], v[214:217], v[20:23]
	v_mfma_f32_16x16x32_bf16 v[8:11], v[186:189], v[218:221], v[8:11]
	s_add_u32 m0, s87, 0xc000
	s_add_u32 s88, s60, s54
	s_addc_u32 s89, s61, s55
	global_load_lds_dwordx4 v145, s[88:89]
	ds_read_b128 v[172:175], v223 offset:8192
	ds_read_b128 v[176:179], v223 offset:10240
	ds_read_b128 v[182:185], v223 offset:12288
	ds_read_b128 v[186:189], v223 offset:14336
	s_waitcnt lgkmcnt(4)
	v_mfma_f32_16x16x32_bf16 v[124:127], v[156:159], v[190:193], v[124:127]
	v_mfma_f32_16x16x32_bf16 v[116:119], v[156:159], v[194:197], v[116:119]
	s_add_u32 m0, s87, 0xe000
	s_add_u32 s88, s60, s56
	s_addc_u32 s89, s61, s57
	global_load_lds_dwordx4 v145, s[88:89]
	v_mfma_f32_16x16x32_bf16 v[120:123], v[156:159], v[198:201], v[120:123]
	v_mfma_f32_16x16x32_bf16 v[112:115], v[156:159], v[202:205], v[112:115]
	v_mfma_f32_16x16x32_bf16 v[108:111], v[160:163], v[190:193], v[108:111]
	v_mfma_f32_16x16x32_bf16 v[100:103], v[160:163], v[194:197], v[100:103]
	v_mfma_f32_16x16x32_bf16 v[104:107], v[160:163], v[198:201], v[104:107]
	v_mfma_f32_16x16x32_bf16 v[96:99], v[160:163], v[202:205], v[96:99]
	v_mfma_f32_16x16x32_bf16 v[92:95], v[164:167], v[190:193], v[92:95]
	v_mfma_f32_16x16x32_bf16 v[84:87], v[164:167], v[194:197], v[84:87]
	v_mfma_f32_16x16x32_bf16 v[88:91], v[164:167], v[198:201], v[88:91]
	v_mfma_f32_16x16x32_bf16 v[80:83], v[164:167], v[202:205], v[80:83]
	v_mfma_f32_16x16x32_bf16 v[76:79], v[168:171], v[190:193], v[76:79]
	v_mfma_f32_16x16x32_bf16 v[68:71], v[168:171], v[194:197], v[68:71]
	v_mfma_f32_16x16x32_bf16 v[72:75], v[168:171], v[198:201], v[72:75]
	v_mfma_f32_16x16x32_bf16 v[64:67], v[168:171], v[202:205], v[64:67]
	ds_read_b128 v[156:159], v224
	ds_read_b128 v[160:163], v224 offset:2048
	ds_read_b128 v[164:167], v224 offset:4096
	ds_read_b128 v[168:171], v224 offset:6144
	ds_read_b128 v[206:209], v226 offset:32768
	ds_read_b128 v[210:213], v226 offset:34816
	ds_read_b128 v[214:217], v226 offset:36864
	ds_read_b128 v[218:221], v226 offset:38912
	s_waitcnt lgkmcnt(8)
	v_mfma_f32_16x16x32_bf16 v[60:63], v[172:175], v[190:193], v[60:63]
	v_mfma_f32_16x16x32_bf16 v[52:55], v[172:175], v[194:197], v[52:55]
	v_mfma_f32_16x16x32_bf16 v[56:59], v[172:175], v[198:201], v[56:59]
	v_mfma_f32_16x16x32_bf16 v[48:51], v[172:175], v[202:205], v[48:51]
	v_mfma_f32_16x16x32_bf16 v[44:47], v[176:179], v[190:193], v[44:47]
	v_mfma_f32_16x16x32_bf16 v[36:39], v[176:179], v[194:197], v[36:39]
	v_mfma_f32_16x16x32_bf16 v[40:43], v[176:179], v[198:201], v[40:43]
	v_mfma_f32_16x16x32_bf16 v[32:35], v[176:179], v[202:205], v[32:35]
	v_mfma_f32_16x16x32_bf16 v[28:31], v[182:185], v[190:193], v[28:31]
	v_mfma_f32_16x16x32_bf16 v[16:19], v[182:185], v[194:197], v[16:19]
	v_mfma_f32_16x16x32_bf16 v[24:27], v[182:185], v[198:201], v[24:27]
	v_mfma_f32_16x16x32_bf16 v[12:15], v[182:185], v[202:205], v[12:15]
	v_mfma_f32_16x16x32_bf16 v[4:7], v[186:189], v[190:193], v[4:7]
	v_mfma_f32_16x16x32_bf16 v[0:3], v[186:189], v[194:197], v[0:3]
	v_mfma_f32_16x16x32_bf16 v[20:23], v[186:189], v[198:201], v[20:23]
	v_mfma_f32_16x16x32_bf16 v[8:11], v[186:189], v[202:205], v[8:11]
	ds_read_b128 v[172:175], v224 offset:8192
	ds_read_b128 v[176:179], v224 offset:10240
	ds_read_b128 v[182:185], v224 offset:12288
	ds_read_b128 v[186:189], v224 offset:14336
	s_waitcnt lgkmcnt(4)
	v_mfma_f32_16x16x32_bf16 v[124:127], v[156:159], v[206:209], v[124:127]
	v_mfma_f32_16x16x32_bf16 v[116:119], v[156:159], v[210:213], v[116:119]
	v_mfma_f32_16x16x32_bf16 v[120:123], v[156:159], v[214:217], v[120:123]
	v_mfma_f32_16x16x32_bf16 v[112:115], v[156:159], v[218:221], v[112:115]
	v_mfma_f32_16x16x32_bf16 v[108:111], v[160:163], v[206:209], v[108:111]
	v_mfma_f32_16x16x32_bf16 v[100:103], v[160:163], v[210:213], v[100:103]
	v_mfma_f32_16x16x32_bf16 v[104:107], v[160:163], v[214:217], v[104:107]
	v_mfma_f32_16x16x32_bf16 v[96:99], v[160:163], v[218:221], v[96:99]
	v_mfma_f32_16x16x32_bf16 v[92:95], v[164:167], v[206:209], v[92:95]
	v_mfma_f32_16x16x32_bf16 v[84:87], v[164:167], v[210:213], v[84:87]
	v_mfma_f32_16x16x32_bf16 v[88:91], v[164:167], v[214:217], v[88:91]
	v_mfma_f32_16x16x32_bf16 v[80:83], v[164:167], v[218:221], v[80:83]
	v_mfma_f32_16x16x32_bf16 v[76:79], v[168:171], v[206:209], v[76:79]
	v_mfma_f32_16x16x32_bf16 v[68:71], v[168:171], v[210:213], v[68:71]
	v_mfma_f32_16x16x32_bf16 v[72:75], v[168:171], v[214:217], v[72:75]
	v_mfma_f32_16x16x32_bf16 v[64:67], v[168:171], v[218:221], v[64:67]
	s_add_u32 s60, s60, 0x80
	s_addc_u32 s61, s61, 0
	s_add_i32 s59, s59, 1
	s_branch .Lg0_top
.Lg0_last:
	s_waitcnt lgkmcnt(0)
	v_mfma_f32_16x16x32_bf16 v[60:63], v[172:175], v[206:209], v[60:63]
	v_mfma_f32_16x16x32_bf16 v[52:55], v[172:175], v[210:213], v[52:55]
	v_mfma_f32_16x16x32_bf16 v[56:59], v[172:175], v[214:217], v[56:59]
	v_mfma_f32_16x16x32_bf16 v[48:51], v[172:175], v[218:221], v[48:51]
	s_waitcnt vmcnt(0)
	s_barrier
	s_xor_b32 s87, s87, 0x10000
	ds_read_b128 v[156:159], v223
	ds_read_b128 v[160:163], v223 offset:2048
	ds_read_b128 v[164:167], v223 offset:4096
	ds_read_b128 v[168:171], v223 offset:6144
	ds_read_b128 v[190:193], v225 offset:32768
	ds_read_b128 v[194:197], v225 offset:34816
	ds_read_b128 v[198:201], v225 offset:36864
	ds_read_b128 v[202:205], v225 offset:38912
	v_mfma_f32_16x16x32_bf16 v[44:47], v[176:179], v[206:209], v[44:47]
	v_mfma_f32_16x16x32_bf16 v[36:39], v[176:179], v[210:213], v[36:39]
	v_mfma_f32_16x16x32_bf16 v[40:43], v[176:179], v[214:217], v[40:43]
	v_mfma_f32_16x16x32_bf16 v[32:35], v[176:179], v[218:221], v[32:35]
	v_mfma_f32_16x16x32_bf16 v[28:31], v[182:185], v[206:209], v[28:31]
	v_mfma_f32_16x16x32_bf16 v[16:19], v[182:185], v[210:213], v[16:19]
	v_mfma_f32_16x16x32_bf16 v[24:27], v[182:185], v[214:217], v[24:27]
	v_mfma_f32_16x16x32_bf16 v[12:15], v[182:185], v[218:221], v[12:15]
	v_mfma_f32_16x16x32_bf16 v[4:7], v[186:189], v[206:209], v[4:7]
	v_mfma_f32_16x16x32_bf16 v[0:3], v[186:189], v[210:213], v[0:3]
	v_mfma_f32_16x16x32_bf16 v[20:23], v[186:189], v[214:217], v[20:23]
	v_mfma_f32_16x16x32_bf16 v[8:11], v[186:189], v[218:221], v[8:11]
	ds_read_b128 v[172:175], v223 offset:8192
	ds_read_b128 v[176:179], v223 offset:10240
	ds_read_b128 v[182:185], v223 offset:12288
	ds_read_b128 v[186:189], v223 offset:14336
	s_waitcnt lgkmcnt(4)
	v_mfma_f32_16x16x32_bf16 v[124:127], v[156:159], v[190:193], v[124:127]
	v_mfma_f32_16x16x32_bf16 v[116:119], v[156:159], v[194:197], v[116:119]
	v_mfma_f32_16x16x32_bf16 v[120:123], v[156:159], v[198:201], v[120:123]
	v_mfma_f32_16x16x32_bf16 v[112:115], v[156:159], v[202:205], v[112:115]
	v_mfma_f32_16x16x32_bf16 v[108:111], v[160:163], v[190:193], v[108:111]
	v_mfma_f32_16x16x32_bf16 v[100:103], v[160:163], v[194:197], v[100:103]
	v_mfma_f32_16x16x32_bf16 v[104:107], v[160:163], v[198:201], v[104:107]
	v_mfma_f32_16x16x32_bf16 v[96:99], v[160:163], v[202:205], v[96:99]
	v_mfma_f32_16x16x32_bf16 v[92:95], v[164:167], v[190:193], v[92:95]
	v_mfma_f32_16x16x32_bf16 v[84:87], v[164:167], v[194:197], v[84:87]
	v_mfma_f32_16x16x32_bf16 v[88:91], v[164:167], v[198:201], v[88:91]
	v_mfma_f32_16x16x32_bf16 v[80:83], v[164:167], v[202:205], v[80:83]
	v_mfma_f32_16x16x32_bf16 v[76:79], v[168:171], v[190:193], v[76:79]
	v_mfma_f32_16x16x32_bf16 v[68:71], v[168:171], v[194:197], v[68:71]
	v_mfma_f32_16x16x32_bf16 v[72:75], v[168:171], v[198:201], v[72:75]
	v_mfma_f32_16x16x32_bf16 v[64:67], v[168:171], v[202:205], v[64:67]
	ds_read_b128 v[156:159], v224
	ds_read_b128 v[160:163], v224 offset:2048
	ds_read_b128 v[164:167], v224 offset:4096
	ds_read_b128 v[168:171], v224 offset:6144
	ds_read_b128 v[206:209], v226 offset:32768
	ds_read_b128 v[210:213], v226 offset:34816
	ds_read_b128 v[214:217], v226 offset:36864
	ds_read_b128 v[218:221], v226 offset:38912
	s_waitcnt lgkmcnt(8)
	v_mfma_f32_16x16x32_bf16 v[60:63], v[172:175], v[190:193], v[60:63]
	v_mfma_f32_16x16x32_bf16 v[52:55], v[172:175], v[194:197], v[52:55]
	v_mfma_f32_16x16x32_bf16 v[56:59], v[172:175], v[198:201], v[56:59]
	v_mfma_f32_16x16x32_bf16 v[48:51], v[172:175], v[202:205], v[48:51]
	v_mfma_f32_16x16x32_bf16 v[44:47], v[176:179], v[190:193], v[44:47]
	v_mfma_f32_16x16x32_bf16 v[36:39], v[176:179], v[194:197], v[36:39]
	v_mfma_f32_16x16x32_bf16 v[40:43], v[176:179], v[198:201], v[40:43]
	v_mfma_f32_16x16x32_bf16 v[32:35], v[176:179], v[202:205], v[32:35]
	v_mfma_f32_16x16x32_bf16 v[28:31], v[182:185], v[190:193], v[28:31]
	v_mfma_f32_16x16x32_bf16 v[16:19], v[182:185], v[194:197], v[16:19]
	v_mfma_f32_16x16x32_bf16 v[24:27], v[182:185], v[198:201], v[24:27]
	v_mfma_f32_16x16x32_bf16 v[12:15], v[182:185], v[202:205], v[12:15]
	v_mfma_f32_16x16x32_bf16 v[4:7], v[186:189], v[190:193], v[4:7]
	v_mfma_f32_16x16x32_bf16 v[0:3], v[186:189], v[194:197], v[0:3]
	v_mfma_f32_16x16x32_bf16 v[20:23], v[186:189], v[198:201], v[20:23]
	v_mfma_f32_16x16x32_bf16 v[8:11], v[186:189], v[202:205], v[8:11]
	ds_read_b128 v[172:175], v224 offset:8192
	ds_read_b128 v[176:179], v224 offset:10240
	ds_read_b128 v[182:185], v224 offset:12288
	ds_read_b128 v[186:189], v224 offset:14336
	s_waitcnt lgkmcnt(4)
	v_mfma_f32_16x16x32_bf16 v[124:127], v[156:159], v[206:209], v[124:127]
	v_mfma_f32_16x16x32_bf16 v[116:119], v[156:159], v[210:213], v[116:119]
	v_mfma_f32_16x16x32_bf16 v[120:123], v[156:159], v[214:217], v[120:123]
	v_mfma_f32_16x16x32_bf16 v[112:115], v[156:159], v[218:221], v[112:115]
	v_mfma_f32_16x16x32_bf16 v[108:111], v[160:163], v[206:209], v[108:111]
	v_mfma_f32_16x16x32_bf16 v[100:103], v[160:163], v[210:213], v[100:103]
	v_mfma_f32_16x16x32_bf16 v[104:107], v[160:163], v[214:217], v[104:107]
	v_mfma_f32_16x16x32_bf16 v[96:99], v[160:163], v[218:221], v[96:99]
	v_mfma_f32_16x16x32_bf16 v[92:95], v[164:167], v[206:209], v[92:95]
	v_mfma_f32_16x16x32_bf16 v[84:87], v[164:167], v[210:213], v[84:87]
	v_mfma_f32_16x16x32_bf16 v[88:91], v[164:167], v[214:217], v[88:91]
	v_mfma_f32_16x16x32_bf16 v[80:83], v[164:167], v[218:221], v[80:83]
	v_mfma_f32_16x16x32_bf16 v[76:79], v[168:171], v[206:209], v[76:79]
	v_mfma_f32_16x16x32_bf16 v[68:71], v[168:171], v[210:213], v[68:71]
	v_mfma_f32_16x16x32_bf16 v[72:75], v[168:171], v[214:217], v[72:75]
	v_mfma_f32_16x16x32_bf16 v[64:67], v[168:171], v[218:221], v[64:67]
	s_add_u32 s60, s60, 0x80
	s_addc_u32 s61, s61, 0
	s_add_i32 s59, s59, 1
	s_waitcnt lgkmcnt(0)
	s_waitcnt vmcnt(0)
	s_barrier
	v_mfma_f32_16x16x32_bf16 v[60:63], v[172:175], v[206:209], v[60:63]
	v_mfma_f32_16x16x32_bf16 v[52:55], v[172:175], v[210:213], v[52:55]
	v_mfma_f32_16x16x32_bf16 v[56:59], v[172:175], v[214:217], v[56:59]
	v_mfma_f32_16x16x32_bf16 v[48:51], v[172:175], v[218:221], v[48:51]
	v_mfma_f32_16x16x32_bf16 v[44:47], v[176:179], v[206:209], v[44:47]
	v_mfma_f32_16x16x32_bf16 v[36:39], v[176:179], v[210:213], v[36:39]
	v_mfma_f32_16x16x32_bf16 v[40:43], v[176:179], v[214:217], v[40:43]
	v_mfma_f32_16x16x32_bf16 v[32:35], v[176:179], v[218:221], v[32:35]
	v_mfma_f32_16x16x32_bf16 v[28:31], v[182:185], v[206:209], v[28:31]
	v_mfma_f32_16x16x32_bf16 v[16:19], v[182:185], v[210:213], v[16:19]
	v_mfma_f32_16x16x32_bf16 v[24:27], v[182:185], v[214:217], v[24:27]
	v_mfma_f32_16x16x32_bf16 v[12:15], v[182:185], v[218:221], v[12:15]
	v_mfma_f32_16x16x32_bf16 v[4:7], v[186:189], v[206:209], v[4:7]
	v_mfma_f32_16x16x32_bf16 v[0:3], v[186:189], v[210:213], v[0:3]
	v_mfma_f32_16x16x32_bf16 v[20:23], v[186:189], v[214:217], v[20:23]
	v_mfma_f32_16x16x32_bf16 v[8:11], v[186:189], v[218:221], v[8:11]
	s_nop 7
	s_nop 7
	s_sub_u32 s60, s60, s34
	s_subb_u32 s61, s61, s35
	s_mov_b32 s87, 0x80000
	s_mov_b32 s96, 0x80000
	s_mov_b64 s[88:89], 0
	s_mov_b64 vcc, exec
	s_branch .LBB0_120

.Lg1_top:
	s_waitcnt lgkmcnt(0)
	v_mfma_f32_16x16x32_bf16 v[60:63], v[158:161], v[194:197], v[60:63]
	v_mfma_f32_16x16x32_bf16 v[56:59], v[158:161], v[198:201], v[56:59]
	v_mfma_f32_16x16x32_bf16 v[52:55], v[158:161], v[202:205], v[52:55]
	v_mfma_f32_16x16x32_bf16 v[48:51], v[158:161], v[206:209], v[48:51]
	s_waitcnt vmcnt(0)
	s_barrier
	s_xor_b32 s59, s59, 0x10000
	s_mov_b32 m0, s59
	s_add_u32 s52, s50, s14
	s_addc_u32 s53, s51, s15
	global_load_lds_dwordx4 v178, s[52:53]
	ds_read_b128 v[142:145], v141
	ds_read_b128 v[146:149], v141 offset:2048
	ds_read_b128 v[150:153], v141 offset:4096
	ds_read_b128 v[154:157], v141 offset:6144
	ds_read_b128 v[174:177], v210 offset:32768
	ds_read_b128 v[182:185], v210 offset:34816
	ds_read_b128 v[186:189], v210 offset:36864
	ds_read_b128 v[190:193], v210 offset:38912
	v_mfma_f32_16x16x32_bf16 v[44:47], v[162:165], v[194:197], v[44:47]
	v_mfma_f32_16x16x32_bf16 v[40:43], v[162:165], v[198:201], v[40:43]
	s_add_u32 m0, s59, 0x2000
	s_add_u32 s52, s50, s16
	s_addc_u32 s53, s51, s17
	global_load_lds_dwordx4 v178, s[52:53]
	v_mfma_f32_16x16x32_bf16 v[36:39], v[162:165], v[202:205], v[36:39]
	v_mfma_f32_16x16x32_bf16 v[32:35], v[162:165], v[206:209], v[32:35]
	s_add_u32 m0, s59, 0x4000
	s_add_u32 s52, s50, s18
	s_addc_u32 s53, s51, s19
	global_load_lds_dwordx4 v178, s[52:53]
	v_mfma_f32_16x16x32_bf16 v[28:31], v[166:169], v[194:197], v[28:31]
	v_mfma_f32_16x16x32_bf16 v[20:23], v[166:169], v[198:201], v[20:23]
	s_add_u32 m0, s59, 0x6000
	s_add_u32 s52, s50, s22
	s_addc_u32 s53, s51, s23
	global_load_lds_dwordx4 v178, s[52:53]
	v_mfma_f32_16x16x32_bf16 v[16:19], v[166:169], v[202:205], v[16:19]
	v_mfma_f32_16x16x32_bf16 v[8:11], v[166:169], v[206:209], v[8:11]
	s_add_u32 m0, s59, 0x8000
	s_add_u32 s52, s50, s40
	s_addc_u32 s53, s51, s41
	global_load_lds_dwordx4 v179, s[52:53]
	v_mfma_f32_16x16x32_bf16 v[4:7], v[170:173], v[194:197], v[4:7]
	v_mfma_f32_16x16x32_bf16 v[0:3], v[170:173], v[198:201], v[0:3]
	s_add_u32 m0, s59, 0xa000
	s_add_u32 s52, s50, s42
	s_addc_u32 s53, s51, s43
	global_load_lds_dwordx4 v179, s[52:53]
	v_mfma_f32_16x16x32_bf16 v[24:27], v[170:173], v[202:205], v[24:27]
	v_mfma_f32_16x16x32_bf16 v[12:15], v[170:173], v[206:209], v[12:15]
	s_add_u32 m0, s59, 0xc000
	s_add_u32 s52, s50, s44
	s_addc_u32 s53, s51, s45
	global_load_lds_dwordx4 v179, s[52:53]
.Lg1_entry:
	ds_read_b128 v[158:161], v141 offset:8192
	ds_read_b128 v[162:165], v141 offset:10240
	ds_read_b128 v[166:169], v141 offset:12288
	ds_read_b128 v[170:173], v141 offset:14336
	s_waitcnt lgkmcnt(4)
	v_mfma_f32_16x16x32_bf16 v[124:127], v[142:145], v[174:177], v[124:127]
	v_mfma_f32_16x16x32_bf16 v[120:123], v[142:145], v[182:185], v[120:123]
	s_add_u32 m0, s59, 0xe000
	s_add_u32 s52, s50, s46
	s_addc_u32 s53, s51, s47
	global_load_lds_dwordx4 v179, s[52:53]
	v_mfma_f32_16x16x32_bf16 v[116:119], v[142:145], v[186:189], v[116:119]
	v_mfma_f32_16x16x32_bf16 v[112:115], v[142:145], v[190:193], v[112:115]
	v_mfma_f32_16x16x32_bf16 v[108:111], v[146:149], v[174:177], v[108:111]
	v_mfma_f32_16x16x32_bf16 v[104:107], v[146:149], v[182:185], v[104:107]
	v_mfma_f32_16x16x32_bf16 v[100:103], v[146:149], v[186:189], v[100:103]
	v_mfma_f32_16x16x32_bf16 v[96:99], v[146:149], v[190:193], v[96:99]
	v_mfma_f32_16x16x32_bf16 v[92:95], v[150:153], v[174:177], v[92:95]
	v_mfma_f32_16x16x32_bf16 v[88:91], v[150:153], v[182:185], v[88:91]
	v_mfma_f32_16x16x32_bf16 v[84:87], v[150:153], v[186:189], v[84:87]
	v_mfma_f32_16x16x32_bf16 v[80:83], v[150:153], v[190:193], v[80:83]
	v_mfma_f32_16x16x32_bf16 v[76:79], v[154:157], v[174:177], v[76:79]
	v_mfma_f32_16x16x32_bf16 v[72:75], v[154:157], v[182:185], v[72:75]
	v_mfma_f32_16x16x32_bf16 v[68:71], v[154:157], v[186:189], v[68:71]
	v_mfma_f32_16x16x32_bf16 v[64:67], v[154:157], v[190:193], v[64:67]
	ds_read_b128 v[142:145], v180
	ds_read_b128 v[146:149], v180 offset:2048
	ds_read_b128 v[150:153], v180 offset:4096
	ds_read_b128 v[154:157], v180 offset:6144
	ds_read_b128 v[194:197], v211 offset:32768
	ds_read_b128 v[198:201], v211 offset:34816
	ds_read_b128 v[202:205], v211 offset:36864
	ds_read_b128 v[206:209], v211 offset:38912
	s_waitcnt lgkmcnt(8)
	v_mfma_f32_16x16x32_bf16 v[60:63], v[158:161], v[174:177], v[60:63]
	v_mfma_f32_16x16x32_bf16 v[56:59], v[158:161], v[182:185], v[56:59]
	v_mfma_f32_16x16x32_bf16 v[52:55], v[158:161], v[186:189], v[52:55]
	v_mfma_f32_16x16x32_bf16 v[48:51], v[158:161], v[190:193], v[48:51]
	v_mfma_f32_16x16x32_bf16 v[44:47], v[162:165], v[174:177], v[44:47]
	v_mfma_f32_16x16x32_bf16 v[40:43], v[162:165], v[182:185], v[40:43]
	v_mfma_f32_16x16x32_bf16 v[36:39], v[162:165], v[186:189], v[36:39]
	v_mfma_f32_16x16x32_bf16 v[32:35], v[162:165], v[190:193], v[32:35]
	v_mfma_f32_16x16x32_bf16 v[28:31], v[166:169], v[174:177], v[28:31]
	v_mfma_f32_16x16x32_bf16 v[20:23], v[166:169], v[182:185], v[20:23]
	v_mfma_f32_16x16x32_bf16 v[16:19], v[166:169], v[186:189], v[16:19]
	v_mfma_f32_16x16x32_bf16 v[8:11], v[166:169], v[190:193], v[8:11]
	v_mfma_f32_16x16x32_bf16 v[4:7], v[170:173], v[174:177], v[4:7]
	v_mfma_f32_16x16x32_bf16 v[0:3], v[170:173], v[182:185], v[0:3]
	v_mfma_f32_16x16x32_bf16 v[24:27], v[170:173], v[186:189], v[24:27]
	v_mfma_f32_16x16x32_bf16 v[12:15], v[170:173], v[190:193], v[12:15]
	ds_read_b128 v[158:161], v180 offset:8192
	ds_read_b128 v[162:165], v180 offset:10240
	ds_read_b128 v[166:169], v180 offset:12288
	ds_read_b128 v[170:173], v180 offset:14336
	s_waitcnt lgkmcnt(4)
	v_mfma_f32_16x16x32_bf16 v[124:127], v[142:145], v[194:197], v[124:127]
	v_mfma_f32_16x16x32_bf16 v[120:123], v[142:145], v[198:201], v[120:123]
	v_mfma_f32_16x16x32_bf16 v[116:119], v[142:145], v[202:205], v[116:119]
	v_mfma_f32_16x16x32_bf16 v[112:115], v[142:145], v[206:209], v[112:115]
	v_mfma_f32_16x16x32_bf16 v[108:111], v[146:149], v[194:197], v[108:111]
	v_mfma_f32_16x16x32_bf16 v[104:107], v[146:149], v[198:201], v[104:107]
	v_mfma_f32_16x16x32_bf16 v[100:103], v[146:149], v[202:205], v[100:103]
	v_mfma_f32_16x16x32_bf16 v[96:99], v[146:149], v[206:209], v[96:99]
	v_mfma_f32_16x16x32_bf16 v[92:95], v[150:153], v[194:197], v[92:95]
	v_mfma_f32_16x16x32_bf16 v[88:91], v[150:153], v[198:201], v[88:91]
	v_mfma_f32_16x16x32_bf16 v[84:87], v[150:153], v[202:205], v[84:87]
	v_mfma_f32_16x16x32_bf16 v[80:83], v[150:153], v[206:209], v[80:83]
	v_mfma_f32_16x16x32_bf16 v[76:79], v[154:157], v[194:197], v[76:79]
	v_mfma_f32_16x16x32_bf16 v[72:75], v[154:157], v[198:201], v[72:75]
	v_mfma_f32_16x16x32_bf16 v[68:71], v[154:157], v[202:205], v[68:71]
	v_mfma_f32_16x16x32_bf16 v[64:67], v[154:157], v[206:209], v[64:67]
	s_add_u32 s50, s50, 0x80
	s_addc_u32 s51, s51, 0
	s_add_i32 s49, s49, 1
	s_cmp_lt_u32 s49, 31
	s_cbranch_scc0 .Lg1_last
	s_waitcnt lgkmcnt(0)
	v_mfma_f32_16x16x32_bf16 v[60:63], v[158:161], v[194:197], v[60:63]
	v_mfma_f32_16x16x32_bf16 v[56:59], v[158:161], v[198:201], v[56:59]
	v_mfma_f32_16x16x32_bf16 v[52:55], v[158:161], v[202:205], v[52:55]
	v_mfma_f32_16x16x32_bf16 v[48:51], v[158:161], v[206:209], v[48:51]
	s_waitcnt vmcnt(0)
	s_barrier
	s_xor_b32 s59, s59, 0x10000
	s_mov_b32 m0, s59
	s_add_u32 s52, s50, s14
	s_addc_u32 s53, s51, s15
	global_load_lds_dwordx4 v178, s[52:53]
	ds_read_b128 v[142:145], v212
	ds_read_b128 v[146:149], v212 offset:2048
	ds_read_b128 v[150:153], v212 offset:4096
	ds_read_b128 v[154:157], v212 offset:6144
	ds_read_b128 v[174:177], v214 offset:32768
	ds_read_b128 v[182:185], v214 offset:34816
	ds_read_b128 v[186:189], v214 offset:36864
	ds_read_b128 v[190:193], v214 offset:38912
	v_mfma_f32_16x16x32_bf16 v[44:47], v[162:165], v[194:197], v[44:47]
	v_mfma_f32_16x16x32_bf16 v[40:43], v[162:165], v[198:201], v[40:43]
	s_add_u32 m0, s59, 0x2000
	s_add_u32 s52, s50, s16
	s_addc_u32 s53, s51, s17
	global_load_lds_dwordx4 v178, s[52:53]
	v_mfma_f32_16x16x32_bf16 v[36:39], v[162:165], v[202:205], v[36:39]
	v_mfma_f32_16x16x32_bf16 v[32:35], v[162:165], v[206:209], v[32:35]
	s_add_u32 m0, s59, 0x4000
	s_add_u32 s52, s50, s18
	s_addc_u32 s53, s51, s19
	global_load_lds_dwordx4 v178, s[52:53]
	v_mfma_f32_16x16x32_bf16 v[28:31], v[166:169], v[194:197], v[28:31]
	v_mfma_f32_16x16x32_bf16 v[20:23], v[166:169], v[198:201], v[20:23]
	s_add_u32 m0, s59, 0x6000
	s_add_u32 s52, s50, s22
	s_addc_u32 s53, s51, s23
	global_load_lds_dwordx4 v178, s[52:53]
	v_mfma_f32_16x16x32_bf16 v[16:19], v[166:169], v[202:205], v[16:19]
	v_mfma_f32_16x16x32_bf16 v[8:11], v[166:169], v[206:209], v[8:11]
	s_add_u32 m0, s59, 0x8000
	s_add_u32 s52, s50, s40
	s_addc_u32 s53, s51, s41
	global_load_lds_dwordx4 v179, s[52:53]
	v_mfma_f32_16x16x32_bf16 v[4:7], v[170:173], v[194:197], v[4:7]
	v_mfma_f32_16x16x32_bf16 v[0:3], v[170:173], v[198:201], v[0:3]
	s_add_u32 m0, s59, 0xa000
	s_add_u32 s52, s50, s42
	s_addc_u32 s53, s51, s43
	global_load_lds_dwordx4 v179, s[52:53]
	v_mfma_f32_16x16x32_bf16 v[24:27], v[170:173], v[202:205], v[24:27]
	v_mfma_f32_16x16x32_bf16 v[12:15], v[170:173], v[206:209], v[12:15]
	s_add_u32 m0, s59, 0xc000
	s_add_u32 s52, s50, s44
	s_addc_u32 s53, s51, s45
	global_load_lds_dwordx4 v179, s[52:53]
	ds_read_b128 v[158:161], v212 offset:8192
	ds_read_b128 v[162:165], v212 offset:10240
	ds_read_b128 v[166:169], v212 offset:12288
	ds_read_b128 v[170:173], v212 offset:14336
	s_waitcnt lgkmcnt(4)
	v_mfma_f32_16x16x32_bf16 v[124:127], v[142:145], v[174:177], v[124:127]
	v_mfma_f32_16x16x32_bf16 v[120:123], v[142:145], v[182:185], v[120:123]
	s_add_u32 m0, s59, 0xe000
	s_add_u32 s52, s50, s46
	s_addc_u32 s53, s51, s47
	global_load_lds_dwordx4 v179, s[52:53]
	v_mfma_f32_16x16x32_bf16 v[116:119], v[142:145], v[186:189], v[116:119]
	v_mfma_f32_16x16x32_bf16 v[112:115], v[142:145], v[190:193], v[112:115]
	v_mfma_f32_16x16x32_bf16 v[108:111], v[146:149], v[174:177], v[108:111]
	v_mfma_f32_16x16x32_bf16 v[104:107], v[146:149], v[182:185], v[104:107]
	v_mfma_f32_16x16x32_bf16 v[100:103], v[146:149], v[186:189], v[100:103]
	v_mfma_f32_16x16x32_bf16 v[96:99], v[146:149], v[190:193], v[96:99]
	v_mfma_f32_16x16x32_bf16 v[92:95], v[150:153], v[174:177], v[92:95]
	v_mfma_f32_16x16x32_bf16 v[88:91], v[150:153], v[182:185], v[88:91]
	v_mfma_f32_16x16x32_bf16 v[84:87], v[150:153], v[186:189], v[84:87]
	v_mfma_f32_16x16x32_bf16 v[80:83], v[150:153], v[190:193], v[80:83]
	v_mfma_f32_16x16x32_bf16 v[76:79], v[154:157], v[174:177], v[76:79]
	v_mfma_f32_16x16x32_bf16 v[72:75], v[154:157], v[182:185], v[72:75]
	v_mfma_f32_16x16x32_bf16 v[68:71], v[154:157], v[186:189], v[68:71]
	v_mfma_f32_16x16x32_bf16 v[64:67], v[154:157], v[190:193], v[64:67]
	ds_read_b128 v[142:145], v213
	ds_read_b128 v[146:149], v213 offset:2048
	ds_read_b128 v[150:153], v213 offset:4096
	ds_read_b128 v[154:157], v213 offset:6144
	ds_read_b128 v[194:197], v215 offset:32768
	ds_read_b128 v[198:201], v215 offset:34816
	ds_read_b128 v[202:205], v215 offset:36864
	ds_read_b128 v[206:209], v215 offset:38912
	s_waitcnt lgkmcnt(8)
	v_mfma_f32_16x16x32_bf16 v[60:63], v[158:161], v[174:177], v[60:63]
	v_mfma_f32_16x16x32_bf16 v[56:59], v[158:161], v[182:185], v[56:59]
	v_mfma_f32_16x16x32_bf16 v[52:55], v[158:161], v[186:189], v[52:55]
	v_mfma_f32_16x16x32_bf16 v[48:51], v[158:161], v[190:193], v[48:51]
	v_mfma_f32_16x16x32_bf16 v[44:47], v[162:165], v[174:177], v[44:47]
	v_mfma_f32_16x16x32_bf16 v[40:43], v[162:165], v[182:185], v[40:43]
	v_mfma_f32_16x16x32_bf16 v[36:39], v[162:165], v[186:189], v[36:39]
	v_mfma_f32_16x16x32_bf16 v[32:35], v[162:165], v[190:193], v[32:35]
	v_mfma_f32_16x16x32_bf16 v[28:31], v[166:169], v[174:177], v[28:31]
	v_mfma_f32_16x16x32_bf16 v[20:23], v[166:169], v[182:185], v[20:23]
	v_mfma_f32_16x16x32_bf16 v[16:19], v[166:169], v[186:189], v[16:19]
	v_mfma_f32_16x16x32_bf16 v[8:11], v[166:169], v[190:193], v[8:11]
	v_mfma_f32_16x16x32_bf16 v[4:7], v[170:173], v[174:177], v[4:7]
	v_mfma_f32_16x16x32_bf16 v[0:3], v[170:173], v[182:185], v[0:3]
	v_mfma_f32_16x16x32_bf16 v[24:27], v[170:173], v[186:189], v[24:27]
	v_mfma_f32_16x16x32_bf16 v[12:15], v[170:173], v[190:193], v[12:15]
	ds_read_b128 v[158:161], v213 offset:8192
	ds_read_b128 v[162:165], v213 offset:10240
	ds_read_b128 v[166:169], v213 offset:12288
	ds_read_b128 v[170:173], v213 offset:14336
	s_waitcnt lgkmcnt(4)
	v_mfma_f32_16x16x32_bf16 v[124:127], v[142:145], v[194:197], v[124:127]
	v_mfma_f32_16x16x32_bf16 v[120:123], v[142:145], v[198:201], v[120:123]
	v_mfma_f32_16x16x32_bf16 v[116:119], v[142:145], v[202:205], v[116:119]
	v_mfma_f32_16x16x32_bf16 v[112:115], v[142:145], v[206:209], v[112:115]
	v_mfma_f32_16x16x32_bf16 v[108:111], v[146:149], v[194:197], v[108:111]
	v_mfma_f32_16x16x32_bf16 v[104:107], v[146:149], v[198:201], v[104:107]
	v_mfma_f32_16x16x32_bf16 v[100:103], v[146:149], v[202:205], v[100:103]
	v_mfma_f32_16x16x32_bf16 v[96:99], v[146:149], v[206:209], v[96:99]
	v_mfma_f32_16x16x32_bf16 v[92:95], v[150:153], v[194:197], v[92:95]
	v_mfma_f32_16x16x32_bf16 v[88:91], v[150:153], v[198:201], v[88:91]
	v_mfma_f32_16x16x32_bf16 v[84:87], v[150:153], v[202:205], v[84:87]
	v_mfma_f32_16x16x32_bf16 v[80:83], v[150:153], v[206:209], v[80:83]
	v_mfma_f32_16x16x32_bf16 v[76:79], v[154:157], v[194:197], v[76:79]
	v_mfma_f32_16x16x32_bf16 v[72:75], v[154:157], v[198:201], v[72:75]
	v_mfma_f32_16x16x32_bf16 v[68:71], v[154:157], v[202:205], v[68:71]
	v_mfma_f32_16x16x32_bf16 v[64:67], v[154:157], v[206:209], v[64:67]
	s_add_u32 s50, s50, 0x80
	s_addc_u32 s51, s51, 0
	s_add_i32 s49, s49, 1
	s_branch .Lg1_top
.Lg1_last:
	s_waitcnt lgkmcnt(0)
	v_mfma_f32_16x16x32_bf16 v[60:63], v[158:161], v[194:197], v[60:63]
	v_mfma_f32_16x16x32_bf16 v[56:59], v[158:161], v[198:201], v[56:59]
	v_mfma_f32_16x16x32_bf16 v[52:55], v[158:161], v[202:205], v[52:55]
	v_mfma_f32_16x16x32_bf16 v[48:51], v[158:161], v[206:209], v[48:51]
	s_waitcnt vmcnt(0)
	s_barrier
	s_xor_b32 s59, s59, 0x10000
	ds_read_b128 v[142:145], v212
	ds_read_b128 v[146:149], v212 offset:2048
	ds_read_b128 v[150:153], v212 offset:4096
	ds_read_b128 v[154:157], v212 offset:6144
	ds_read_b128 v[174:177], v214 offset:32768
	ds_read_b128 v[182:185], v214 offset:34816
	ds_read_b128 v[186:189], v214 offset:36864
	ds_read_b128 v[190:193], v214 offset:38912
	v_mfma_f32_16x16x32_bf16 v[44:47], v[162:165], v[194:197], v[44:47]
	v_mfma_f32_16x16x32_bf16 v[40:43], v[162:165], v[198:201], v[40:43]
	v_mfma_f32_16x16x32_bf16 v[36:39], v[162:165], v[202:205], v[36:39]
	v_mfma_f32_16x16x32_bf16 v[32:35], v[162:165], v[206:209], v[32:35]
	v_mfma_f32_16x16x32_bf16 v[28:31], v[166:169], v[194:197], v[28:31]
	v_mfma_f32_16x16x32_bf16 v[20:23], v[166:169], v[198:201], v[20:23]
	v_mfma_f32_16x16x32_bf16 v[16:19], v[166:169], v[202:205], v[16:19]
	v_mfma_f32_16x16x32_bf16 v[8:11], v[166:169], v[206:209], v[8:11]
	v_mfma_f32_16x16x32_bf16 v[4:7], v[170:173], v[194:197], v[4:7]
	v_mfma_f32_16x16x32_bf16 v[0:3], v[170:173], v[198:201], v[0:3]
	v_mfma_f32_16x16x32_bf16 v[24:27], v[170:173], v[202:205], v[24:27]
	v_mfma_f32_16x16x32_bf16 v[12:15], v[170:173], v[206:209], v[12:15]
	ds_read_b128 v[158:161], v212 offset:8192
	ds_read_b128 v[162:165], v212 offset:10240
	ds_read_b128 v[166:169], v212 offset:12288
	ds_read_b128 v[170:173], v212 offset:14336
	s_waitcnt lgkmcnt(4)
	v_mfma_f32_16x16x32_bf16 v[124:127], v[142:145], v[174:177], v[124:127]
	v_mfma_f32_16x16x32_bf16 v[120:123], v[142:145], v[182:185], v[120:123]
	v_mfma_f32_16x16x32_bf16 v[116:119], v[142:145], v[186:189], v[116:119]
	v_mfma_f32_16x16x32_bf16 v[112:115], v[142:145], v[190:193], v[112:115]
	v_mfma_f32_16x16x32_bf16 v[108:111], v[146:149], v[174:177], v[108:111]
	v_mfma_f32_16x16x32_bf16 v[104:107], v[146:149], v[182:185], v[104:107]
	v_mfma_f32_16x16x32_bf16 v[100:103], v[146:149], v[186:189], v[100:103]
	v_mfma_f32_16x16x32_bf16 v[96:99], v[146:149], v[190:193], v[96:99]
	v_mfma_f32_16x16x32_bf16 v[92:95], v[150:153], v[174:177], v[92:95]
	v_mfma_f32_16x16x32_bf16 v[88:91], v[150:153], v[182:185], v[88:91]
	v_mfma_f32_16x16x32_bf16 v[84:87], v[150:153], v[186:189], v[84:87]
	v_mfma_f32_16x16x32_bf16 v[80:83], v[150:153], v[190:193], v[80:83]
	v_mfma_f32_16x16x32_bf16 v[76:79], v[154:157], v[174:177], v[76:79]
	v_mfma_f32_16x16x32_bf16 v[72:75], v[154:157], v[182:185], v[72:75]
	v_mfma_f32_16x16x32_bf16 v[68:71], v[154:157], v[186:189], v[68:71]
	v_mfma_f32_16x16x32_bf16 v[64:67], v[154:157], v[190:193], v[64:67]
	ds_read_b128 v[142:145], v213
	ds_read_b128 v[146:149], v213 offset:2048
	ds_read_b128 v[150:153], v213 offset:4096
	ds_read_b128 v[154:157], v213 offset:6144
	ds_read_b128 v[194:197], v215 offset:32768
	ds_read_b128 v[198:201], v215 offset:34816
	ds_read_b128 v[202:205], v215 offset:36864
	ds_read_b128 v[206:209], v215 offset:38912
	s_waitcnt lgkmcnt(8)
	v_mfma_f32_16x16x32_bf16 v[60:63], v[158:161], v[174:177], v[60:63]
	v_mfma_f32_16x16x32_bf16 v[56:59], v[158:161], v[182:185], v[56:59]
	v_mfma_f32_16x16x32_bf16 v[52:55], v[158:161], v[186:189], v[52:55]
	v_mfma_f32_16x16x32_bf16 v[48:51], v[158:161], v[190:193], v[48:51]
	v_mfma_f32_16x16x32_bf16 v[44:47], v[162:165], v[174:177], v[44:47]
	v_mfma_f32_16x16x32_bf16 v[40:43], v[162:165], v[182:185], v[40:43]
	v_mfma_f32_16x16x32_bf16 v[36:39], v[162:165], v[186:189], v[36:39]
	v_mfma_f32_16x16x32_bf16 v[32:35], v[162:165], v[190:193], v[32:35]
	v_mfma_f32_16x16x32_bf16 v[28:31], v[166:169], v[174:177], v[28:31]
	v_mfma_f32_16x16x32_bf16 v[20:23], v[166:169], v[182:185], v[20:23]
	v_mfma_f32_16x16x32_bf16 v[16:19], v[166:169], v[186:189], v[16:19]
	v_mfma_f32_16x16x32_bf16 v[8:11], v[166:169], v[190:193], v[8:11]
	v_mfma_f32_16x16x32_bf16 v[4:7], v[170:173], v[174:177], v[4:7]
	v_mfma_f32_16x16x32_bf16 v[0:3], v[170:173], v[182:185], v[0:3]
	v_mfma_f32_16x16x32_bf16 v[24:27], v[170:173], v[186:189], v[24:27]
	v_mfma_f32_16x16x32_bf16 v[12:15], v[170:173], v[190:193], v[12:15]
	ds_read_b128 v[158:161], v213 offset:8192
	ds_read_b128 v[162:165], v213 offset:10240
	ds_read_b128 v[166:169], v213 offset:12288
	ds_read_b128 v[170:173], v213 offset:14336
	s_waitcnt lgkmcnt(4)
	v_mfma_f32_16x16x32_bf16 v[124:127], v[142:145], v[194:197], v[124:127]
	v_mfma_f32_16x16x32_bf16 v[120:123], v[142:145], v[198:201], v[120:123]
	v_mfma_f32_16x16x32_bf16 v[116:119], v[142:145], v[202:205], v[116:119]
	v_mfma_f32_16x16x32_bf16 v[112:115], v[142:145], v[206:209], v[112:115]
	v_mfma_f32_16x16x32_bf16 v[108:111], v[146:149], v[194:197], v[108:111]
	v_mfma_f32_16x16x32_bf16 v[104:107], v[146:149], v[198:201], v[104:107]
	v_mfma_f32_16x16x32_bf16 v[100:103], v[146:149], v[202:205], v[100:103]
	v_mfma_f32_16x16x32_bf16 v[96:99], v[146:149], v[206:209], v[96:99]
	v_mfma_f32_16x16x32_bf16 v[92:95], v[150:153], v[194:197], v[92:95]
	v_mfma_f32_16x16x32_bf16 v[88:91], v[150:153], v[198:201], v[88:91]
	v_mfma_f32_16x16x32_bf16 v[84:87], v[150:153], v[202:205], v[84:87]
	v_mfma_f32_16x16x32_bf16 v[80:83], v[150:153], v[206:209], v[80:83]
	v_mfma_f32_16x16x32_bf16 v[76:79], v[154:157], v[194:197], v[76:79]
	v_mfma_f32_16x16x32_bf16 v[72:75], v[154:157], v[198:201], v[72:75]
	v_mfma_f32_16x16x32_bf16 v[68:71], v[154:157], v[202:205], v[68:71]
	v_mfma_f32_16x16x32_bf16 v[64:67], v[154:157], v[206:209], v[64:67]
	s_add_u32 s50, s50, 0x80
	s_addc_u32 s51, s51, 0
	s_add_i32 s49, s49, 1
	s_waitcnt lgkmcnt(0)
	s_waitcnt vmcnt(0)
	s_barrier
	v_mfma_f32_16x16x32_bf16 v[60:63], v[158:161], v[194:197], v[60:63]
	v_mfma_f32_16x16x32_bf16 v[56:59], v[158:161], v[198:201], v[56:59]
	v_mfma_f32_16x16x32_bf16 v[52:55], v[158:161], v[202:205], v[52:55]
	v_mfma_f32_16x16x32_bf16 v[48:51], v[158:161], v[206:209], v[48:51]
	v_mfma_f32_16x16x32_bf16 v[44:47], v[162:165], v[194:197], v[44:47]
	v_mfma_f32_16x16x32_bf16 v[40:43], v[162:165], v[198:201], v[40:43]
	v_mfma_f32_16x16x32_bf16 v[36:39], v[162:165], v[202:205], v[36:39]
	v_mfma_f32_16x16x32_bf16 v[32:35], v[162:165], v[206:209], v[32:35]
	v_mfma_f32_16x16x32_bf16 v[28:31], v[166:169], v[194:197], v[28:31]
	v_mfma_f32_16x16x32_bf16 v[20:23], v[166:169], v[198:201], v[20:23]
	v_mfma_f32_16x16x32_bf16 v[16:19], v[166:169], v[202:205], v[16:19]
	v_mfma_f32_16x16x32_bf16 v[8:11], v[166:169], v[206:209], v[8:11]
	v_mfma_f32_16x16x32_bf16 v[4:7], v[170:173], v[194:197], v[4:7]
	v_mfma_f32_16x16x32_bf16 v[0:3], v[170:173], v[198:201], v[0:3]
	v_mfma_f32_16x16x32_bf16 v[24:27], v[170:173], v[202:205], v[24:27]
	v_mfma_f32_16x16x32_bf16 v[12:15], v[170:173], v[206:209], v[12:15]
	s_nop 7
	s_nop 7
	s_sub_u32 s50, s50, s34
	s_subb_u32 s51, s51, s35
	s_mov_b32 s59, 0x100000
	s_mov_b32 s60, 0x100000
	s_mov_b64 s[52:53], 0
	s_mov_b64 vcc, exec
	s_branch .LBB0_262

.Lg2_top:
	s_waitcnt lgkmcnt(0)
	v_mfma_f32_16x16x32_bf16 v[60:63], v[162:165], v[198:201], v[60:63]
	v_mfma_f32_16x16x32_bf16 v[56:59], v[162:165], v[202:205], v[56:59]
	v_mfma_f32_16x16x32_bf16 v[52:55], v[162:165], v[206:209], v[52:55]
	v_mfma_f32_16x16x32_bf16 v[44:47], v[162:165], v[210:213], v[44:47]
	s_waitcnt vmcnt(0)
	s_barrier
	s_xor_b32 s62, s62, 0x10000
	s_mov_b32 m0, s62
	s_add_u32 s50, s48, s12
	s_addc_u32 s51, s49, s13
	global_load_lds_dwordx4 v178, s[50:51]
	ds_read_b128 v[146:149], v180
	ds_read_b128 v[150:153], v180 offset:2048
	ds_read_b128 v[154:157], v180 offset:4096
	ds_read_b128 v[158:161], v180 offset:6144
	ds_read_b128 v[182:185], v215 offset:32768
	ds_read_b128 v[186:189], v215 offset:34816
	ds_read_b128 v[190:193], v215 offset:36864
	ds_read_b128 v[194:197], v215 offset:38912
	v_mfma_f32_16x16x32_bf16 v[36:39], v[166:169], v[198:201], v[36:39]
	v_mfma_f32_16x16x32_bf16 v[32:35], v[166:169], v[202:205], v[32:35]
	s_add_u32 m0, s62, 0x2000
	s_add_u32 s50, s48, s14
	s_addc_u32 s51, s49, s15
	global_load_lds_dwordx4 v178, s[50:51]
	v_mfma_f32_16x16x32_bf16 v[28:31], v[166:169], v[206:209], v[28:31]
	v_mfma_f32_16x16x32_bf16 v[24:27], v[166:169], v[210:213], v[24:27]
	s_add_u32 m0, s62, 0x4000
	s_add_u32 s50, s48, s16
	s_addc_u32 s51, s49, s17
	global_load_lds_dwordx4 v178, s[50:51]
	v_mfma_f32_16x16x32_bf16 v[20:23], v[170:173], v[198:201], v[20:23]
	v_mfma_f32_16x16x32_bf16 v[16:19], v[170:173], v[202:205], v[16:19]
	s_add_u32 m0, s62, 0x6000
	s_add_u32 s50, s48, s18
	s_addc_u32 s51, s49, s19
	global_load_lds_dwordx4 v178, s[50:51]
	v_mfma_f32_16x16x32_bf16 v[12:15], v[170:173], v[206:209], v[12:15]
	v_mfma_f32_16x16x32_bf16 v[8:11], v[170:173], v[210:213], v[8:11]
	s_add_u32 m0, s62, 0x8000
	s_add_u32 s50, s48, s22
	s_addc_u32 s51, s49, s23
	global_load_lds_dwordx4 v179, s[50:51]
	v_mfma_f32_16x16x32_bf16 v[4:7], v[174:177], v[198:201], v[4:7]
	v_mfma_f32_16x16x32_bf16 v[0:3], v[174:177], v[202:205], v[0:3]
	s_add_u32 m0, s62, 0xa000
	s_add_u32 s50, s48, s36
	s_addc_u32 s51, s49, s37
	global_load_lds_dwordx4 v179, s[50:51]
	v_mfma_f32_16x16x32_bf16 v[48:51], v[174:177], v[206:209], v[48:51]
	v_mfma_f32_16x16x32_bf16 v[40:43], v[174:177], v[210:213], v[40:43]
	s_add_u32 m0, s62, 0xc000
	s_add_u32 s50, s48, s40
	s_addc_u32 s51, s49, s41
	global_load_lds_dwordx4 v179, s[50:51]
.Lg2_entry:
	ds_read_b128 v[162:165], v180 offset:8192
	ds_read_b128 v[166:169], v180 offset:10240
	ds_read_b128 v[170:173], v180 offset:12288
	ds_read_b128 v[174:177], v180 offset:14336
	s_waitcnt lgkmcnt(4)
	v_mfma_f32_16x16x32_bf16 v[124:127], v[146:149], v[182:185], v[124:127]
	v_mfma_f32_16x16x32_bf16 v[120:123], v[146:149], v[186:189], v[120:123]
	s_add_u32 m0, s62, 0xe000
	s_add_u32 s50, s48, s42
	s_addc_u32 s51, s49, s43
	global_load_lds_dwordx4 v179, s[50:51]
	v_mfma_f32_16x16x32_bf16 v[116:119], v[146:149], v[190:193], v[116:119]
	v_mfma_f32_16x16x32_bf16 v[112:115], v[146:149], v[194:197], v[112:115]
	v_mfma_f32_16x16x32_bf16 v[108:111], v[150:153], v[182:185], v[108:111]
	v_mfma_f32_16x16x32_bf16 v[104:107], v[150:153], v[186:189], v[104:107]
	v_mfma_f32_16x16x32_bf16 v[100:103], v[150:153], v[190:193], v[100:103]
	v_mfma_f32_16x16x32_bf16 v[96:99], v[150:153], v[194:197], v[96:99]
	v_mfma_f32_16x16x32_bf16 v[92:95], v[154:157], v[182:185], v[92:95]
	v_mfma_f32_16x16x32_bf16 v[88:91], v[154:157], v[186:189], v[88:91]
	v_mfma_f32_16x16x32_bf16 v[84:87], v[154:157], v[190:193], v[84:87]
	v_mfma_f32_16x16x32_bf16 v[80:83], v[154:157], v[194:197], v[80:83]
	v_mfma_f32_16x16x32_bf16 v[76:79], v[158:161], v[182:185], v[76:79]
	v_mfma_f32_16x16x32_bf16 v[72:75], v[158:161], v[186:189], v[72:75]
	v_mfma_f32_16x16x32_bf16 v[68:71], v[158:161], v[190:193], v[68:71]
	v_mfma_f32_16x16x32_bf16 v[64:67], v[158:161], v[194:197], v[64:67]
	ds_read_b128 v[146:149], v214
	ds_read_b128 v[150:153], v214 offset:2048
	ds_read_b128 v[154:157], v214 offset:4096
	ds_read_b128 v[158:161], v214 offset:6144
	ds_read_b128 v[198:201], v216 offset:32768
	ds_read_b128 v[202:205], v216 offset:34816
	ds_read_b128 v[206:209], v216 offset:36864
	ds_read_b128 v[210:213], v216 offset:38912
	s_waitcnt lgkmcnt(8)
	v_mfma_f32_16x16x32_bf16 v[60:63], v[162:165], v[182:185], v[60:63]
	v_mfma_f32_16x16x32_bf16 v[56:59], v[162:165], v[186:189], v[56:59]
	v_mfma_f32_16x16x32_bf16 v[52:55], v[162:165], v[190:193], v[52:55]
	v_mfma_f32_16x16x32_bf16 v[44:47], v[162:165], v[194:197], v[44:47]
	v_mfma_f32_16x16x32_bf16 v[36:39], v[166:169], v[182:185], v[36:39]
	v_mfma_f32_16x16x32_bf16 v[32:35], v[166:169], v[186:189], v[32:35]
	v_mfma_f32_16x16x32_bf16 v[28:31], v[166:169], v[190:193], v[28:31]
	v_mfma_f32_16x16x32_bf16 v[24:27], v[166:169], v[194:197], v[24:27]
	v_mfma_f32_16x16x32_bf16 v[20:23], v[170:173], v[182:185], v[20:23]
	v_mfma_f32_16x16x32_bf16 v[16:19], v[170:173], v[186:189], v[16:19]
	v_mfma_f32_16x16x32_bf16 v[12:15], v[170:173], v[190:193], v[12:15]
	v_mfma_f32_16x16x32_bf16 v[8:11], v[170:173], v[194:197], v[8:11]
	v_mfma_f32_16x16x32_bf16 v[4:7], v[174:177], v[182:185], v[4:7]
	v_mfma_f32_16x16x32_bf16 v[0:3], v[174:177], v[186:189], v[0:3]
	v_mfma_f32_16x16x32_bf16 v[48:51], v[174:177], v[190:193], v[48:51]
	v_mfma_f32_16x16x32_bf16 v[40:43], v[174:177], v[194:197], v[40:43]
	ds_read_b128 v[162:165], v214 offset:8192
	ds_read_b128 v[166:169], v214 offset:10240
	ds_read_b128 v[170:173], v214 offset:12288
	ds_read_b128 v[174:177], v214 offset:14336
	s_waitcnt lgkmcnt(4)
	v_mfma_f32_16x16x32_bf16 v[124:127], v[146:149], v[198:201], v[124:127]
	v_mfma_f32_16x16x32_bf16 v[120:123], v[146:149], v[202:205], v[120:123]
	v_mfma_f32_16x16x32_bf16 v[116:119], v[146:149], v[206:209], v[116:119]
	v_mfma_f32_16x16x32_bf16 v[112:115], v[146:149], v[210:213], v[112:115]
	v_mfma_f32_16x16x32_bf16 v[108:111], v[150:153], v[198:201], v[108:111]
	v_mfma_f32_16x16x32_bf16 v[104:107], v[150:153], v[202:205], v[104:107]
	v_mfma_f32_16x16x32_bf16 v[100:103], v[150:153], v[206:209], v[100:103]
	v_mfma_f32_16x16x32_bf16 v[96:99], v[150:153], v[210:213], v[96:99]
	v_mfma_f32_16x16x32_bf16 v[92:95], v[154:157], v[198:201], v[92:95]
	v_mfma_f32_16x16x32_bf16 v[88:91], v[154:157], v[202:205], v[88:91]
	v_mfma_f32_16x16x32_bf16 v[84:87], v[154:157], v[206:209], v[84:87]
	v_mfma_f32_16x16x32_bf16 v[80:83], v[154:157], v[210:213], v[80:83]
	v_mfma_f32_16x16x32_bf16 v[76:79], v[158:161], v[198:201], v[76:79]
	v_mfma_f32_16x16x32_bf16 v[72:75], v[158:161], v[202:205], v[72:75]
	v_mfma_f32_16x16x32_bf16 v[68:71], v[158:161], v[206:209], v[68:71]
	v_mfma_f32_16x16x32_bf16 v[64:67], v[158:161], v[210:213], v[64:67]
	s_add_u32 s48, s48, 0x80
	s_addc_u32 s49, s49, 0
	s_add_i32 s47, s47, 1
	s_cmp_lt_u32 s47, 15
	s_cbranch_scc0 .Lg2_last
	s_waitcnt lgkmcnt(0)
	v_mfma_f32_16x16x32_bf16 v[60:63], v[162:165], v[198:201], v[60:63]
	v_mfma_f32_16x16x32_bf16 v[56:59], v[162:165], v[202:205], v[56:59]
	v_mfma_f32_16x16x32_bf16 v[52:55], v[162:165], v[206:209], v[52:55]
	v_mfma_f32_16x16x32_bf16 v[44:47], v[162:165], v[210:213], v[44:47]
	s_waitcnt vmcnt(0)
	s_barrier
	s_xor_b32 s62, s62, 0x10000
	s_mov_b32 m0, s62
	s_add_u32 s50, s48, s12
	s_addc_u32 s51, s49, s13
	global_load_lds_dwordx4 v178, s[50:51]
	ds_read_b128 v[146:149], v217
	ds_read_b128 v[150:153], v217 offset:2048
	ds_read_b128 v[154:157], v217 offset:4096
	ds_read_b128 v[158:161], v217 offset:6144
	ds_read_b128 v[182:185], v219 offset:32768
	ds_read_b128 v[186:189], v219 offset:34816
	ds_read_b128 v[190:193], v219 offset:36864
	ds_read_b128 v[194:197], v219 offset:38912
	v_mfma_f32_16x16x32_bf16 v[36:39], v[166:169], v[198:201], v[36:39]
	v_mfma_f32_16x16x32_bf16 v[32:35], v[166:169], v[202:205], v[32:35]
	s_add_u32 m0, s62, 0x2000
	s_add_u32 s50, s48, s14
	s_addc_u32 s51, s49, s15
	global_load_lds_dwordx4 v178, s[50:51]
	v_mfma_f32_16x16x32_bf16 v[28:31], v[166:169], v[206:209], v[28:31]
	v_mfma_f32_16x16x32_bf16 v[24:27], v[166:169], v[210:213], v[24:27]
	s_add_u32 m0, s62, 0x4000
	s_add_u32 s50, s48, s16
	s_addc_u32 s51, s49, s17
	global_load_lds_dwordx4 v178, s[50:51]
	v_mfma_f32_16x16x32_bf16 v[20:23], v[170:173], v[198:201], v[20:23]
	v_mfma_f32_16x16x32_bf16 v[16:19], v[170:173], v[202:205], v[16:19]
	s_add_u32 m0, s62, 0x6000
	s_add_u32 s50, s48, s18
	s_addc_u32 s51, s49, s19
	global_load_lds_dwordx4 v178, s[50:51]
	v_mfma_f32_16x16x32_bf16 v[12:15], v[170:173], v[206:209], v[12:15]
	v_mfma_f32_16x16x32_bf16 v[8:11], v[170:173], v[210:213], v[8:11]
	s_add_u32 m0, s62, 0x8000
	s_add_u32 s50, s48, s22
	s_addc_u32 s51, s49, s23
	global_load_lds_dwordx4 v179, s[50:51]
	v_mfma_f32_16x16x32_bf16 v[4:7], v[174:177], v[198:201], v[4:7]
	v_mfma_f32_16x16x32_bf16 v[0:3], v[174:177], v[202:205], v[0:3]
	s_add_u32 m0, s62, 0xa000
	s_add_u32 s50, s48, s36
	s_addc_u32 s51, s49, s37
	global_load_lds_dwordx4 v179, s[50:51]
	v_mfma_f32_16x16x32_bf16 v[48:51], v[174:177], v[206:209], v[48:51]
	v_mfma_f32_16x16x32_bf16 v[40:43], v[174:177], v[210:213], v[40:43]
	s_add_u32 m0, s62, 0xc000
	s_add_u32 s50, s48, s40
	s_addc_u32 s51, s49, s41
	global_load_lds_dwordx4 v179, s[50:51]
	ds_read_b128 v[162:165], v217 offset:8192
	ds_read_b128 v[166:169], v217 offset:10240
	ds_read_b128 v[170:173], v217 offset:12288
	ds_read_b128 v[174:177], v217 offset:14336
	s_waitcnt lgkmcnt(4)
	v_mfma_f32_16x16x32_bf16 v[124:127], v[146:149], v[182:185], v[124:127]
	v_mfma_f32_16x16x32_bf16 v[120:123], v[146:149], v[186:189], v[120:123]
	s_add_u32 m0, s62, 0xe000
	s_add_u32 s50, s48, s42
	s_addc_u32 s51, s49, s43
	global_load_lds_dwordx4 v179, s[50:51]
	v_mfma_f32_16x16x32_bf16 v[116:119], v[146:149], v[190:193], v[116:119]
	v_mfma_f32_16x16x32_bf16 v[112:115], v[146:149], v[194:197], v[112:115]
	v_mfma_f32_16x16x32_bf16 v[108:111], v[150:153], v[182:185], v[108:111]
	v_mfma_f32_16x16x32_bf16 v[104:107], v[150:153], v[186:189], v[104:107]
	v_mfma_f32_16x16x32_bf16 v[100:103], v[150:153], v[190:193], v[100:103]
	v_mfma_f32_16x16x32_bf16 v[96:99], v[150:153], v[194:197], v[96:99]
	v_mfma_f32_16x16x32_bf16 v[92:95], v[154:157], v[182:185], v[92:95]
	v_mfma_f32_16x16x32_bf16 v[88:91], v[154:157], v[186:189], v[88:91]
	v_mfma_f32_16x16x32_bf16 v[84:87], v[154:157], v[190:193], v[84:87]
	v_mfma_f32_16x16x32_bf16 v[80:83], v[154:157], v[194:197], v[80:83]
	v_mfma_f32_16x16x32_bf16 v[76:79], v[158:161], v[182:185], v[76:79]
	v_mfma_f32_16x16x32_bf16 v[72:75], v[158:161], v[186:189], v[72:75]
	v_mfma_f32_16x16x32_bf16 v[68:71], v[158:161], v[190:193], v[68:71]
	v_mfma_f32_16x16x32_bf16 v[64:67], v[158:161], v[194:197], v[64:67]
	ds_read_b128 v[146:149], v218
	ds_read_b128 v[150:153], v218 offset:2048
	ds_read_b128 v[154:157], v218 offset:4096
	ds_read_b128 v[158:161], v218 offset:6144
	ds_read_b128 v[198:201], v220 offset:32768
	ds_read_b128 v[202:205], v220 offset:34816
	ds_read_b128 v[206:209], v220 offset:36864
	ds_read_b128 v[210:213], v220 offset:38912
	s_waitcnt lgkmcnt(8)
	v_mfma_f32_16x16x32_bf16 v[60:63], v[162:165], v[182:185], v[60:63]
	v_mfma_f32_16x16x32_bf16 v[56:59], v[162:165], v[186:189], v[56:59]
	v_mfma_f32_16x16x32_bf16 v[52:55], v[162:165], v[190:193], v[52:55]
	v_mfma_f32_16x16x32_bf16 v[44:47], v[162:165], v[194:197], v[44:47]
	v_mfma_f32_16x16x32_bf16 v[36:39], v[166:169], v[182:185], v[36:39]
	v_mfma_f32_16x16x32_bf16 v[32:35], v[166:169], v[186:189], v[32:35]
	v_mfma_f32_16x16x32_bf16 v[28:31], v[166:169], v[190:193], v[28:31]
	v_mfma_f32_16x16x32_bf16 v[24:27], v[166:169], v[194:197], v[24:27]
	v_mfma_f32_16x16x32_bf16 v[20:23], v[170:173], v[182:185], v[20:23]
	v_mfma_f32_16x16x32_bf16 v[16:19], v[170:173], v[186:189], v[16:19]
	v_mfma_f32_16x16x32_bf16 v[12:15], v[170:173], v[190:193], v[12:15]
	v_mfma_f32_16x16x32_bf16 v[8:11], v[170:173], v[194:197], v[8:11]
	v_mfma_f32_16x16x32_bf16 v[4:7], v[174:177], v[182:185], v[4:7]
	v_mfma_f32_16x16x32_bf16 v[0:3], v[174:177], v[186:189], v[0:3]
	v_mfma_f32_16x16x32_bf16 v[48:51], v[174:177], v[190:193], v[48:51]
	v_mfma_f32_16x16x32_bf16 v[40:43], v[174:177], v[194:197], v[40:43]
	ds_read_b128 v[162:165], v218 offset:8192
	ds_read_b128 v[166:169], v218 offset:10240
	ds_read_b128 v[170:173], v218 offset:12288
	ds_read_b128 v[174:177], v218 offset:14336
	s_waitcnt lgkmcnt(4)
	v_mfma_f32_16x16x32_bf16 v[124:127], v[146:149], v[198:201], v[124:127]
	v_mfma_f32_16x16x32_bf16 v[120:123], v[146:149], v[202:205], v[120:123]
	v_mfma_f32_16x16x32_bf16 v[116:119], v[146:149], v[206:209], v[116:119]
	v_mfma_f32_16x16x32_bf16 v[112:115], v[146:149], v[210:213], v[112:115]
	v_mfma_f32_16x16x32_bf16 v[108:111], v[150:153], v[198:201], v[108:111]
	v_mfma_f32_16x16x32_bf16 v[104:107], v[150:153], v[202:205], v[104:107]
	v_mfma_f32_16x16x32_bf16 v[100:103], v[150:153], v[206:209], v[100:103]
	v_mfma_f32_16x16x32_bf16 v[96:99], v[150:153], v[210:213], v[96:99]
	v_mfma_f32_16x16x32_bf16 v[92:95], v[154:157], v[198:201], v[92:95]
	v_mfma_f32_16x16x32_bf16 v[88:91], v[154:157], v[202:205], v[88:91]
	v_mfma_f32_16x16x32_bf16 v[84:87], v[154:157], v[206:209], v[84:87]
	v_mfma_f32_16x16x32_bf16 v[80:83], v[154:157], v[210:213], v[80:83]
	v_mfma_f32_16x16x32_bf16 v[76:79], v[158:161], v[198:201], v[76:79]
	v_mfma_f32_16x16x32_bf16 v[72:75], v[158:161], v[202:205], v[72:75]
	v_mfma_f32_16x16x32_bf16 v[68:71], v[158:161], v[206:209], v[68:71]
	v_mfma_f32_16x16x32_bf16 v[64:67], v[158:161], v[210:213], v[64:67]
	s_add_u32 s48, s48, 0x80
	s_addc_u32 s49, s49, 0
	s_add_i32 s47, s47, 1
	s_branch .Lg2_top
.Lg2_last:
	s_waitcnt lgkmcnt(0)
	v_mfma_f32_16x16x32_bf16 v[60:63], v[162:165], v[198:201], v[60:63]
	v_mfma_f32_16x16x32_bf16 v[56:59], v[162:165], v[202:205], v[56:59]
	v_mfma_f32_16x16x32_bf16 v[52:55], v[162:165], v[206:209], v[52:55]
	v_mfma_f32_16x16x32_bf16 v[44:47], v[162:165], v[210:213], v[44:47]
	s_waitcnt vmcnt(0)
	s_barrier
	s_xor_b32 s62, s62, 0x10000
	ds_read_b128 v[146:149], v217
	ds_read_b128 v[150:153], v217 offset:2048
	ds_read_b128 v[154:157], v217 offset:4096
	ds_read_b128 v[158:161], v217 offset:6144
	ds_read_b128 v[182:185], v219 offset:32768
	ds_read_b128 v[186:189], v219 offset:34816
	ds_read_b128 v[190:193], v219 offset:36864
	ds_read_b128 v[194:197], v219 offset:38912
	v_mfma_f32_16x16x32_bf16 v[36:39], v[166:169], v[198:201], v[36:39]
	v_mfma_f32_16x16x32_bf16 v[32:35], v[166:169], v[202:205], v[32:35]
	v_mfma_f32_16x16x32_bf16 v[28:31], v[166:169], v[206:209], v[28:31]
	v_mfma_f32_16x16x32_bf16 v[24:27], v[166:169], v[210:213], v[24:27]
	v_mfma_f32_16x16x32_bf16 v[20:23], v[170:173], v[198:201], v[20:23]
	v_mfma_f32_16x16x32_bf16 v[16:19], v[170:173], v[202:205], v[16:19]
	v_mfma_f32_16x16x32_bf16 v[12:15], v[170:173], v[206:209], v[12:15]
	v_mfma_f32_16x16x32_bf16 v[8:11], v[170:173], v[210:213], v[8:11]
	v_mfma_f32_16x16x32_bf16 v[4:7], v[174:177], v[198:201], v[4:7]
	v_mfma_f32_16x16x32_bf16 v[0:3], v[174:177], v[202:205], v[0:3]
	v_mfma_f32_16x16x32_bf16 v[48:51], v[174:177], v[206:209], v[48:51]
	v_mfma_f32_16x16x32_bf16 v[40:43], v[174:177], v[210:213], v[40:43]
	ds_read_b128 v[162:165], v217 offset:8192
	ds_read_b128 v[166:169], v217 offset:10240
	ds_read_b128 v[170:173], v217 offset:12288
	ds_read_b128 v[174:177], v217 offset:14336
	s_waitcnt lgkmcnt(4)
	v_mfma_f32_16x16x32_bf16 v[124:127], v[146:149], v[182:185], v[124:127]
	v_mfma_f32_16x16x32_bf16 v[120:123], v[146:149], v[186:189], v[120:123]
	v_mfma_f32_16x16x32_bf16 v[116:119], v[146:149], v[190:193], v[116:119]
	v_mfma_f32_16x16x32_bf16 v[112:115], v[146:149], v[194:197], v[112:115]
	v_mfma_f32_16x16x32_bf16 v[108:111], v[150:153], v[182:185], v[108:111]
	v_mfma_f32_16x16x32_bf16 v[104:107], v[150:153], v[186:189], v[104:107]
	v_mfma_f32_16x16x32_bf16 v[100:103], v[150:153], v[190:193], v[100:103]
	v_mfma_f32_16x16x32_bf16 v[96:99], v[150:153], v[194:197], v[96:99]
	v_mfma_f32_16x16x32_bf16 v[92:95], v[154:157], v[182:185], v[92:95]
	v_mfma_f32_16x16x32_bf16 v[88:91], v[154:157], v[186:189], v[88:91]
	v_mfma_f32_16x16x32_bf16 v[84:87], v[154:157], v[190:193], v[84:87]
	v_mfma_f32_16x16x32_bf16 v[80:83], v[154:157], v[194:197], v[80:83]
	v_mfma_f32_16x16x32_bf16 v[76:79], v[158:161], v[182:185], v[76:79]
	v_mfma_f32_16x16x32_bf16 v[72:75], v[158:161], v[186:189], v[72:75]
	v_mfma_f32_16x16x32_bf16 v[68:71], v[158:161], v[190:193], v[68:71]
	v_mfma_f32_16x16x32_bf16 v[64:67], v[158:161], v[194:197], v[64:67]
	ds_read_b128 v[146:149], v218
	ds_read_b128 v[150:153], v218 offset:2048
	ds_read_b128 v[154:157], v218 offset:4096
	ds_read_b128 v[158:161], v218 offset:6144
	ds_read_b128 v[198:201], v220 offset:32768
	ds_read_b128 v[202:205], v220 offset:34816
	ds_read_b128 v[206:209], v220 offset:36864
	ds_read_b128 v[210:213], v220 offset:38912
	s_waitcnt lgkmcnt(8)
	v_mfma_f32_16x16x32_bf16 v[60:63], v[162:165], v[182:185], v[60:63]
	v_mfma_f32_16x16x32_bf16 v[56:59], v[162:165], v[186:189], v[56:59]
	v_mfma_f32_16x16x32_bf16 v[52:55], v[162:165], v[190:193], v[52:55]
	v_mfma_f32_16x16x32_bf16 v[44:47], v[162:165], v[194:197], v[44:47]
	v_mfma_f32_16x16x32_bf16 v[36:39], v[166:169], v[182:185], v[36:39]
	v_mfma_f32_16x16x32_bf16 v[32:35], v[166:169], v[186:189], v[32:35]
	v_mfma_f32_16x16x32_bf16 v[28:31], v[166:169], v[190:193], v[28:31]
	v_mfma_f32_16x16x32_bf16 v[24:27], v[166:169], v[194:197], v[24:27]
	v_mfma_f32_16x16x32_bf16 v[20:23], v[170:173], v[182:185], v[20:23]
	v_mfma_f32_16x16x32_bf16 v[16:19], v[170:173], v[186:189], v[16:19]
	v_mfma_f32_16x16x32_bf16 v[12:15], v[170:173], v[190:193], v[12:15]
	v_mfma_f32_16x16x32_bf16 v[8:11], v[170:173], v[194:197], v[8:11]
	v_mfma_f32_16x16x32_bf16 v[4:7], v[174:177], v[182:185], v[4:7]
	v_mfma_f32_16x16x32_bf16 v[0:3], v[174:177], v[186:189], v[0:3]
	v_mfma_f32_16x16x32_bf16 v[48:51], v[174:177], v[190:193], v[48:51]
	v_mfma_f32_16x16x32_bf16 v[40:43], v[174:177], v[194:197], v[40:43]
	ds_read_b128 v[162:165], v218 offset:8192
	ds_read_b128 v[166:169], v218 offset:10240
	ds_read_b128 v[170:173], v218 offset:12288
	ds_read_b128 v[174:177], v218 offset:14336
	s_waitcnt lgkmcnt(4)
	v_mfma_f32_16x16x32_bf16 v[124:127], v[146:149], v[198:201], v[124:127]
	v_mfma_f32_16x16x32_bf16 v[120:123], v[146:149], v[202:205], v[120:123]
	v_mfma_f32_16x16x32_bf16 v[116:119], v[146:149], v[206:209], v[116:119]
	v_mfma_f32_16x16x32_bf16 v[112:115], v[146:149], v[210:213], v[112:115]
	v_mfma_f32_16x16x32_bf16 v[108:111], v[150:153], v[198:201], v[108:111]
	v_mfma_f32_16x16x32_bf16 v[104:107], v[150:153], v[202:205], v[104:107]
	v_mfma_f32_16x16x32_bf16 v[100:103], v[150:153], v[206:209], v[100:103]
	v_mfma_f32_16x16x32_bf16 v[96:99], v[150:153], v[210:213], v[96:99]
	v_mfma_f32_16x16x32_bf16 v[92:95], v[154:157], v[198:201], v[92:95]
	v_mfma_f32_16x16x32_bf16 v[88:91], v[154:157], v[202:205], v[88:91]
	v_mfma_f32_16x16x32_bf16 v[84:87], v[154:157], v[206:209], v[84:87]
	v_mfma_f32_16x16x32_bf16 v[80:83], v[154:157], v[210:213], v[80:83]
	v_mfma_f32_16x16x32_bf16 v[76:79], v[158:161], v[198:201], v[76:79]
	v_mfma_f32_16x16x32_bf16 v[72:75], v[158:161], v[202:205], v[72:75]
	v_mfma_f32_16x16x32_bf16 v[68:71], v[158:161], v[206:209], v[68:71]
	v_mfma_f32_16x16x32_bf16 v[64:67], v[158:161], v[210:213], v[64:67]
	s_add_u32 s48, s48, 0x80
	s_addc_u32 s49, s49, 0
	s_add_i32 s47, s47, 1
	s_waitcnt lgkmcnt(0)
	s_waitcnt vmcnt(0)
	s_barrier
	v_mfma_f32_16x16x32_bf16 v[60:63], v[162:165], v[198:201], v[60:63]
	v_mfma_f32_16x16x32_bf16 v[56:59], v[162:165], v[202:205], v[56:59]
	v_mfma_f32_16x16x32_bf16 v[52:55], v[162:165], v[206:209], v[52:55]
	v_mfma_f32_16x16x32_bf16 v[44:47], v[162:165], v[210:213], v[44:47]
	v_mfma_f32_16x16x32_bf16 v[36:39], v[166:169], v[198:201], v[36:39]
	v_mfma_f32_16x16x32_bf16 v[32:35], v[166:169], v[202:205], v[32:35]
	v_mfma_f32_16x16x32_bf16 v[28:31], v[166:169], v[206:209], v[28:31]
	v_mfma_f32_16x16x32_bf16 v[24:27], v[166:169], v[210:213], v[24:27]
	v_mfma_f32_16x16x32_bf16 v[20:23], v[170:173], v[198:201], v[20:23]
	v_mfma_f32_16x16x32_bf16 v[16:19], v[170:173], v[202:205], v[16:19]
	v_mfma_f32_16x16x32_bf16 v[12:15], v[170:173], v[206:209], v[12:15]
	v_mfma_f32_16x16x32_bf16 v[8:11], v[170:173], v[210:213], v[8:11]
	v_mfma_f32_16x16x32_bf16 v[4:7], v[174:177], v[198:201], v[4:7]
	v_mfma_f32_16x16x32_bf16 v[0:3], v[174:177], v[202:205], v[0:3]
	v_mfma_f32_16x16x32_bf16 v[48:51], v[174:177], v[206:209], v[48:51]
	v_mfma_f32_16x16x32_bf16 v[40:43], v[174:177], v[210:213], v[40:43]
	s_nop 7
	s_nop 7
	s_sub_u32 s48, s48, s34
	s_subb_u32 s49, s49, s35
	s_mov_b32 s62, 0x80000
	s_mov_b32 s63, 0x80000
	s_mov_b64 s[50:51], 0
	s_mov_b64 vcc, exec
	s_branch .LBB0_458

.Lg5_top:
	s_waitcnt lgkmcnt(0)
	v_mfma_f32_16x16x32_bf16 v[60:63], v[194:197], v[226:229], v[60:63]
	v_mfma_f32_16x16x32_bf16 v[56:59], v[194:197], v[230:233], v[56:59]
	v_mfma_f32_16x16x32_bf16 v[52:55], v[194:197], v[234:237], v[52:55]
	v_mfma_f32_16x16x32_bf16 v[48:51], v[194:197], v[238:241], v[48:51]
	s_waitcnt vmcnt(0)
	s_barrier
	s_xor_b32 s87, s87, 0x10000
	s_mov_b32 m0, s87
	s_add_u32 s70, s68, 0x4000080
	s_addc_u32 s71, s69, 0
	global_load_lds_dwordx4 v242, s[70:71]
	ds_read_b128 v[176:179], v180
	ds_read_b128 v[182:185], v180 offset:2048
	ds_read_b128 v[186:189], v180 offset:4096
	ds_read_b128 v[190:193], v180 offset:6144
	ds_read_b128 v[210:213], v245 offset:32768
	ds_read_b128 v[214:217], v245 offset:34816
	ds_read_b128 v[218:221], v245 offset:36864
	ds_read_b128 v[222:225], v245 offset:38912
	v_mfma_f32_16x16x32_bf16 v[44:47], v[198:201], v[226:229], v[44:47]
	v_mfma_f32_16x16x32_bf16 v[40:43], v[198:201], v[230:233], v[40:43]
	s_add_u32 m0, s87, 0x2000
	s_add_u32 s70, s68, 0x4020080
	s_addc_u32 s71, s69, 0
	global_load_lds_dwordx4 v242, s[70:71]
	v_mfma_f32_16x16x32_bf16 v[36:39], v[198:201], v[234:237], v[36:39]
	v_mfma_f32_16x16x32_bf16 v[32:35], v[198:201], v[238:241], v[32:35]
	s_add_u32 m0, s87, 0x4000
	s_add_u32 s70, s68, 0x4040080
	s_addc_u32 s71, s69, 0
	global_load_lds_dwordx4 v242, s[70:71]
	v_mfma_f32_16x16x32_bf16 v[28:31], v[202:205], v[226:229], v[28:31]
	v_mfma_f32_16x16x32_bf16 v[24:27], v[202:205], v[230:233], v[24:27]
	s_add_u32 m0, s87, 0x6000
	s_add_u32 s70, s68, s14
	s_addc_u32 s71, s69, s15
	global_load_lds_dwordx4 v242, s[70:71]
	v_mfma_f32_16x16x32_bf16 v[20:23], v[202:205], v[234:237], v[20:23]
	v_mfma_f32_16x16x32_bf16 v[16:19], v[202:205], v[238:241], v[16:19]
	s_add_u32 m0, s87, 0x8000
	s_add_u32 s70, s68, s16
	s_addc_u32 s71, s69, s17
	global_load_lds_dwordx4 v243, s[70:71]
	v_mfma_f32_16x16x32_bf16 v[8:11], v[206:209], v[226:229], v[8:11]
	v_mfma_f32_16x16x32_bf16 v[0:3], v[206:209], v[230:233], v[0:3]
	s_add_u32 m0, s87, 0xa000
	s_add_u32 s70, s68, s18
	s_addc_u32 s71, s69, s19
	global_load_lds_dwordx4 v243, s[70:71]
	v_mfma_f32_16x16x32_bf16 v[12:15], v[206:209], v[234:237], v[12:15]
	v_mfma_f32_16x16x32_bf16 v[4:7], v[206:209], v[238:241], v[4:7]
	s_add_u32 m0, s87, 0xc000
	s_add_u32 s70, s68, s22
	s_addc_u32 s71, s69, s23
	global_load_lds_dwordx4 v243, s[70:71]
.Lg5_entry:
	ds_read_b128 v[194:197], v180 offset:8192
	ds_read_b128 v[198:201], v180 offset:10240
	ds_read_b128 v[202:205], v180 offset:12288
	ds_read_b128 v[206:209], v180 offset:14336
	s_waitcnt lgkmcnt(4)
	v_mfma_f32_16x16x32_bf16 v[124:127], v[176:179], v[210:213], v[124:127]
	v_mfma_f32_16x16x32_bf16 v[120:123], v[176:179], v[214:217], v[120:123]
	s_add_u32 m0, s87, 0xe000
	s_add_u32 s70, s68, s36
	s_addc_u32 s71, s69, s37
	global_load_lds_dwordx4 v243, s[70:71]
	v_mfma_f32_16x16x32_bf16 v[116:119], v[176:179], v[218:221], v[116:119]
	v_mfma_f32_16x16x32_bf16 v[112:115], v[176:179], v[222:225], v[112:115]
	v_mfma_f32_16x16x32_bf16 v[108:111], v[182:185], v[210:213], v[108:111]
	v_mfma_f32_16x16x32_bf16 v[104:107], v[182:185], v[214:217], v[104:107]
	v_mfma_f32_16x16x32_bf16 v[100:103], v[182:185], v[218:221], v[100:103]
	v_mfma_f32_16x16x32_bf16 v[96:99], v[182:185], v[222:225], v[96:99]
	v_mfma_f32_16x16x32_bf16 v[92:95], v[186:189], v[210:213], v[92:95]
	v_mfma_f32_16x16x32_bf16 v[88:91], v[186:189], v[214:217], v[88:91]
	v_mfma_f32_16x16x32_bf16 v[84:87], v[186:189], v[218:221], v[84:87]
	v_mfma_f32_16x16x32_bf16 v[80:83], v[186:189], v[222:225], v[80:83]
	v_mfma_f32_16x16x32_bf16 v[76:79], v[190:193], v[210:213], v[76:79]
	v_mfma_f32_16x16x32_bf16 v[72:75], v[190:193], v[214:217], v[72:75]
	v_mfma_f32_16x16x32_bf16 v[68:71], v[190:193], v[218:221], v[68:71]
	v_mfma_f32_16x16x32_bf16 v[64:67], v[190:193], v[222:225], v[64:67]
	ds_read_b128 v[176:179], v244
	ds_read_b128 v[182:185], v244 offset:2048
	ds_read_b128 v[186:189], v244 offset:4096
	ds_read_b128 v[190:193], v244 offset:6144
	ds_read_b128 v[226:229], v246 offset:32768
	ds_read_b128 v[230:233], v246 offset:34816
	ds_read_b128 v[234:237], v246 offset:36864
	ds_read_b128 v[238:241], v246 offset:38912
	s_waitcnt lgkmcnt(8)
	v_mfma_f32_16x16x32_bf16 v[60:63], v[194:197], v[210:213], v[60:63]
	v_mfma_f32_16x16x32_bf16 v[56:59], v[194:197], v[214:217], v[56:59]
	v_mfma_f32_16x16x32_bf16 v[52:55], v[194:197], v[218:221], v[52:55]
	v_mfma_f32_16x16x32_bf16 v[48:51], v[194:197], v[222:225], v[48:51]
	v_mfma_f32_16x16x32_bf16 v[44:47], v[198:201], v[210:213], v[44:47]
	v_mfma_f32_16x16x32_bf16 v[40:43], v[198:201], v[214:217], v[40:43]
	v_mfma_f32_16x16x32_bf16 v[36:39], v[198:201], v[218:221], v[36:39]
	v_mfma_f32_16x16x32_bf16 v[32:35], v[198:201], v[222:225], v[32:35]
	v_mfma_f32_16x16x32_bf16 v[28:31], v[202:205], v[210:213], v[28:31]
	v_mfma_f32_16x16x32_bf16 v[24:27], v[202:205], v[214:217], v[24:27]
	v_mfma_f32_16x16x32_bf16 v[20:23], v[202:205], v[218:221], v[20:23]
	v_mfma_f32_16x16x32_bf16 v[16:19], v[202:205], v[222:225], v[16:19]
	v_mfma_f32_16x16x32_bf16 v[8:11], v[206:209], v[210:213], v[8:11]
	v_mfma_f32_16x16x32_bf16 v[0:3], v[206:209], v[214:217], v[0:3]
	v_mfma_f32_16x16x32_bf16 v[12:15], v[206:209], v[218:221], v[12:15]
	v_mfma_f32_16x16x32_bf16 v[4:7], v[206:209], v[222:225], v[4:7]
	ds_read_b128 v[194:197], v244 offset:8192
	ds_read_b128 v[198:201], v244 offset:10240
	ds_read_b128 v[202:205], v244 offset:12288
	ds_read_b128 v[206:209], v244 offset:14336
	s_waitcnt lgkmcnt(4)
	v_mfma_f32_16x16x32_bf16 v[124:127], v[176:179], v[226:229], v[124:127]
	v_mfma_f32_16x16x32_bf16 v[120:123], v[176:179], v[230:233], v[120:123]
	v_mfma_f32_16x16x32_bf16 v[116:119], v[176:179], v[234:237], v[116:119]
	v_mfma_f32_16x16x32_bf16 v[112:115], v[176:179], v[238:241], v[112:115]
	v_mfma_f32_16x16x32_bf16 v[108:111], v[182:185], v[226:229], v[108:111]
	v_mfma_f32_16x16x32_bf16 v[104:107], v[182:185], v[230:233], v[104:107]
	v_mfma_f32_16x16x32_bf16 v[100:103], v[182:185], v[234:237], v[100:103]
	v_mfma_f32_16x16x32_bf16 v[96:99], v[182:185], v[238:241], v[96:99]
	v_mfma_f32_16x16x32_bf16 v[92:95], v[186:189], v[226:229], v[92:95]
	v_mfma_f32_16x16x32_bf16 v[88:91], v[186:189], v[230:233], v[88:91]
	v_mfma_f32_16x16x32_bf16 v[84:87], v[186:189], v[234:237], v[84:87]
	v_mfma_f32_16x16x32_bf16 v[80:83], v[186:189], v[238:241], v[80:83]
	v_mfma_f32_16x16x32_bf16 v[76:79], v[190:193], v[226:229], v[76:79]
	v_mfma_f32_16x16x32_bf16 v[72:75], v[190:193], v[230:233], v[72:75]
	v_mfma_f32_16x16x32_bf16 v[68:71], v[190:193], v[234:237], v[68:71]
	v_mfma_f32_16x16x32_bf16 v[64:67], v[190:193], v[238:241], v[64:67]
	s_add_u32 s68, s68, 0x80
	s_addc_u32 s69, s69, 0
	s_add_i32 s86, s86, 1
	s_cmp_lt_u32 s86, 15
	s_cbranch_scc0 .Lg5_last
	s_waitcnt lgkmcnt(0)
	v_mfma_f32_16x16x32_bf16 v[60:63], v[194:197], v[226:229], v[60:63]
	v_mfma_f32_16x16x32_bf16 v[56:59], v[194:197], v[230:233], v[56:59]
	v_mfma_f32_16x16x32_bf16 v[52:55], v[194:197], v[234:237], v[52:55]
	v_mfma_f32_16x16x32_bf16 v[48:51], v[194:197], v[238:241], v[48:51]
	s_waitcnt vmcnt(0)
	s_barrier
	s_xor_b32 s87, s87, 0x10000
	s_mov_b32 m0, s87
	s_add_u32 s70, s68, 0x4000080
	s_addc_u32 s71, s69, 0
	global_load_lds_dwordx4 v242, s[70:71]
	ds_read_b128 v[176:179], v247
	ds_read_b128 v[182:185], v247 offset:2048
	ds_read_b128 v[186:189], v247 offset:4096
	ds_read_b128 v[190:193], v247 offset:6144
	ds_read_b128 v[210:213], v249 offset:32768
	ds_read_b128 v[214:217], v249 offset:34816
	ds_read_b128 v[218:221], v249 offset:36864
	ds_read_b128 v[222:225], v249 offset:38912
	v_mfma_f32_16x16x32_bf16 v[44:47], v[198:201], v[226:229], v[44:47]
	v_mfma_f32_16x16x32_bf16 v[40:43], v[198:201], v[230:233], v[40:43]
	s_add_u32 m0, s87, 0x2000
	s_add_u32 s70, s68, 0x4020080
	s_addc_u32 s71, s69, 0
	global_load_lds_dwordx4 v242, s[70:71]
	v_mfma_f32_16x16x32_bf16 v[36:39], v[198:201], v[234:237], v[36:39]
	v_mfma_f32_16x16x32_bf16 v[32:35], v[198:201], v[238:241], v[32:35]
	s_add_u32 m0, s87, 0x4000
	s_add_u32 s70, s68, 0x4040080
	s_addc_u32 s71, s69, 0
	global_load_lds_dwordx4 v242, s[70:71]
	v_mfma_f32_16x16x32_bf16 v[28:31], v[202:205], v[226:229], v[28:31]
	v_mfma_f32_16x16x32_bf16 v[24:27], v[202:205], v[230:233], v[24:27]
	s_add_u32 m0, s87, 0x6000
	s_add_u32 s70, s68, s14
	s_addc_u32 s71, s69, s15
	global_load_lds_dwordx4 v242, s[70:71]
	v_mfma_f32_16x16x32_bf16 v[20:23], v[202:205], v[234:237], v[20:23]
	v_mfma_f32_16x16x32_bf16 v[16:19], v[202:205], v[238:241], v[16:19]
	s_add_u32 m0, s87, 0x8000
	s_add_u32 s70, s68, s16
	s_addc_u32 s71, s69, s17
	global_load_lds_dwordx4 v243, s[70:71]
	v_mfma_f32_16x16x32_bf16 v[8:11], v[206:209], v[226:229], v[8:11]
	v_mfma_f32_16x16x32_bf16 v[0:3], v[206:209], v[230:233], v[0:3]
	s_add_u32 m0, s87, 0xa000
	s_add_u32 s70, s68, s18
	s_addc_u32 s71, s69, s19
	global_load_lds_dwordx4 v243, s[70:71]
	v_mfma_f32_16x16x32_bf16 v[12:15], v[206:209], v[234:237], v[12:15]
	v_mfma_f32_16x16x32_bf16 v[4:7], v[206:209], v[238:241], v[4:7]
	s_add_u32 m0, s87, 0xc000
	s_add_u32 s70, s68, s22
	s_addc_u32 s71, s69, s23
	global_load_lds_dwordx4 v243, s[70:71]
	ds_read_b128 v[194:197], v247 offset:8192
	ds_read_b128 v[198:201], v247 offset:10240
	ds_read_b128 v[202:205], v247 offset:12288
	ds_read_b128 v[206:209], v247 offset:14336
	s_waitcnt lgkmcnt(4)
	v_mfma_f32_16x16x32_bf16 v[124:127], v[176:179], v[210:213], v[124:127]
	v_mfma_f32_16x16x32_bf16 v[120:123], v[176:179], v[214:217], v[120:123]
	s_add_u32 m0, s87, 0xe000
	s_add_u32 s70, s68, s36
	s_addc_u32 s71, s69, s37
	global_load_lds_dwordx4 v243, s[70:71]
	v_mfma_f32_16x16x32_bf16 v[116:119], v[176:179], v[218:221], v[116:119]
	v_mfma_f32_16x16x32_bf16 v[112:115], v[176:179], v[222:225], v[112:115]
	v_mfma_f32_16x16x32_bf16 v[108:111], v[182:185], v[210:213], v[108:111]
	v_mfma_f32_16x16x32_bf16 v[104:107], v[182:185], v[214:217], v[104:107]
	v_mfma_f32_16x16x32_bf16 v[100:103], v[182:185], v[218:221], v[100:103]
	v_mfma_f32_16x16x32_bf16 v[96:99], v[182:185], v[222:225], v[96:99]
	v_mfma_f32_16x16x32_bf16 v[92:95], v[186:189], v[210:213], v[92:95]
	v_mfma_f32_16x16x32_bf16 v[88:91], v[186:189], v[214:217], v[88:91]
	v_mfma_f32_16x16x32_bf16 v[84:87], v[186:189], v[218:221], v[84:87]
	v_mfma_f32_16x16x32_bf16 v[80:83], v[186:189], v[222:225], v[80:83]
	v_mfma_f32_16x16x32_bf16 v[76:79], v[190:193], v[210:213], v[76:79]
	v_mfma_f32_16x16x32_bf16 v[72:75], v[190:193], v[214:217], v[72:75]
	v_mfma_f32_16x16x32_bf16 v[68:71], v[190:193], v[218:221], v[68:71]
	v_mfma_f32_16x16x32_bf16 v[64:67], v[190:193], v[222:225], v[64:67]
	ds_read_b128 v[176:179], v248
	ds_read_b128 v[182:185], v248 offset:2048
	ds_read_b128 v[186:189], v248 offset:4096
	ds_read_b128 v[190:193], v248 offset:6144
	ds_read_b128 v[226:229], v250 offset:32768
	ds_read_b128 v[230:233], v250 offset:34816
	ds_read_b128 v[234:237], v250 offset:36864
	ds_read_b128 v[238:241], v250 offset:38912
	s_waitcnt lgkmcnt(8)
	v_mfma_f32_16x16x32_bf16 v[60:63], v[194:197], v[210:213], v[60:63]
	v_mfma_f32_16x16x32_bf16 v[56:59], v[194:197], v[214:217], v[56:59]
	v_mfma_f32_16x16x32_bf16 v[52:55], v[194:197], v[218:221], v[52:55]
	v_mfma_f32_16x16x32_bf16 v[48:51], v[194:197], v[222:225], v[48:51]
	v_mfma_f32_16x16x32_bf16 v[44:47], v[198:201], v[210:213], v[44:47]
	v_mfma_f32_16x16x32_bf16 v[40:43], v[198:201], v[214:217], v[40:43]
	v_mfma_f32_16x16x32_bf16 v[36:39], v[198:201], v[218:221], v[36:39]
	v_mfma_f32_16x16x32_bf16 v[32:35], v[198:201], v[222:225], v[32:35]
	v_mfma_f32_16x16x32_bf16 v[28:31], v[202:205], v[210:213], v[28:31]
	v_mfma_f32_16x16x32_bf16 v[24:27], v[202:205], v[214:217], v[24:27]
	v_mfma_f32_16x16x32_bf16 v[20:23], v[202:205], v[218:221], v[20:23]
	v_mfma_f32_16x16x32_bf16 v[16:19], v[202:205], v[222:225], v[16:19]
	v_mfma_f32_16x16x32_bf16 v[8:11], v[206:209], v[210:213], v[8:11]
	v_mfma_f32_16x16x32_bf16 v[0:3], v[206:209], v[214:217], v[0:3]
	v_mfma_f32_16x16x32_bf16 v[12:15], v[206:209], v[218:221], v[12:15]
	v_mfma_f32_16x16x32_bf16 v[4:7], v[206:209], v[222:225], v[4:7]
	ds_read_b128 v[194:197], v248 offset:8192
	ds_read_b128 v[198:201], v248 offset:10240
	ds_read_b128 v[202:205], v248 offset:12288
	ds_read_b128 v[206:209], v248 offset:14336
	s_waitcnt lgkmcnt(4)
	v_mfma_f32_16x16x32_bf16 v[124:127], v[176:179], v[226:229], v[124:127]
	v_mfma_f32_16x16x32_bf16 v[120:123], v[176:179], v[230:233], v[120:123]
	v_mfma_f32_16x16x32_bf16 v[116:119], v[176:179], v[234:237], v[116:119]
	v_mfma_f32_16x16x32_bf16 v[112:115], v[176:179], v[238:241], v[112:115]
	v_mfma_f32_16x16x32_bf16 v[108:111], v[182:185], v[226:229], v[108:111]
	v_mfma_f32_16x16x32_bf16 v[104:107], v[182:185], v[230:233], v[104:107]
	v_mfma_f32_16x16x32_bf16 v[100:103], v[182:185], v[234:237], v[100:103]
	v_mfma_f32_16x16x32_bf16 v[96:99], v[182:185], v[238:241], v[96:99]
	v_mfma_f32_16x16x32_bf16 v[92:95], v[186:189], v[226:229], v[92:95]
	v_mfma_f32_16x16x32_bf16 v[88:91], v[186:189], v[230:233], v[88:91]
	v_mfma_f32_16x16x32_bf16 v[84:87], v[186:189], v[234:237], v[84:87]
	v_mfma_f32_16x16x32_bf16 v[80:83], v[186:189], v[238:241], v[80:83]
	v_mfma_f32_16x16x32_bf16 v[76:79], v[190:193], v[226:229], v[76:79]
	v_mfma_f32_16x16x32_bf16 v[72:75], v[190:193], v[230:233], v[72:75]
	v_mfma_f32_16x16x32_bf16 v[68:71], v[190:193], v[234:237], v[68:71]
	v_mfma_f32_16x16x32_bf16 v[64:67], v[190:193], v[238:241], v[64:67]
	s_add_u32 s68, s68, 0x80
	s_addc_u32 s69, s69, 0
	s_add_i32 s86, s86, 1
	s_branch .Lg5_top
.Lg5_last:
	s_waitcnt lgkmcnt(0)
	v_mfma_f32_16x16x32_bf16 v[60:63], v[194:197], v[226:229], v[60:63]
	v_mfma_f32_16x16x32_bf16 v[56:59], v[194:197], v[230:233], v[56:59]
	v_mfma_f32_16x16x32_bf16 v[52:55], v[194:197], v[234:237], v[52:55]
	v_mfma_f32_16x16x32_bf16 v[48:51], v[194:197], v[238:241], v[48:51]
	s_waitcnt vmcnt(0)
	s_barrier
	s_xor_b32 s87, s87, 0x10000
	ds_read_b128 v[176:179], v247
	ds_read_b128 v[182:185], v247 offset:2048
	ds_read_b128 v[186:189], v247 offset:4096
	ds_read_b128 v[190:193], v247 offset:6144
	ds_read_b128 v[210:213], v249 offset:32768
	ds_read_b128 v[214:217], v249 offset:34816
	ds_read_b128 v[218:221], v249 offset:36864
	ds_read_b128 v[222:225], v249 offset:38912
	v_mfma_f32_16x16x32_bf16 v[44:47], v[198:201], v[226:229], v[44:47]
	v_mfma_f32_16x16x32_bf16 v[40:43], v[198:201], v[230:233], v[40:43]
	v_mfma_f32_16x16x32_bf16 v[36:39], v[198:201], v[234:237], v[36:39]
	v_mfma_f32_16x16x32_bf16 v[32:35], v[198:201], v[238:241], v[32:35]
	v_mfma_f32_16x16x32_bf16 v[28:31], v[202:205], v[226:229], v[28:31]
	v_mfma_f32_16x16x32_bf16 v[24:27], v[202:205], v[230:233], v[24:27]
	v_mfma_f32_16x16x32_bf16 v[20:23], v[202:205], v[234:237], v[20:23]
	v_mfma_f32_16x16x32_bf16 v[16:19], v[202:205], v[238:241], v[16:19]
	v_mfma_f32_16x16x32_bf16 v[8:11], v[206:209], v[226:229], v[8:11]
	v_mfma_f32_16x16x32_bf16 v[0:3], v[206:209], v[230:233], v[0:3]
	v_mfma_f32_16x16x32_bf16 v[12:15], v[206:209], v[234:237], v[12:15]
	v_mfma_f32_16x16x32_bf16 v[4:7], v[206:209], v[238:241], v[4:7]
	ds_read_b128 v[194:197], v247 offset:8192
	ds_read_b128 v[198:201], v247 offset:10240
	ds_read_b128 v[202:205], v247 offset:12288
	ds_read_b128 v[206:209], v247 offset:14336
	s_waitcnt lgkmcnt(4)
	v_mfma_f32_16x16x32_bf16 v[124:127], v[176:179], v[210:213], v[124:127]
	v_mfma_f32_16x16x32_bf16 v[120:123], v[176:179], v[214:217], v[120:123]
	v_mfma_f32_16x16x32_bf16 v[116:119], v[176:179], v[218:221], v[116:119]
	v_mfma_f32_16x16x32_bf16 v[112:115], v[176:179], v[222:225], v[112:115]
	v_mfma_f32_16x16x32_bf16 v[108:111], v[182:185], v[210:213], v[108:111]
	v_mfma_f32_16x16x32_bf16 v[104:107], v[182:185], v[214:217], v[104:107]
	v_mfma_f32_16x16x32_bf16 v[100:103], v[182:185], v[218:221], v[100:103]
	v_mfma_f32_16x16x32_bf16 v[96:99], v[182:185], v[222:225], v[96:99]
	v_mfma_f32_16x16x32_bf16 v[92:95], v[186:189], v[210:213], v[92:95]
	v_mfma_f32_16x16x32_bf16 v[88:91], v[186:189], v[214:217], v[88:91]
	v_mfma_f32_16x16x32_bf16 v[84:87], v[186:189], v[218:221], v[84:87]
	v_mfma_f32_16x16x32_bf16 v[80:83], v[186:189], v[222:225], v[80:83]
	v_mfma_f32_16x16x32_bf16 v[76:79], v[190:193], v[210:213], v[76:79]
	v_mfma_f32_16x16x32_bf16 v[72:75], v[190:193], v[214:217], v[72:75]
	v_mfma_f32_16x16x32_bf16 v[68:71], v[190:193], v[218:221], v[68:71]
	v_mfma_f32_16x16x32_bf16 v[64:67], v[190:193], v[222:225], v[64:67]
	ds_read_b128 v[176:179], v248
	ds_read_b128 v[182:185], v248 offset:2048
	ds_read_b128 v[186:189], v248 offset:4096
	ds_read_b128 v[190:193], v248 offset:6144
	ds_read_b128 v[226:229], v250 offset:32768
	ds_read_b128 v[230:233], v250 offset:34816
	ds_read_b128 v[234:237], v250 offset:36864
	ds_read_b128 v[238:241], v250 offset:38912
	s_waitcnt lgkmcnt(8)
	v_mfma_f32_16x16x32_bf16 v[60:63], v[194:197], v[210:213], v[60:63]
	v_mfma_f32_16x16x32_bf16 v[56:59], v[194:197], v[214:217], v[56:59]
	v_mfma_f32_16x16x32_bf16 v[52:55], v[194:197], v[218:221], v[52:55]
	v_mfma_f32_16x16x32_bf16 v[48:51], v[194:197], v[222:225], v[48:51]
	v_mfma_f32_16x16x32_bf16 v[44:47], v[198:201], v[210:213], v[44:47]
	v_mfma_f32_16x16x32_bf16 v[40:43], v[198:201], v[214:217], v[40:43]
	v_mfma_f32_16x16x32_bf16 v[36:39], v[198:201], v[218:221], v[36:39]
	v_mfma_f32_16x16x32_bf16 v[32:35], v[198:201], v[222:225], v[32:35]
	v_mfma_f32_16x16x32_bf16 v[28:31], v[202:205], v[210:213], v[28:31]
	v_mfma_f32_16x16x32_bf16 v[24:27], v[202:205], v[214:217], v[24:27]
	v_mfma_f32_16x16x32_bf16 v[20:23], v[202:205], v[218:221], v[20:23]
	v_mfma_f32_16x16x32_bf16 v[16:19], v[202:205], v[222:225], v[16:19]
	v_mfma_f32_16x16x32_bf16 v[8:11], v[206:209], v[210:213], v[8:11]
	v_mfma_f32_16x16x32_bf16 v[0:3], v[206:209], v[214:217], v[0:3]
	v_mfma_f32_16x16x32_bf16 v[12:15], v[206:209], v[218:221], v[12:15]
	v_mfma_f32_16x16x32_bf16 v[4:7], v[206:209], v[222:225], v[4:7]
	ds_read_b128 v[194:197], v248 offset:8192
	ds_read_b128 v[198:201], v248 offset:10240
	ds_read_b128 v[202:205], v248 offset:12288
	ds_read_b128 v[206:209], v248 offset:14336
	s_waitcnt lgkmcnt(4)
	v_mfma_f32_16x16x32_bf16 v[124:127], v[176:179], v[226:229], v[124:127]
	v_mfma_f32_16x16x32_bf16 v[120:123], v[176:179], v[230:233], v[120:123]
	v_mfma_f32_16x16x32_bf16 v[116:119], v[176:179], v[234:237], v[116:119]
	v_mfma_f32_16x16x32_bf16 v[112:115], v[176:179], v[238:241], v[112:115]
	v_mfma_f32_16x16x32_bf16 v[108:111], v[182:185], v[226:229], v[108:111]
	v_mfma_f32_16x16x32_bf16 v[104:107], v[182:185], v[230:233], v[104:107]
	v_mfma_f32_16x16x32_bf16 v[100:103], v[182:185], v[234:237], v[100:103]
	v_mfma_f32_16x16x32_bf16 v[96:99], v[182:185], v[238:241], v[96:99]
	v_mfma_f32_16x16x32_bf16 v[92:95], v[186:189], v[226:229], v[92:95]
	v_mfma_f32_16x16x32_bf16 v[88:91], v[186:189], v[230:233], v[88:91]
	v_mfma_f32_16x16x32_bf16 v[84:87], v[186:189], v[234:237], v[84:87]
	v_mfma_f32_16x16x32_bf16 v[80:83], v[186:189], v[238:241], v[80:83]
	v_mfma_f32_16x16x32_bf16 v[76:79], v[190:193], v[226:229], v[76:79]
	v_mfma_f32_16x16x32_bf16 v[72:75], v[190:193], v[230:233], v[72:75]
	v_mfma_f32_16x16x32_bf16 v[68:71], v[190:193], v[234:237], v[68:71]
	v_mfma_f32_16x16x32_bf16 v[64:67], v[190:193], v[238:241], v[64:67]
	s_add_u32 s68, s68, 0x80
	s_addc_u32 s69, s69, 0
	s_add_i32 s86, s86, 1
	s_waitcnt lgkmcnt(0)
	s_waitcnt vmcnt(0)
	s_barrier
	v_mfma_f32_16x16x32_bf16 v[60:63], v[194:197], v[226:229], v[60:63]
	v_mfma_f32_16x16x32_bf16 v[56:59], v[194:197], v[230:233], v[56:59]
	v_mfma_f32_16x16x32_bf16 v[52:55], v[194:197], v[234:237], v[52:55]
	v_mfma_f32_16x16x32_bf16 v[48:51], v[194:197], v[238:241], v[48:51]
	v_mfma_f32_16x16x32_bf16 v[44:47], v[198:201], v[226:229], v[44:47]
	v_mfma_f32_16x16x32_bf16 v[40:43], v[198:201], v[230:233], v[40:43]
	v_mfma_f32_16x16x32_bf16 v[36:39], v[198:201], v[234:237], v[36:39]
	v_mfma_f32_16x16x32_bf16 v[32:35], v[198:201], v[238:241], v[32:35]
	v_mfma_f32_16x16x32_bf16 v[28:31], v[202:205], v[226:229], v[28:31]
	v_mfma_f32_16x16x32_bf16 v[24:27], v[202:205], v[230:233], v[24:27]
	v_mfma_f32_16x16x32_bf16 v[20:23], v[202:205], v[234:237], v[20:23]
	v_mfma_f32_16x16x32_bf16 v[16:19], v[202:205], v[238:241], v[16:19]
	v_mfma_f32_16x16x32_bf16 v[8:11], v[206:209], v[226:229], v[8:11]
	v_mfma_f32_16x16x32_bf16 v[0:3], v[206:209], v[230:233], v[0:3]
	v_mfma_f32_16x16x32_bf16 v[12:15], v[206:209], v[234:237], v[12:15]
	v_mfma_f32_16x16x32_bf16 v[4:7], v[206:209], v[238:241], v[4:7]
	s_nop 7
	s_nop 7
	s_sub_u32 s68, s68, s34
	s_subb_u32 s69, s69, s35
	s_mov_b32 s87, 0x80000
	s_mov_b32 s87, 0x80000
	s_mov_b64 s[70:71], 0
	s_mov_b64 vcc, exec
	s_branch .LBB0_666

.Lg6_top:
	s_waitcnt lgkmcnt(0)
	v_mfma_f32_16x16x32_bf16 v[60:63], v[198:201], v[230:233], v[60:63]
	v_mfma_f32_16x16x32_bf16 v[56:59], v[198:201], v[234:237], v[56:59]
	v_mfma_f32_16x16x32_bf16 v[52:55], v[198:201], v[238:241], v[52:55]
	v_mfma_f32_16x16x32_bf16 v[48:51], v[198:201], v[242:245], v[48:51]
	s_waitcnt vmcnt(0)
	s_barrier
	v_xor_b32_e32 v180, 0x10000, v180
	v_xor_b32_e32 v249, 0x10000, v249
	v_xor_b32_e32 v248, 0x10000, v248
	v_xor_b32_e32 v250, 0x10000, v250
	s_xor_b32 s69, s69, 0x10000
	s_mov_b32 m0, s69
	s_add_u32 s66, s64, s44
	s_addc_u32 s67, s65, s45
	global_load_lds_dwordx4 v246, s[66:67]
	ds_read_b128 v[182:185], v180
	ds_read_b128 v[186:189], v180 offset:2048
	ds_read_b128 v[190:193], v180 offset:4096
	ds_read_b128 v[194:197], v180 offset:6144
	ds_read_b128 v[214:217], v249 offset:32768
	ds_read_b128 v[218:221], v249 offset:34816
	ds_read_b128 v[222:225], v249 offset:36864
	ds_read_b128 v[226:229], v249 offset:38912
	v_mfma_f32_16x16x32_bf16 v[44:47], v[202:205], v[230:233], v[44:47]
	v_mfma_f32_16x16x32_bf16 v[40:43], v[202:205], v[234:237], v[40:43]
	s_add_u32 m0, s69, 0x2000
	s_add_u32 s66, s64, s46
	s_addc_u32 s67, s65, s47
	global_load_lds_dwordx4 v246, s[66:67]
	v_mfma_f32_16x16x32_bf16 v[36:39], v[202:205], v[238:241], v[36:39]
	v_mfma_f32_16x16x32_bf16 v[32:35], v[202:205], v[242:245], v[32:35]
	s_add_u32 m0, s69, 0x4000
	s_add_u32 s66, s64, s48
	s_addc_u32 s67, s65, s49
	global_load_lds_dwordx4 v246, s[66:67]
	v_mfma_f32_16x16x32_bf16 v[28:31], v[206:209], v[230:233], v[28:31]
	v_mfma_f32_16x16x32_bf16 v[24:27], v[206:209], v[234:237], v[24:27]
	s_add_u32 m0, s69, 0x6000
	s_add_u32 s66, s64, s50
	s_addc_u32 s67, s65, s51
	global_load_lds_dwordx4 v246, s[66:67]
	v_mfma_f32_16x16x32_bf16 v[20:23], v[206:209], v[238:241], v[20:23]
	v_mfma_f32_16x16x32_bf16 v[16:19], v[206:209], v[242:245], v[16:19]
	s_add_u32 m0, s69, 0x8000
	s_add_u32 s66, s64, s52
	s_addc_u32 s67, s65, s53
	global_load_lds_dwordx4 v247, s[66:67]
	v_mfma_f32_16x16x32_bf16 v[12:15], v[210:213], v[230:233], v[12:15]
	v_mfma_f32_16x16x32_bf16 v[0:3], v[210:213], v[234:237], v[0:3]
	s_add_u32 m0, s69, 0xa000
	s_add_u32 s66, s64, s54
	s_addc_u32 s67, s65, s55
	global_load_lds_dwordx4 v247, s[66:67]
	v_mfma_f32_16x16x32_bf16 v[8:11], v[210:213], v[238:241], v[8:11]
	v_mfma_f32_16x16x32_bf16 v[4:7], v[210:213], v[242:245], v[4:7]
	s_add_u32 m0, s69, 0xc000
	s_add_u32 s66, s64, s60
	s_addc_u32 s67, s65, s61
	global_load_lds_dwordx4 v247, s[66:67]
.Lg6_entry:
	ds_read_b128 v[198:201], v180 offset:8192
	ds_read_b128 v[202:205], v180 offset:10240
	ds_read_b128 v[206:209], v180 offset:12288
	ds_read_b128 v[210:213], v180 offset:14336
	s_waitcnt lgkmcnt(4)
	v_mfma_f32_16x16x32_bf16 v[124:127], v[182:185], v[214:217], v[124:127]
	v_mfma_f32_16x16x32_bf16 v[120:123], v[182:185], v[218:221], v[120:123]
	s_add_u32 m0, s69, 0xe000
	s_add_u32 s66, s64, s62
	s_addc_u32 s67, s65, s63
	global_load_lds_dwordx4 v247, s[66:67]
	v_mfma_f32_16x16x32_bf16 v[116:119], v[182:185], v[222:225], v[116:119]
	v_mfma_f32_16x16x32_bf16 v[112:115], v[182:185], v[226:229], v[112:115]
	v_mfma_f32_16x16x32_bf16 v[108:111], v[186:189], v[214:217], v[108:111]
	v_mfma_f32_16x16x32_bf16 v[104:107], v[186:189], v[218:221], v[104:107]
	v_mfma_f32_16x16x32_bf16 v[100:103], v[186:189], v[222:225], v[100:103]
	v_mfma_f32_16x16x32_bf16 v[96:99], v[186:189], v[226:229], v[96:99]
	v_mfma_f32_16x16x32_bf16 v[92:95], v[190:193], v[214:217], v[92:95]
	v_mfma_f32_16x16x32_bf16 v[88:91], v[190:193], v[218:221], v[88:91]
	v_mfma_f32_16x16x32_bf16 v[84:87], v[190:193], v[222:225], v[84:87]
	v_mfma_f32_16x16x32_bf16 v[80:83], v[190:193], v[226:229], v[80:83]
	v_mfma_f32_16x16x32_bf16 v[76:79], v[194:197], v[214:217], v[76:79]
	v_mfma_f32_16x16x32_bf16 v[72:75], v[194:197], v[218:221], v[72:75]
	v_mfma_f32_16x16x32_bf16 v[68:71], v[194:197], v[222:225], v[68:71]
	v_mfma_f32_16x16x32_bf16 v[64:67], v[194:197], v[226:229], v[64:67]
	ds_read_b128 v[182:185], v248
	ds_read_b128 v[186:189], v248 offset:2048
	ds_read_b128 v[190:193], v248 offset:4096
	ds_read_b128 v[194:197], v248 offset:6144
	ds_read_b128 v[230:233], v250 offset:32768
	ds_read_b128 v[234:237], v250 offset:34816
	ds_read_b128 v[238:241], v250 offset:36864
	ds_read_b128 v[242:245], v250 offset:38912
	s_waitcnt lgkmcnt(8)
	v_mfma_f32_16x16x32_bf16 v[60:63], v[198:201], v[214:217], v[60:63]
	v_mfma_f32_16x16x32_bf16 v[56:59], v[198:201], v[218:221], v[56:59]
	v_mfma_f32_16x16x32_bf16 v[52:55], v[198:201], v[222:225], v[52:55]
	v_mfma_f32_16x16x32_bf16 v[48:51], v[198:201], v[226:229], v[48:51]
	v_mfma_f32_16x16x32_bf16 v[44:47], v[202:205], v[214:217], v[44:47]
	v_mfma_f32_16x16x32_bf16 v[40:43], v[202:205], v[218:221], v[40:43]
	v_mfma_f32_16x16x32_bf16 v[36:39], v[202:205], v[222:225], v[36:39]
	v_mfma_f32_16x16x32_bf16 v[32:35], v[202:205], v[226:229], v[32:35]
	v_mfma_f32_16x16x32_bf16 v[28:31], v[206:209], v[214:217], v[28:31]
	v_mfma_f32_16x16x32_bf16 v[24:27], v[206:209], v[218:221], v[24:27]
	v_mfma_f32_16x16x32_bf16 v[20:23], v[206:209], v[222:225], v[20:23]
	v_mfma_f32_16x16x32_bf16 v[16:19], v[206:209], v[226:229], v[16:19]
	v_mfma_f32_16x16x32_bf16 v[12:15], v[210:213], v[214:217], v[12:15]
	v_mfma_f32_16x16x32_bf16 v[0:3], v[210:213], v[218:221], v[0:3]
	v_mfma_f32_16x16x32_bf16 v[8:11], v[210:213], v[222:225], v[8:11]
	v_mfma_f32_16x16x32_bf16 v[4:7], v[210:213], v[226:229], v[4:7]
	ds_read_b128 v[198:201], v248 offset:8192
	ds_read_b128 v[202:205], v248 offset:10240
	ds_read_b128 v[206:209], v248 offset:12288
	ds_read_b128 v[210:213], v248 offset:14336
	s_waitcnt lgkmcnt(4)
	v_mfma_f32_16x16x32_bf16 v[124:127], v[182:185], v[230:233], v[124:127]
	v_mfma_f32_16x16x32_bf16 v[120:123], v[182:185], v[234:237], v[120:123]
	v_mfma_f32_16x16x32_bf16 v[116:119], v[182:185], v[238:241], v[116:119]
	v_mfma_f32_16x16x32_bf16 v[112:115], v[182:185], v[242:245], v[112:115]
	v_mfma_f32_16x16x32_bf16 v[108:111], v[186:189], v[230:233], v[108:111]
	v_mfma_f32_16x16x32_bf16 v[104:107], v[186:189], v[234:237], v[104:107]
	v_mfma_f32_16x16x32_bf16 v[100:103], v[186:189], v[238:241], v[100:103]
	v_mfma_f32_16x16x32_bf16 v[96:99], v[186:189], v[242:245], v[96:99]
	v_mfma_f32_16x16x32_bf16 v[92:95], v[190:193], v[230:233], v[92:95]
	v_mfma_f32_16x16x32_bf16 v[88:91], v[190:193], v[234:237], v[88:91]
	v_mfma_f32_16x16x32_bf16 v[84:87], v[190:193], v[238:241], v[84:87]
	v_mfma_f32_16x16x32_bf16 v[80:83], v[190:193], v[242:245], v[80:83]
	v_mfma_f32_16x16x32_bf16 v[76:79], v[194:197], v[230:233], v[76:79]
	v_mfma_f32_16x16x32_bf16 v[72:75], v[194:197], v[234:237], v[72:75]
	v_mfma_f32_16x16x32_bf16 v[68:71], v[194:197], v[238:241], v[68:71]
	v_mfma_f32_16x16x32_bf16 v[64:67], v[194:197], v[242:245], v[64:67]
	s_add_u32 s64, s64, 0x80
	s_addc_u32 s65, s65, 0
	s_add_i32 s68, s68, 1
	s_cmp_lt_u32 s68, 31
	s_cbranch_scc1 .Lg6_top
	s_waitcnt lgkmcnt(0)
	v_mfma_f32_16x16x32_bf16 v[60:63], v[198:201], v[230:233], v[60:63]
	v_mfma_f32_16x16x32_bf16 v[56:59], v[198:201], v[234:237], v[56:59]
	v_mfma_f32_16x16x32_bf16 v[52:55], v[198:201], v[238:241], v[52:55]
	v_mfma_f32_16x16x32_bf16 v[48:51], v[198:201], v[242:245], v[48:51]
	s_waitcnt vmcnt(0)
	s_barrier
	v_xor_b32_e32 v180, 0x10000, v180
	v_xor_b32_e32 v249, 0x10000, v249
	v_xor_b32_e32 v248, 0x10000, v248
	v_xor_b32_e32 v250, 0x10000, v250
	s_xor_b32 s69, s69, 0x10000
	ds_read_b128 v[182:185], v180
	ds_read_b128 v[186:189], v180 offset:2048
	ds_read_b128 v[190:193], v180 offset:4096
	ds_read_b128 v[194:197], v180 offset:6144
	ds_read_b128 v[214:217], v249 offset:32768
	ds_read_b128 v[218:221], v249 offset:34816
	ds_read_b128 v[222:225], v249 offset:36864
	ds_read_b128 v[226:229], v249 offset:38912
	v_mfma_f32_16x16x32_bf16 v[44:47], v[202:205], v[230:233], v[44:47]
	v_mfma_f32_16x16x32_bf16 v[40:43], v[202:205], v[234:237], v[40:43]
	v_mfma_f32_16x16x32_bf16 v[36:39], v[202:205], v[238:241], v[36:39]
	v_mfma_f32_16x16x32_bf16 v[32:35], v[202:205], v[242:245], v[32:35]
	v_mfma_f32_16x16x32_bf16 v[28:31], v[206:209], v[230:233], v[28:31]
	v_mfma_f32_16x16x32_bf16 v[24:27], v[206:209], v[234:237], v[24:27]
	v_mfma_f32_16x16x32_bf16 v[20:23], v[206:209], v[238:241], v[20:23]
	v_mfma_f32_16x16x32_bf16 v[16:19], v[206:209], v[242:245], v[16:19]
	v_mfma_f32_16x16x32_bf16 v[12:15], v[210:213], v[230:233], v[12:15]
	v_mfma_f32_16x16x32_bf16 v[0:3], v[210:213], v[234:237], v[0:3]
	v_mfma_f32_16x16x32_bf16 v[8:11], v[210:213], v[238:241], v[8:11]
	v_mfma_f32_16x16x32_bf16 v[4:7], v[210:213], v[242:245], v[4:7]
	ds_read_b128 v[198:201], v180 offset:8192
	ds_read_b128 v[202:205], v180 offset:10240
	ds_read_b128 v[206:209], v180 offset:12288
	ds_read_b128 v[210:213], v180 offset:14336
	s_waitcnt lgkmcnt(4)
	v_mfma_f32_16x16x32_bf16 v[124:127], v[182:185], v[214:217], v[124:127]
	v_mfma_f32_16x16x32_bf16 v[120:123], v[182:185], v[218:221], v[120:123]
	v_mfma_f32_16x16x32_bf16 v[116:119], v[182:185], v[222:225], v[116:119]
	v_mfma_f32_16x16x32_bf16 v[112:115], v[182:185], v[226:229], v[112:115]
	v_mfma_f32_16x16x32_bf16 v[108:111], v[186:189], v[214:217], v[108:111]
	v_mfma_f32_16x16x32_bf16 v[104:107], v[186:189], v[218:221], v[104:107]
	v_mfma_f32_16x16x32_bf16 v[100:103], v[186:189], v[222:225], v[100:103]
	v_mfma_f32_16x16x32_bf16 v[96:99], v[186:189], v[226:229], v[96:99]
	v_mfma_f32_16x16x32_bf16 v[92:95], v[190:193], v[214:217], v[92:95]
	v_mfma_f32_16x16x32_bf16 v[88:91], v[190:193], v[218:221], v[88:91]
	v_mfma_f32_16x16x32_bf16 v[84:87], v[190:193], v[222:225], v[84:87]
	v_mfma_f32_16x16x32_bf16 v[80:83], v[190:193], v[226:229], v[80:83]
	v_mfma_f32_16x16x32_bf16 v[76:79], v[194:197], v[214:217], v[76:79]
	v_mfma_f32_16x16x32_bf16 v[72:75], v[194:197], v[218:221], v[72:75]
	v_mfma_f32_16x16x32_bf16 v[68:71], v[194:197], v[222:225], v[68:71]
	v_mfma_f32_16x16x32_bf16 v[64:67], v[194:197], v[226:229], v[64:67]
	ds_read_b128 v[182:185], v248
	ds_read_b128 v[186:189], v248 offset:2048
	ds_read_b128 v[190:193], v248 offset:4096
	ds_read_b128 v[194:197], v248 offset:6144
	ds_read_b128 v[230:233], v250 offset:32768
	ds_read_b128 v[234:237], v250 offset:34816
	ds_read_b128 v[238:241], v250 offset:36864
	ds_read_b128 v[242:245], v250 offset:38912
	s_waitcnt lgkmcnt(8)
	v_mfma_f32_16x16x32_bf16 v[60:63], v[198:201], v[214:217], v[60:63]
	v_mfma_f32_16x16x32_bf16 v[56:59], v[198:201], v[218:221], v[56:59]
	v_mfma_f32_16x16x32_bf16 v[52:55], v[198:201], v[222:225], v[52:55]
	v_mfma_f32_16x16x32_bf16 v[48:51], v[198:201], v[226:229], v[48:51]
	v_mfma_f32_16x16x32_bf16 v[44:47], v[202:205], v[214:217], v[44:47]
	v_mfma_f32_16x16x32_bf16 v[40:43], v[202:205], v[218:221], v[40:43]
	v_mfma_f32_16x16x32_bf16 v[36:39], v[202:205], v[222:225], v[36:39]
	v_mfma_f32_16x16x32_bf16 v[32:35], v[202:205], v[226:229], v[32:35]
	v_mfma_f32_16x16x32_bf16 v[28:31], v[206:209], v[214:217], v[28:31]
	v_mfma_f32_16x16x32_bf16 v[24:27], v[206:209], v[218:221], v[24:27]
	v_mfma_f32_16x16x32_bf16 v[20:23], v[206:209], v[222:225], v[20:23]
	v_mfma_f32_16x16x32_bf16 v[16:19], v[206:209], v[226:229], v[16:19]
	v_mfma_f32_16x16x32_bf16 v[12:15], v[210:213], v[214:217], v[12:15]
	v_mfma_f32_16x16x32_bf16 v[0:3], v[210:213], v[218:221], v[0:3]
	v_mfma_f32_16x16x32_bf16 v[8:11], v[210:213], v[222:225], v[8:11]
	v_mfma_f32_16x16x32_bf16 v[4:7], v[210:213], v[226:229], v[4:7]
	ds_read_b128 v[198:201], v248 offset:8192
	ds_read_b128 v[202:205], v248 offset:10240
	ds_read_b128 v[206:209], v248 offset:12288
	ds_read_b128 v[210:213], v248 offset:14336
	s_waitcnt lgkmcnt(4)
	v_mfma_f32_16x16x32_bf16 v[124:127], v[182:185], v[230:233], v[124:127]
	v_mfma_f32_16x16x32_bf16 v[120:123], v[182:185], v[234:237], v[120:123]
	v_mfma_f32_16x16x32_bf16 v[116:119], v[182:185], v[238:241], v[116:119]
	v_mfma_f32_16x16x32_bf16 v[112:115], v[182:185], v[242:245], v[112:115]
	v_mfma_f32_16x16x32_bf16 v[108:111], v[186:189], v[230:233], v[108:111]
	v_mfma_f32_16x16x32_bf16 v[104:107], v[186:189], v[234:237], v[104:107]
	v_mfma_f32_16x16x32_bf16 v[100:103], v[186:189], v[238:241], v[100:103]
	v_mfma_f32_16x16x32_bf16 v[96:99], v[186:189], v[242:245], v[96:99]
	v_mfma_f32_16x16x32_bf16 v[92:95], v[190:193], v[230:233], v[92:95]
	v_mfma_f32_16x16x32_bf16 v[88:91], v[190:193], v[234:237], v[88:91]
	v_mfma_f32_16x16x32_bf16 v[84:87], v[190:193], v[238:241], v[84:87]
	v_mfma_f32_16x16x32_bf16 v[80:83], v[190:193], v[242:245], v[80:83]
	v_mfma_f32_16x16x32_bf16 v[76:79], v[194:197], v[230:233], v[76:79]
	v_mfma_f32_16x16x32_bf16 v[72:75], v[194:197], v[234:237], v[72:75]
	v_mfma_f32_16x16x32_bf16 v[68:71], v[194:197], v[238:241], v[68:71]
	v_mfma_f32_16x16x32_bf16 v[64:67], v[194:197], v[242:245], v[64:67]
	s_add_u32 s64, s64, 0x80
	s_addc_u32 s65, s65, 0
	s_add_i32 s68, s68, 1
	s_waitcnt lgkmcnt(0)
	s_waitcnt vmcnt(0)
	s_barrier
	v_mfma_f32_16x16x32_bf16 v[60:63], v[198:201], v[230:233], v[60:63]
	v_mfma_f32_16x16x32_bf16 v[56:59], v[198:201], v[234:237], v[56:59]
	v_mfma_f32_16x16x32_bf16 v[52:55], v[198:201], v[238:241], v[52:55]
	v_mfma_f32_16x16x32_bf16 v[48:51], v[198:201], v[242:245], v[48:51]
	v_mfma_f32_16x16x32_bf16 v[44:47], v[202:205], v[230:233], v[44:47]
	v_mfma_f32_16x16x32_bf16 v[40:43], v[202:205], v[234:237], v[40:43]
	v_mfma_f32_16x16x32_bf16 v[36:39], v[202:205], v[238:241], v[36:39]
	v_mfma_f32_16x16x32_bf16 v[32:35], v[202:205], v[242:245], v[32:35]
	v_mfma_f32_16x16x32_bf16 v[28:31], v[206:209], v[230:233], v[28:31]
	v_mfma_f32_16x16x32_bf16 v[24:27], v[206:209], v[234:237], v[24:27]
	v_mfma_f32_16x16x32_bf16 v[20:23], v[206:209], v[238:241], v[20:23]
	v_mfma_f32_16x16x32_bf16 v[16:19], v[206:209], v[242:245], v[16:19]
	v_mfma_f32_16x16x32_bf16 v[12:15], v[210:213], v[230:233], v[12:15]
	v_mfma_f32_16x16x32_bf16 v[0:3], v[210:213], v[234:237], v[0:3]
	v_mfma_f32_16x16x32_bf16 v[8:11], v[210:213], v[238:241], v[8:11]
	v_mfma_f32_16x16x32_bf16 v[4:7], v[210:213], v[242:245], v[4:7]
	s_nop 7
	s_nop 7
	s_sub_u32 s64, s64, s34
	s_subb_u32 s65, s65, s35
	s_mov_b32 s69, 0x100000
	s_mov_b32 s70, 0x100000
	s_mov_b64 s[66:67], 0
	s_mov_b64 vcc, exec
	s_branch .LBB0_674

.Lg7_top:
	s_waitcnt lgkmcnt(0)
	v_mfma_f32_16x16x32_bf16 v[60:63], v[158:161], v[194:197], v[60:63]
	v_mfma_f32_16x16x32_bf16 v[56:59], v[158:161], v[198:201], v[56:59]
	v_mfma_f32_16x16x32_bf16 v[52:55], v[158:161], v[202:205], v[52:55]
	v_mfma_f32_16x16x32_bf16 v[48:51], v[158:161], v[206:209], v[48:51]
	s_waitcnt vmcnt(0)
	s_barrier
	s_xor_b32 s61, s61, 0x10000
	s_mov_b32 m0, s61
	s_add_u32 s50, s48, s14
	s_addc_u32 s51, s49, s15
	global_load_lds_dwordx4 v178, s[50:51]
	ds_read_b128 v[142:145], v141
	ds_read_b128 v[146:149], v141 offset:2048
	ds_read_b128 v[150:153], v141 offset:4096
	ds_read_b128 v[154:157], v141 offset:6144
	ds_read_b128 v[174:177], v210 offset:32768
	ds_read_b128 v[182:185], v210 offset:34816
	ds_read_b128 v[186:189], v210 offset:36864
	ds_read_b128 v[190:193], v210 offset:38912
	v_mfma_f32_16x16x32_bf16 v[44:47], v[162:165], v[194:197], v[44:47]
	v_mfma_f32_16x16x32_bf16 v[32:35], v[162:165], v[198:201], v[32:35]
	s_add_u32 m0, s61, 0x2000
	s_add_u32 s50, s48, s16
	s_addc_u32 s51, s49, s17
	global_load_lds_dwordx4 v178, s[50:51]
	v_mfma_f32_16x16x32_bf16 v[28:31], v[162:165], v[202:205], v[28:31]
	v_mfma_f32_16x16x32_bf16 v[24:27], v[162:165], v[206:209], v[24:27]
	s_add_u32 m0, s61, 0x4000
	s_add_u32 s50, s48, s18
	s_addc_u32 s51, s49, s19
	global_load_lds_dwordx4 v178, s[50:51]
	v_mfma_f32_16x16x32_bf16 v[20:23], v[166:169], v[194:197], v[20:23]
	v_mfma_f32_16x16x32_bf16 v[16:19], v[166:169], v[198:201], v[16:19]
	s_add_u32 m0, s61, 0x6000
	s_add_u32 s50, s48, s22
	s_addc_u32 s51, s49, s23
	global_load_lds_dwordx4 v178, s[50:51]
	v_mfma_f32_16x16x32_bf16 v[12:15], v[166:169], v[202:205], v[12:15]
	v_mfma_f32_16x16x32_bf16 v[8:11], v[166:169], v[206:209], v[8:11]
	s_add_u32 m0, s61, 0x8000
	s_add_u32 s50, s48, s36
	s_addc_u32 s51, s49, s37
	global_load_lds_dwordx4 v179, s[50:51]
	v_mfma_f32_16x16x32_bf16 v[4:7], v[170:173], v[194:197], v[4:7]
	v_mfma_f32_16x16x32_bf16 v[0:3], v[170:173], v[198:201], v[0:3]
	s_add_u32 m0, s61, 0xa000
	s_add_u32 s50, s48, s40
	s_addc_u32 s51, s49, s41
	global_load_lds_dwordx4 v179, s[50:51]
	v_mfma_f32_16x16x32_bf16 v[40:43], v[170:173], v[202:205], v[40:43]
	v_mfma_f32_16x16x32_bf16 v[36:39], v[170:173], v[206:209], v[36:39]
	s_add_u32 m0, s61, 0xc000
	s_add_u32 s50, s48, s42
	s_addc_u32 s51, s49, s43
	global_load_lds_dwordx4 v179, s[50:51]
.Lg7_entry:
	ds_read_b128 v[158:161], v141 offset:8192
	ds_read_b128 v[162:165], v141 offset:10240
	ds_read_b128 v[166:169], v141 offset:12288
	ds_read_b128 v[170:173], v141 offset:14336
	s_waitcnt lgkmcnt(4)
	v_mfma_f32_16x16x32_bf16 v[124:127], v[142:145], v[174:177], v[124:127]
	v_mfma_f32_16x16x32_bf16 v[120:123], v[142:145], v[182:185], v[120:123]
	s_add_u32 m0, s61, 0xe000
	s_add_u32 s50, s48, s44
	s_addc_u32 s51, s49, s45
	global_load_lds_dwordx4 v179, s[50:51]
	v_mfma_f32_16x16x32_bf16 v[116:119], v[142:145], v[186:189], v[116:119]
	v_mfma_f32_16x16x32_bf16 v[112:115], v[142:145], v[190:193], v[112:115]
	v_mfma_f32_16x16x32_bf16 v[108:111], v[146:149], v[174:177], v[108:111]
	v_mfma_f32_16x16x32_bf16 v[104:107], v[146:149], v[182:185], v[104:107]
	v_mfma_f32_16x16x32_bf16 v[100:103], v[146:149], v[186:189], v[100:103]
	v_mfma_f32_16x16x32_bf16 v[96:99], v[146:149], v[190:193], v[96:99]
	v_mfma_f32_16x16x32_bf16 v[92:95], v[150:153], v[174:177], v[92:95]
	v_mfma_f32_16x16x32_bf16 v[88:91], v[150:153], v[182:185], v[88:91]
	v_mfma_f32_16x16x32_bf16 v[84:87], v[150:153], v[186:189], v[84:87]
	v_mfma_f32_16x16x32_bf16 v[80:83], v[150:153], v[190:193], v[80:83]
	v_mfma_f32_16x16x32_bf16 v[76:79], v[154:157], v[174:177], v[76:79]
	v_mfma_f32_16x16x32_bf16 v[72:75], v[154:157], v[182:185], v[72:75]
	v_mfma_f32_16x16x32_bf16 v[68:71], v[154:157], v[186:189], v[68:71]
	v_mfma_f32_16x16x32_bf16 v[64:67], v[154:157], v[190:193], v[64:67]
	ds_read_b128 v[142:145], v180
	ds_read_b128 v[146:149], v180 offset:2048
	ds_read_b128 v[150:153], v180 offset:4096
	ds_read_b128 v[154:157], v180 offset:6144
	ds_read_b128 v[194:197], v211 offset:32768
	ds_read_b128 v[198:201], v211 offset:34816
	ds_read_b128 v[202:205], v211 offset:36864
	ds_read_b128 v[206:209], v211 offset:38912
	s_waitcnt lgkmcnt(8)
	v_mfma_f32_16x16x32_bf16 v[60:63], v[158:161], v[174:177], v[60:63]
	v_mfma_f32_16x16x32_bf16 v[56:59], v[158:161], v[182:185], v[56:59]
	v_mfma_f32_16x16x32_bf16 v[52:55], v[158:161], v[186:189], v[52:55]
	v_mfma_f32_16x16x32_bf16 v[48:51], v[158:161], v[190:193], v[48:51]
	v_mfma_f32_16x16x32_bf16 v[44:47], v[162:165], v[174:177], v[44:47]
	v_mfma_f32_16x16x32_bf16 v[32:35], v[162:165], v[182:185], v[32:35]
	v_mfma_f32_16x16x32_bf16 v[28:31], v[162:165], v[186:189], v[28:31]
	v_mfma_f32_16x16x32_bf16 v[24:27], v[162:165], v[190:193], v[24:27]
	v_mfma_f32_16x16x32_bf16 v[20:23], v[166:169], v[174:177], v[20:23]
	v_mfma_f32_16x16x32_bf16 v[16:19], v[166:169], v[182:185], v[16:19]
	v_mfma_f32_16x16x32_bf16 v[12:15], v[166:169], v[186:189], v[12:15]
	v_mfma_f32_16x16x32_bf16 v[8:11], v[166:169], v[190:193], v[8:11]
	v_mfma_f32_16x16x32_bf16 v[4:7], v[170:173], v[174:177], v[4:7]
	v_mfma_f32_16x16x32_bf16 v[0:3], v[170:173], v[182:185], v[0:3]
	v_mfma_f32_16x16x32_bf16 v[40:43], v[170:173], v[186:189], v[40:43]
	v_mfma_f32_16x16x32_bf16 v[36:39], v[170:173], v[190:193], v[36:39]
	ds_read_b128 v[158:161], v180 offset:8192
	ds_read_b128 v[162:165], v180 offset:10240
	ds_read_b128 v[166:169], v180 offset:12288
	ds_read_b128 v[170:173], v180 offset:14336
	s_waitcnt lgkmcnt(4)
	v_mfma_f32_16x16x32_bf16 v[124:127], v[142:145], v[194:197], v[124:127]
	v_mfma_f32_16x16x32_bf16 v[120:123], v[142:145], v[198:201], v[120:123]
	v_mfma_f32_16x16x32_bf16 v[116:119], v[142:145], v[202:205], v[116:119]
	v_mfma_f32_16x16x32_bf16 v[112:115], v[142:145], v[206:209], v[112:115]
	v_mfma_f32_16x16x32_bf16 v[108:111], v[146:149], v[194:197], v[108:111]
	v_mfma_f32_16x16x32_bf16 v[104:107], v[146:149], v[198:201], v[104:107]
	v_mfma_f32_16x16x32_bf16 v[100:103], v[146:149], v[202:205], v[100:103]
	v_mfma_f32_16x16x32_bf16 v[96:99], v[146:149], v[206:209], v[96:99]
	v_mfma_f32_16x16x32_bf16 v[92:95], v[150:153], v[194:197], v[92:95]
	v_mfma_f32_16x16x32_bf16 v[88:91], v[150:153], v[198:201], v[88:91]
	v_mfma_f32_16x16x32_bf16 v[84:87], v[150:153], v[202:205], v[84:87]
	v_mfma_f32_16x16x32_bf16 v[80:83], v[150:153], v[206:209], v[80:83]
	v_mfma_f32_16x16x32_bf16 v[76:79], v[154:157], v[194:197], v[76:79]
	v_mfma_f32_16x16x32_bf16 v[72:75], v[154:157], v[198:201], v[72:75]
	v_mfma_f32_16x16x32_bf16 v[68:71], v[154:157], v[202:205], v[68:71]
	v_mfma_f32_16x16x32_bf16 v[64:67], v[154:157], v[206:209], v[64:67]
	s_add_u32 s48, s48, 0x80
	s_addc_u32 s49, s49, 0
	s_add_i32 s47, s47, 1
	s_cmp_lt_u32 s47, 31
	s_cbranch_scc0 .Lg7_last
	s_waitcnt lgkmcnt(0)
	v_mfma_f32_16x16x32_bf16 v[60:63], v[158:161], v[194:197], v[60:63]
	v_mfma_f32_16x16x32_bf16 v[56:59], v[158:161], v[198:201], v[56:59]
	v_mfma_f32_16x16x32_bf16 v[52:55], v[158:161], v[202:205], v[52:55]
	v_mfma_f32_16x16x32_bf16 v[48:51], v[158:161], v[206:209], v[48:51]
	s_waitcnt vmcnt(0)
	s_barrier
	s_xor_b32 s61, s61, 0x10000
	s_mov_b32 m0, s61
	s_add_u32 s50, s48, s14
	s_addc_u32 s51, s49, s15
	global_load_lds_dwordx4 v178, s[50:51]
	ds_read_b128 v[142:145], v212
	ds_read_b128 v[146:149], v212 offset:2048
	ds_read_b128 v[150:153], v212 offset:4096
	ds_read_b128 v[154:157], v212 offset:6144
	ds_read_b128 v[174:177], v214 offset:32768
	ds_read_b128 v[182:185], v214 offset:34816
	ds_read_b128 v[186:189], v214 offset:36864
	ds_read_b128 v[190:193], v214 offset:38912
	v_mfma_f32_16x16x32_bf16 v[44:47], v[162:165], v[194:197], v[44:47]
	v_mfma_f32_16x16x32_bf16 v[32:35], v[162:165], v[198:201], v[32:35]
	s_add_u32 m0, s61, 0x2000
	s_add_u32 s50, s48, s16
	s_addc_u32 s51, s49, s17
	global_load_lds_dwordx4 v178, s[50:51]
	v_mfma_f32_16x16x32_bf16 v[28:31], v[162:165], v[202:205], v[28:31]
	v_mfma_f32_16x16x32_bf16 v[24:27], v[162:165], v[206:209], v[24:27]
	s_add_u32 m0, s61, 0x4000
	s_add_u32 s50, s48, s18
	s_addc_u32 s51, s49, s19
	global_load_lds_dwordx4 v178, s[50:51]
	v_mfma_f32_16x16x32_bf16 v[20:23], v[166:169], v[194:197], v[20:23]
	v_mfma_f32_16x16x32_bf16 v[16:19], v[166:169], v[198:201], v[16:19]
	s_add_u32 m0, s61, 0x6000
	s_add_u32 s50, s48, s22
	s_addc_u32 s51, s49, s23
	global_load_lds_dwordx4 v178, s[50:51]
	v_mfma_f32_16x16x32_bf16 v[12:15], v[166:169], v[202:205], v[12:15]
	v_mfma_f32_16x16x32_bf16 v[8:11], v[166:169], v[206:209], v[8:11]
	s_add_u32 m0, s61, 0x8000
	s_add_u32 s50, s48, s36
	s_addc_u32 s51, s49, s37
	global_load_lds_dwordx4 v179, s[50:51]
	v_mfma_f32_16x16x32_bf16 v[4:7], v[170:173], v[194:197], v[4:7]
	v_mfma_f32_16x16x32_bf16 v[0:3], v[170:173], v[198:201], v[0:3]
	s_add_u32 m0, s61, 0xa000
	s_add_u32 s50, s48, s40
	s_addc_u32 s51, s49, s41
	global_load_lds_dwordx4 v179, s[50:51]
	v_mfma_f32_16x16x32_bf16 v[40:43], v[170:173], v[202:205], v[40:43]
	v_mfma_f32_16x16x32_bf16 v[36:39], v[170:173], v[206:209], v[36:39]
	s_add_u32 m0, s61, 0xc000
	s_add_u32 s50, s48, s42
	s_addc_u32 s51, s49, s43
	global_load_lds_dwordx4 v179, s[50:51]
	ds_read_b128 v[158:161], v212 offset:8192
	ds_read_b128 v[162:165], v212 offset:10240
	ds_read_b128 v[166:169], v212 offset:12288
	ds_read_b128 v[170:173], v212 offset:14336
	s_waitcnt lgkmcnt(4)
	v_mfma_f32_16x16x32_bf16 v[124:127], v[142:145], v[174:177], v[124:127]
	v_mfma_f32_16x16x32_bf16 v[120:123], v[142:145], v[182:185], v[120:123]
	s_add_u32 m0, s61, 0xe000
	s_add_u32 s50, s48, s44
	s_addc_u32 s51, s49, s45
	global_load_lds_dwordx4 v179, s[50:51]
	v_mfma_f32_16x16x32_bf16 v[116:119], v[142:145], v[186:189], v[116:119]
	v_mfma_f32_16x16x32_bf16 v[112:115], v[142:145], v[190:193], v[112:115]
	v_mfma_f32_16x16x32_bf16 v[108:111], v[146:149], v[174:177], v[108:111]
	v_mfma_f32_16x16x32_bf16 v[104:107], v[146:149], v[182:185], v[104:107]
	v_mfma_f32_16x16x32_bf16 v[100:103], v[146:149], v[186:189], v[100:103]
	v_mfma_f32_16x16x32_bf16 v[96:99], v[146:149], v[190:193], v[96:99]
	v_mfma_f32_16x16x32_bf16 v[92:95], v[150:153], v[174:177], v[92:95]
	v_mfma_f32_16x16x32_bf16 v[88:91], v[150:153], v[182:185], v[88:91]
	v_mfma_f32_16x16x32_bf16 v[84:87], v[150:153], v[186:189], v[84:87]
	v_mfma_f32_16x16x32_bf16 v[80:83], v[150:153], v[190:193], v[80:83]
	v_mfma_f32_16x16x32_bf16 v[76:79], v[154:157], v[174:177], v[76:79]
	v_mfma_f32_16x16x32_bf16 v[72:75], v[154:157], v[182:185], v[72:75]
	v_mfma_f32_16x16x32_bf16 v[68:71], v[154:157], v[186:189], v[68:71]
	v_mfma_f32_16x16x32_bf16 v[64:67], v[154:157], v[190:193], v[64:67]
	ds_read_b128 v[142:145], v213
	ds_read_b128 v[146:149], v213 offset:2048
	ds_read_b128 v[150:153], v213 offset:4096
	ds_read_b128 v[154:157], v213 offset:6144
	ds_read_b128 v[194:197], v215 offset:32768
	ds_read_b128 v[198:201], v215 offset:34816
	ds_read_b128 v[202:205], v215 offset:36864
	ds_read_b128 v[206:209], v215 offset:38912
	s_waitcnt lgkmcnt(8)
	v_mfma_f32_16x16x32_bf16 v[60:63], v[158:161], v[174:177], v[60:63]
	v_mfma_f32_16x16x32_bf16 v[56:59], v[158:161], v[182:185], v[56:59]
	v_mfma_f32_16x16x32_bf16 v[52:55], v[158:161], v[186:189], v[52:55]
	v_mfma_f32_16x16x32_bf16 v[48:51], v[158:161], v[190:193], v[48:51]
	v_mfma_f32_16x16x32_bf16 v[44:47], v[162:165], v[174:177], v[44:47]
	v_mfma_f32_16x16x32_bf16 v[32:35], v[162:165], v[182:185], v[32:35]
	v_mfma_f32_16x16x32_bf16 v[28:31], v[162:165], v[186:189], v[28:31]
	v_mfma_f32_16x16x32_bf16 v[24:27], v[162:165], v[190:193], v[24:27]
	v_mfma_f32_16x16x32_bf16 v[20:23], v[166:169], v[174:177], v[20:23]
	v_mfma_f32_16x16x32_bf16 v[16:19], v[166:169], v[182:185], v[16:19]
	v_mfma_f32_16x16x32_bf16 v[12:15], v[166:169], v[186:189], v[12:15]
	v_mfma_f32_16x16x32_bf16 v[8:11], v[166:169], v[190:193], v[8:11]
	v_mfma_f32_16x16x32_bf16 v[4:7], v[170:173], v[174:177], v[4:7]
	v_mfma_f32_16x16x32_bf16 v[0:3], v[170:173], v[182:185], v[0:3]
	v_mfma_f32_16x16x32_bf16 v[40:43], v[170:173], v[186:189], v[40:43]
	v_mfma_f32_16x16x32_bf16 v[36:39], v[170:173], v[190:193], v[36:39]
	ds_read_b128 v[158:161], v213 offset:8192
	ds_read_b128 v[162:165], v213 offset:10240
	ds_read_b128 v[166:169], v213 offset:12288
	ds_read_b128 v[170:173], v213 offset:14336
	s_waitcnt lgkmcnt(4)
	v_mfma_f32_16x16x32_bf16 v[124:127], v[142:145], v[194:197], v[124:127]
	v_mfma_f32_16x16x32_bf16 v[120:123], v[142:145], v[198:201], v[120:123]
	v_mfma_f32_16x16x32_bf16 v[116:119], v[142:145], v[202:205], v[116:119]
	v_mfma_f32_16x16x32_bf16 v[112:115], v[142:145], v[206:209], v[112:115]
	v_mfma_f32_16x16x32_bf16 v[108:111], v[146:149], v[194:197], v[108:111]
	v_mfma_f32_16x16x32_bf16 v[104:107], v[146:149], v[198:201], v[104:107]
	v_mfma_f32_16x16x32_bf16 v[100:103], v[146:149], v[202:205], v[100:103]
	v_mfma_f32_16x16x32_bf16 v[96:99], v[146:149], v[206:209], v[96:99]
	v_mfma_f32_16x16x32_bf16 v[92:95], v[150:153], v[194:197], v[92:95]
	v_mfma_f32_16x16x32_bf16 v[88:91], v[150:153], v[198:201], v[88:91]
	v_mfma_f32_16x16x32_bf16 v[84:87], v[150:153], v[202:205], v[84:87]
	v_mfma_f32_16x16x32_bf16 v[80:83], v[150:153], v[206:209], v[80:83]
	v_mfma_f32_16x16x32_bf16 v[76:79], v[154:157], v[194:197], v[76:79]
	v_mfma_f32_16x16x32_bf16 v[72:75], v[154:157], v[198:201], v[72:75]
	v_mfma_f32_16x16x32_bf16 v[68:71], v[154:157], v[202:205], v[68:71]
	v_mfma_f32_16x16x32_bf16 v[64:67], v[154:157], v[206:209], v[64:67]
	s_add_u32 s48, s48, 0x80
	s_addc_u32 s49, s49, 0
	s_add_i32 s47, s47, 1
	s_branch .Lg7_top
.Lg7_last:
	s_waitcnt lgkmcnt(0)
	v_mfma_f32_16x16x32_bf16 v[60:63], v[158:161], v[194:197], v[60:63]
	v_mfma_f32_16x16x32_bf16 v[56:59], v[158:161], v[198:201], v[56:59]
	v_mfma_f32_16x16x32_bf16 v[52:55], v[158:161], v[202:205], v[52:55]
	v_mfma_f32_16x16x32_bf16 v[48:51], v[158:161], v[206:209], v[48:51]
	s_waitcnt vmcnt(0)
	s_barrier
	s_xor_b32 s61, s61, 0x10000
	ds_read_b128 v[142:145], v212
	ds_read_b128 v[146:149], v212 offset:2048
	ds_read_b128 v[150:153], v212 offset:4096
	ds_read_b128 v[154:157], v212 offset:6144
	ds_read_b128 v[174:177], v214 offset:32768
	ds_read_b128 v[182:185], v214 offset:34816
	ds_read_b128 v[186:189], v214 offset:36864
	ds_read_b128 v[190:193], v214 offset:38912
	v_mfma_f32_16x16x32_bf16 v[44:47], v[162:165], v[194:197], v[44:47]
	v_mfma_f32_16x16x32_bf16 v[32:35], v[162:165], v[198:201], v[32:35]
	v_mfma_f32_16x16x32_bf16 v[28:31], v[162:165], v[202:205], v[28:31]
	v_mfma_f32_16x16x32_bf16 v[24:27], v[162:165], v[206:209], v[24:27]
	v_mfma_f32_16x16x32_bf16 v[20:23], v[166:169], v[194:197], v[20:23]
	v_mfma_f32_16x16x32_bf16 v[16:19], v[166:169], v[198:201], v[16:19]
	v_mfma_f32_16x16x32_bf16 v[12:15], v[166:169], v[202:205], v[12:15]
	v_mfma_f32_16x16x32_bf16 v[8:11], v[166:169], v[206:209], v[8:11]
	v_mfma_f32_16x16x32_bf16 v[4:7], v[170:173], v[194:197], v[4:7]
	v_mfma_f32_16x16x32_bf16 v[0:3], v[170:173], v[198:201], v[0:3]
	v_mfma_f32_16x16x32_bf16 v[40:43], v[170:173], v[202:205], v[40:43]
	v_mfma_f32_16x16x32_bf16 v[36:39], v[170:173], v[206:209], v[36:39]
	ds_read_b128 v[158:161], v212 offset:8192
	ds_read_b128 v[162:165], v212 offset:10240
	ds_read_b128 v[166:169], v212 offset:12288
	ds_read_b128 v[170:173], v212 offset:14336
	s_waitcnt lgkmcnt(4)
	v_mfma_f32_16x16x32_bf16 v[124:127], v[142:145], v[174:177], v[124:127]
	v_mfma_f32_16x16x32_bf16 v[120:123], v[142:145], v[182:185], v[120:123]
	v_mfma_f32_16x16x32_bf16 v[116:119], v[142:145], v[186:189], v[116:119]
	v_mfma_f32_16x16x32_bf16 v[112:115], v[142:145], v[190:193], v[112:115]
	v_mfma_f32_16x16x32_bf16 v[108:111], v[146:149], v[174:177], v[108:111]
	v_mfma_f32_16x16x32_bf16 v[104:107], v[146:149], v[182:185], v[104:107]
	v_mfma_f32_16x16x32_bf16 v[100:103], v[146:149], v[186:189], v[100:103]
	v_mfma_f32_16x16x32_bf16 v[96:99], v[146:149], v[190:193], v[96:99]
	v_mfma_f32_16x16x32_bf16 v[92:95], v[150:153], v[174:177], v[92:95]
	v_mfma_f32_16x16x32_bf16 v[88:91], v[150:153], v[182:185], v[88:91]
	v_mfma_f32_16x16x32_bf16 v[84:87], v[150:153], v[186:189], v[84:87]
	v_mfma_f32_16x16x32_bf16 v[80:83], v[150:153], v[190:193], v[80:83]
	v_mfma_f32_16x16x32_bf16 v[76:79], v[154:157], v[174:177], v[76:79]
	v_mfma_f32_16x16x32_bf16 v[72:75], v[154:157], v[182:185], v[72:75]
	v_mfma_f32_16x16x32_bf16 v[68:71], v[154:157], v[186:189], v[68:71]
	v_mfma_f32_16x16x32_bf16 v[64:67], v[154:157], v[190:193], v[64:67]
	ds_read_b128 v[142:145], v213
	ds_read_b128 v[146:149], v213 offset:2048
	ds_read_b128 v[150:153], v213 offset:4096
	ds_read_b128 v[154:157], v213 offset:6144
	ds_read_b128 v[194:197], v215 offset:32768
	ds_read_b128 v[198:201], v215 offset:34816
	ds_read_b128 v[202:205], v215 offset:36864
	ds_read_b128 v[206:209], v215 offset:38912
	s_waitcnt lgkmcnt(8)
	v_mfma_f32_16x16x32_bf16 v[60:63], v[158:161], v[174:177], v[60:63]
	v_mfma_f32_16x16x32_bf16 v[56:59], v[158:161], v[182:185], v[56:59]
	v_mfma_f32_16x16x32_bf16 v[52:55], v[158:161], v[186:189], v[52:55]
	v_mfma_f32_16x16x32_bf16 v[48:51], v[158:161], v[190:193], v[48:51]
	v_mfma_f32_16x16x32_bf16 v[44:47], v[162:165], v[174:177], v[44:47]
	v_mfma_f32_16x16x32_bf16 v[32:35], v[162:165], v[182:185], v[32:35]
	v_mfma_f32_16x16x32_bf16 v[28:31], v[162:165], v[186:189], v[28:31]
	v_mfma_f32_16x16x32_bf16 v[24:27], v[162:165], v[190:193], v[24:27]
	v_mfma_f32_16x16x32_bf16 v[20:23], v[166:169], v[174:177], v[20:23]
	v_mfma_f32_16x16x32_bf16 v[16:19], v[166:169], v[182:185], v[16:19]
	v_mfma_f32_16x16x32_bf16 v[12:15], v[166:169], v[186:189], v[12:15]
	v_mfma_f32_16x16x32_bf16 v[8:11], v[166:169], v[190:193], v[8:11]
	v_mfma_f32_16x16x32_bf16 v[4:7], v[170:173], v[174:177], v[4:7]
	v_mfma_f32_16x16x32_bf16 v[0:3], v[170:173], v[182:185], v[0:3]
	v_mfma_f32_16x16x32_bf16 v[40:43], v[170:173], v[186:189], v[40:43]
	v_mfma_f32_16x16x32_bf16 v[36:39], v[170:173], v[190:193], v[36:39]
	ds_read_b128 v[158:161], v213 offset:8192
	ds_read_b128 v[162:165], v213 offset:10240
	ds_read_b128 v[166:169], v213 offset:12288
	ds_read_b128 v[170:173], v213 offset:14336
	s_waitcnt lgkmcnt(4)
	v_mfma_f32_16x16x32_bf16 v[124:127], v[142:145], v[194:197], v[124:127]
	v_mfma_f32_16x16x32_bf16 v[120:123], v[142:145], v[198:201], v[120:123]
	v_mfma_f32_16x16x32_bf16 v[116:119], v[142:145], v[202:205], v[116:119]
	v_mfma_f32_16x16x32_bf16 v[112:115], v[142:145], v[206:209], v[112:115]
	v_mfma_f32_16x16x32_bf16 v[108:111], v[146:149], v[194:197], v[108:111]
	v_mfma_f32_16x16x32_bf16 v[104:107], v[146:149], v[198:201], v[104:107]
	v_mfma_f32_16x16x32_bf16 v[100:103], v[146:149], v[202:205], v[100:103]
	v_mfma_f32_16x16x32_bf16 v[96:99], v[146:149], v[206:209], v[96:99]
	v_mfma_f32_16x16x32_bf16 v[92:95], v[150:153], v[194:197], v[92:95]
	v_mfma_f32_16x16x32_bf16 v[88:91], v[150:153], v[198:201], v[88:91]
	v_mfma_f32_16x16x32_bf16 v[84:87], v[150:153], v[202:205], v[84:87]
	v_mfma_f32_16x16x32_bf16 v[80:83], v[150:153], v[206:209], v[80:83]
	v_mfma_f32_16x16x32_bf16 v[76:79], v[154:157], v[194:197], v[76:79]
	v_mfma_f32_16x16x32_bf16 v[72:75], v[154:157], v[198:201], v[72:75]
	v_mfma_f32_16x16x32_bf16 v[68:71], v[154:157], v[202:205], v[68:71]
	v_mfma_f32_16x16x32_bf16 v[64:67], v[154:157], v[206:209], v[64:67]
	s_add_u32 s48, s48, 0x80
	s_addc_u32 s49, s49, 0
	s_add_i32 s47, s47, 1
	s_waitcnt lgkmcnt(0)
	s_waitcnt vmcnt(0)
	s_barrier
	v_mfma_f32_16x16x32_bf16 v[60:63], v[158:161], v[194:197], v[60:63]
	v_mfma_f32_16x16x32_bf16 v[56:59], v[158:161], v[198:201], v[56:59]
	v_mfma_f32_16x16x32_bf16 v[52:55], v[158:161], v[202:205], v[52:55]
	v_mfma_f32_16x16x32_bf16 v[48:51], v[158:161], v[206:209], v[48:51]
	v_mfma_f32_16x16x32_bf16 v[44:47], v[162:165], v[194:197], v[44:47]
	v_mfma_f32_16x16x32_bf16 v[32:35], v[162:165], v[198:201], v[32:35]
	v_mfma_f32_16x16x32_bf16 v[28:31], v[162:165], v[202:205], v[28:31]
	v_mfma_f32_16x16x32_bf16 v[24:27], v[162:165], v[206:209], v[24:27]
	v_mfma_f32_16x16x32_bf16 v[20:23], v[166:169], v[194:197], v[20:23]
	v_mfma_f32_16x16x32_bf16 v[16:19], v[166:169], v[198:201], v[16:19]
	v_mfma_f32_16x16x32_bf16 v[12:15], v[166:169], v[202:205], v[12:15]
	v_mfma_f32_16x16x32_bf16 v[8:11], v[166:169], v[206:209], v[8:11]
	v_mfma_f32_16x16x32_bf16 v[4:7], v[170:173], v[194:197], v[4:7]
	v_mfma_f32_16x16x32_bf16 v[0:3], v[170:173], v[198:201], v[0:3]
	v_mfma_f32_16x16x32_bf16 v[40:43], v[170:173], v[202:205], v[40:43]
	v_mfma_f32_16x16x32_bf16 v[36:39], v[170:173], v[206:209], v[36:39]
	s_nop 7
	s_nop 7
	s_sub_u32 s48, s48, s34
	s_subb_u32 s49, s49, s35
	s_mov_b32 s61, 0x100000
	s_mov_b32 s62, 0x100000
	s_mov_b64 s[50:51], 0
	s_mov_b64 vcc, exec
	s_branch .LBB0_745

.Lg8_top:
	s_waitcnt lgkmcnt(0)
	v_mfma_f32_16x16x32_bf16 v[60:63], v[170:173], v[206:209], v[60:63]
	v_mfma_f32_16x16x32_bf16 v[56:59], v[170:173], v[210:213], v[56:59]
	v_mfma_f32_16x16x32_bf16 v[52:55], v[170:173], v[214:217], v[52:55]
	v_mfma_f32_16x16x32_bf16 v[44:47], v[170:173], v[218:221], v[44:47]
	s_waitcnt vmcnt(0)
	s_barrier
	s_xor_b32 s59, s59, 0x10000
	s_mov_b32 m0, s59
	s_add_u32 s62, s60, s22
	s_addc_u32 s63, s61, s23
	global_load_lds_dwordx4 v178, s[62:63]
	ds_read_b128 v[154:157], v180
	ds_read_b128 v[158:161], v180 offset:2048
	ds_read_b128 v[162:165], v180 offset:4096
	ds_read_b128 v[166:169], v180 offset:6144
	ds_read_b128 v[190:193], v223 offset:32768
	ds_read_b128 v[194:197], v223 offset:34816
	ds_read_b128 v[198:201], v223 offset:36864
	ds_read_b128 v[202:205], v223 offset:38912
	v_mfma_f32_16x16x32_bf16 v[36:39], v[174:177], v[206:209], v[36:39]
	v_mfma_f32_16x16x32_bf16 v[32:35], v[174:177], v[210:213], v[32:35]
	s_add_u32 m0, s59, 0x2000
	s_add_u32 s62, s60, s36
	s_addc_u32 s63, s61, s37
	global_load_lds_dwordx4 v178, s[62:63]
	v_mfma_f32_16x16x32_bf16 v[28:31], v[174:177], v[214:217], v[28:31]
	v_mfma_f32_16x16x32_bf16 v[24:27], v[174:177], v[218:221], v[24:27]
	s_add_u32 m0, s59, 0x4000
	s_add_u32 s62, s60, s38
	s_addc_u32 s63, s61, s39
	global_load_lds_dwordx4 v178, s[62:63]
	v_mfma_f32_16x16x32_bf16 v[20:23], v[182:185], v[206:209], v[20:23]
	v_mfma_f32_16x16x32_bf16 v[16:19], v[182:185], v[210:213], v[16:19]
	s_add_u32 m0, s59, 0x6000
	s_add_u32 s62, s60, s40
	s_addc_u32 s63, s61, s41
	global_load_lds_dwordx4 v178, s[62:63]
	v_mfma_f32_16x16x32_bf16 v[12:15], v[182:185], v[214:217], v[12:15]
	v_mfma_f32_16x16x32_bf16 v[8:11], v[182:185], v[218:221], v[8:11]
	s_add_u32 m0, s59, 0x8000
	s_add_u32 s62, s60, s42
	s_addc_u32 s63, s61, s43
	global_load_lds_dwordx4 v179, s[62:63]
	v_mfma_f32_16x16x32_bf16 v[4:7], v[186:189], v[206:209], v[4:7]
	v_mfma_f32_16x16x32_bf16 v[0:3], v[186:189], v[210:213], v[0:3]
	s_add_u32 m0, s59, 0xa000
	s_add_u32 s62, s60, s44
	s_addc_u32 s63, s61, s45
	global_load_lds_dwordx4 v179, s[62:63]
	v_mfma_f32_16x16x32_bf16 v[48:51], v[186:189], v[214:217], v[48:51]
	v_mfma_f32_16x16x32_bf16 v[40:43], v[186:189], v[218:221], v[40:43]
	s_add_u32 m0, s59, 0xc000
	s_add_u32 s62, s60, s46
	s_addc_u32 s63, s61, s47
	global_load_lds_dwordx4 v179, s[62:63]
.Lg8_entry:
	ds_read_b128 v[170:173], v180 offset:8192
	ds_read_b128 v[174:177], v180 offset:10240
	ds_read_b128 v[182:185], v180 offset:12288
	ds_read_b128 v[186:189], v180 offset:14336
	s_waitcnt lgkmcnt(4)
	v_mfma_f32_16x16x32_bf16 v[124:127], v[154:157], v[190:193], v[124:127]
	v_mfma_f32_16x16x32_bf16 v[120:123], v[154:157], v[194:197], v[120:123]
	s_add_u32 m0, s59, 0xe000
	s_add_u32 s62, s60, s48
	s_addc_u32 s63, s61, s49
	global_load_lds_dwordx4 v179, s[62:63]
	v_mfma_f32_16x16x32_bf16 v[116:119], v[154:157], v[198:201], v[116:119]
	v_mfma_f32_16x16x32_bf16 v[112:115], v[154:157], v[202:205], v[112:115]
	v_mfma_f32_16x16x32_bf16 v[108:111], v[158:161], v[190:193], v[108:111]
	v_mfma_f32_16x16x32_bf16 v[104:107], v[158:161], v[194:197], v[104:107]
	v_mfma_f32_16x16x32_bf16 v[100:103], v[158:161], v[198:201], v[100:103]
	v_mfma_f32_16x16x32_bf16 v[96:99], v[158:161], v[202:205], v[96:99]
	v_mfma_f32_16x16x32_bf16 v[92:95], v[162:165], v[190:193], v[92:95]
	v_mfma_f32_16x16x32_bf16 v[88:91], v[162:165], v[194:197], v[88:91]
	v_mfma_f32_16x16x32_bf16 v[84:87], v[162:165], v[198:201], v[84:87]
	v_mfma_f32_16x16x32_bf16 v[80:83], v[162:165], v[202:205], v[80:83]
	v_mfma_f32_16x16x32_bf16 v[76:79], v[166:169], v[190:193], v[76:79]
	v_mfma_f32_16x16x32_bf16 v[72:75], v[166:169], v[194:197], v[72:75]
	v_mfma_f32_16x16x32_bf16 v[68:71], v[166:169], v[198:201], v[68:71]
	v_mfma_f32_16x16x32_bf16 v[64:67], v[166:169], v[202:205], v[64:67]
	ds_read_b128 v[154:157], v222
	ds_read_b128 v[158:161], v222 offset:2048
	ds_read_b128 v[162:165], v222 offset:4096
	ds_read_b128 v[166:169], v222 offset:6144
	ds_read_b128 v[206:209], v224 offset:32768
	ds_read_b128 v[210:213], v224 offset:34816
	ds_read_b128 v[214:217], v224 offset:36864
	ds_read_b128 v[218:221], v224 offset:38912
	s_waitcnt lgkmcnt(8)
	v_mfma_f32_16x16x32_bf16 v[60:63], v[170:173], v[190:193], v[60:63]
	v_mfma_f32_16x16x32_bf16 v[56:59], v[170:173], v[194:197], v[56:59]
	v_mfma_f32_16x16x32_bf16 v[52:55], v[170:173], v[198:201], v[52:55]
	v_mfma_f32_16x16x32_bf16 v[44:47], v[170:173], v[202:205], v[44:47]
	v_mfma_f32_16x16x32_bf16 v[36:39], v[174:177], v[190:193], v[36:39]
	v_mfma_f32_16x16x32_bf16 v[32:35], v[174:177], v[194:197], v[32:35]
	v_mfma_f32_16x16x32_bf16 v[28:31], v[174:177], v[198:201], v[28:31]
	v_mfma_f32_16x16x32_bf16 v[24:27], v[174:177], v[202:205], v[24:27]
	v_mfma_f32_16x16x32_bf16 v[20:23], v[182:185], v[190:193], v[20:23]
	v_mfma_f32_16x16x32_bf16 v[16:19], v[182:185], v[194:197], v[16:19]
	v_mfma_f32_16x16x32_bf16 v[12:15], v[182:185], v[198:201], v[12:15]
	v_mfma_f32_16x16x32_bf16 v[8:11], v[182:185], v[202:205], v[8:11]
	v_mfma_f32_16x16x32_bf16 v[4:7], v[186:189], v[190:193], v[4:7]
	v_mfma_f32_16x16x32_bf16 v[0:3], v[186:189], v[194:197], v[0:3]
	v_mfma_f32_16x16x32_bf16 v[48:51], v[186:189], v[198:201], v[48:51]
	v_mfma_f32_16x16x32_bf16 v[40:43], v[186:189], v[202:205], v[40:43]
	ds_read_b128 v[170:173], v222 offset:8192
	ds_read_b128 v[174:177], v222 offset:10240
	ds_read_b128 v[182:185], v222 offset:12288
	ds_read_b128 v[186:189], v222 offset:14336
	s_waitcnt lgkmcnt(4)
	v_mfma_f32_16x16x32_bf16 v[124:127], v[154:157], v[206:209], v[124:127]
	v_mfma_f32_16x16x32_bf16 v[120:123], v[154:157], v[210:213], v[120:123]
	v_mfma_f32_16x16x32_bf16 v[116:119], v[154:157], v[214:217], v[116:119]
	v_mfma_f32_16x16x32_bf16 v[112:115], v[154:157], v[218:221], v[112:115]
	v_mfma_f32_16x16x32_bf16 v[108:111], v[158:161], v[206:209], v[108:111]
	v_mfma_f32_16x16x32_bf16 v[104:107], v[158:161], v[210:213], v[104:107]
	v_mfma_f32_16x16x32_bf16 v[100:103], v[158:161], v[214:217], v[100:103]
	v_mfma_f32_16x16x32_bf16 v[96:99], v[158:161], v[218:221], v[96:99]
	v_mfma_f32_16x16x32_bf16 v[92:95], v[162:165], v[206:209], v[92:95]
	v_mfma_f32_16x16x32_bf16 v[88:91], v[162:165], v[210:213], v[88:91]
	v_mfma_f32_16x16x32_bf16 v[84:87], v[162:165], v[214:217], v[84:87]
	v_mfma_f32_16x16x32_bf16 v[80:83], v[162:165], v[218:221], v[80:83]
	v_mfma_f32_16x16x32_bf16 v[76:79], v[166:169], v[206:209], v[76:79]
	v_mfma_f32_16x16x32_bf16 v[72:75], v[166:169], v[210:213], v[72:75]
	v_mfma_f32_16x16x32_bf16 v[68:71], v[166:169], v[214:217], v[68:71]
	v_mfma_f32_16x16x32_bf16 v[64:67], v[166:169], v[218:221], v[64:67]
	s_add_u32 s60, s60, 0x80
	s_addc_u32 s61, s61, 0
	s_add_i32 s57, s57, 1
	s_cmp_lt_u32 s57, 15
	s_cbranch_scc0 .Lg8_last
	s_waitcnt lgkmcnt(0)
	v_mfma_f32_16x16x32_bf16 v[60:63], v[170:173], v[206:209], v[60:63]
	v_mfma_f32_16x16x32_bf16 v[56:59], v[170:173], v[210:213], v[56:59]
	v_mfma_f32_16x16x32_bf16 v[52:55], v[170:173], v[214:217], v[52:55]
	v_mfma_f32_16x16x32_bf16 v[44:47], v[170:173], v[218:221], v[44:47]
	s_waitcnt vmcnt(0)
	s_barrier
	s_xor_b32 s59, s59, 0x10000
	s_mov_b32 m0, s59
	s_add_u32 s62, s60, s22
	s_addc_u32 s63, s61, s23
	global_load_lds_dwordx4 v178, s[62:63]
	ds_read_b128 v[154:157], v225
	ds_read_b128 v[158:161], v225 offset:2048
	ds_read_b128 v[162:165], v225 offset:4096
	ds_read_b128 v[166:169], v225 offset:6144
	ds_read_b128 v[190:193], v227 offset:32768
	ds_read_b128 v[194:197], v227 offset:34816
	ds_read_b128 v[198:201], v227 offset:36864
	ds_read_b128 v[202:205], v227 offset:38912
	v_mfma_f32_16x16x32_bf16 v[36:39], v[174:177], v[206:209], v[36:39]
	v_mfma_f32_16x16x32_bf16 v[32:35], v[174:177], v[210:213], v[32:35]
	s_add_u32 m0, s59, 0x2000
	s_add_u32 s62, s60, s36
	s_addc_u32 s63, s61, s37
	global_load_lds_dwordx4 v178, s[62:63]
	v_mfma_f32_16x16x32_bf16 v[28:31], v[174:177], v[214:217], v[28:31]
	v_mfma_f32_16x16x32_bf16 v[24:27], v[174:177], v[218:221], v[24:27]
	s_add_u32 m0, s59, 0x4000
	s_add_u32 s62, s60, s38
	s_addc_u32 s63, s61, s39
	global_load_lds_dwordx4 v178, s[62:63]
	v_mfma_f32_16x16x32_bf16 v[20:23], v[182:185], v[206:209], v[20:23]
	v_mfma_f32_16x16x32_bf16 v[16:19], v[182:185], v[210:213], v[16:19]
	s_add_u32 m0, s59, 0x6000
	s_add_u32 s62, s60, s40
	s_addc_u32 s63, s61, s41
	global_load_lds_dwordx4 v178, s[62:63]
	v_mfma_f32_16x16x32_bf16 v[12:15], v[182:185], v[214:217], v[12:15]
	v_mfma_f32_16x16x32_bf16 v[8:11], v[182:185], v[218:221], v[8:11]
	s_add_u32 m0, s59, 0x8000
	s_add_u32 s62, s60, s42
	s_addc_u32 s63, s61, s43
	global_load_lds_dwordx4 v179, s[62:63]
	v_mfma_f32_16x16x32_bf16 v[4:7], v[186:189], v[206:209], v[4:7]
	v_mfma_f32_16x16x32_bf16 v[0:3], v[186:189], v[210:213], v[0:3]
	s_add_u32 m0, s59, 0xa000
	s_add_u32 s62, s60, s44
	s_addc_u32 s63, s61, s45
	global_load_lds_dwordx4 v179, s[62:63]
	v_mfma_f32_16x16x32_bf16 v[48:51], v[186:189], v[214:217], v[48:51]
	v_mfma_f32_16x16x32_bf16 v[40:43], v[186:189], v[218:221], v[40:43]
	s_add_u32 m0, s59, 0xc000
	s_add_u32 s62, s60, s46
	s_addc_u32 s63, s61, s47
	global_load_lds_dwordx4 v179, s[62:63]
	ds_read_b128 v[170:173], v225 offset:8192
	ds_read_b128 v[174:177], v225 offset:10240
	ds_read_b128 v[182:185], v225 offset:12288
	ds_read_b128 v[186:189], v225 offset:14336
	s_waitcnt lgkmcnt(4)
	v_mfma_f32_16x16x32_bf16 v[124:127], v[154:157], v[190:193], v[124:127]
	v_mfma_f32_16x16x32_bf16 v[120:123], v[154:157], v[194:197], v[120:123]
	s_add_u32 m0, s59, 0xe000
	s_add_u32 s62, s60, s48
	s_addc_u32 s63, s61, s49
	global_load_lds_dwordx4 v179, s[62:63]
	v_mfma_f32_16x16x32_bf16 v[116:119], v[154:157], v[198:201], v[116:119]
	v_mfma_f32_16x16x32_bf16 v[112:115], v[154:157], v[202:205], v[112:115]
	v_mfma_f32_16x16x32_bf16 v[108:111], v[158:161], v[190:193], v[108:111]
	v_mfma_f32_16x16x32_bf16 v[104:107], v[158:161], v[194:197], v[104:107]
	v_mfma_f32_16x16x32_bf16 v[100:103], v[158:161], v[198:201], v[100:103]
	v_mfma_f32_16x16x32_bf16 v[96:99], v[158:161], v[202:205], v[96:99]
	v_mfma_f32_16x16x32_bf16 v[92:95], v[162:165], v[190:193], v[92:95]
	v_mfma_f32_16x16x32_bf16 v[88:91], v[162:165], v[194:197], v[88:91]
	v_mfma_f32_16x16x32_bf16 v[84:87], v[162:165], v[198:201], v[84:87]
	v_mfma_f32_16x16x32_bf16 v[80:83], v[162:165], v[202:205], v[80:83]
	v_mfma_f32_16x16x32_bf16 v[76:79], v[166:169], v[190:193], v[76:79]
	v_mfma_f32_16x16x32_bf16 v[72:75], v[166:169], v[194:197], v[72:75]
	v_mfma_f32_16x16x32_bf16 v[68:71], v[166:169], v[198:201], v[68:71]
	v_mfma_f32_16x16x32_bf16 v[64:67], v[166:169], v[202:205], v[64:67]
	ds_read_b128 v[154:157], v226
	ds_read_b128 v[158:161], v226 offset:2048
	ds_read_b128 v[162:165], v226 offset:4096
	ds_read_b128 v[166:169], v226 offset:6144
	ds_read_b128 v[206:209], v228 offset:32768
	ds_read_b128 v[210:213], v228 offset:34816
	ds_read_b128 v[214:217], v228 offset:36864
	ds_read_b128 v[218:221], v228 offset:38912
	s_waitcnt lgkmcnt(8)
	v_mfma_f32_16x16x32_bf16 v[60:63], v[170:173], v[190:193], v[60:63]
	v_mfma_f32_16x16x32_bf16 v[56:59], v[170:173], v[194:197], v[56:59]
	v_mfma_f32_16x16x32_bf16 v[52:55], v[170:173], v[198:201], v[52:55]
	v_mfma_f32_16x16x32_bf16 v[44:47], v[170:173], v[202:205], v[44:47]
	v_mfma_f32_16x16x32_bf16 v[36:39], v[174:177], v[190:193], v[36:39]
	v_mfma_f32_16x16x32_bf16 v[32:35], v[174:177], v[194:197], v[32:35]
	v_mfma_f32_16x16x32_bf16 v[28:31], v[174:177], v[198:201], v[28:31]
	v_mfma_f32_16x16x32_bf16 v[24:27], v[174:177], v[202:205], v[24:27]
	v_mfma_f32_16x16x32_bf16 v[20:23], v[182:185], v[190:193], v[20:23]
	v_mfma_f32_16x16x32_bf16 v[16:19], v[182:185], v[194:197], v[16:19]
	v_mfma_f32_16x16x32_bf16 v[12:15], v[182:185], v[198:201], v[12:15]
	v_mfma_f32_16x16x32_bf16 v[8:11], v[182:185], v[202:205], v[8:11]
	v_mfma_f32_16x16x32_bf16 v[4:7], v[186:189], v[190:193], v[4:7]
	v_mfma_f32_16x16x32_bf16 v[0:3], v[186:189], v[194:197], v[0:3]
	v_mfma_f32_16x16x32_bf16 v[48:51], v[186:189], v[198:201], v[48:51]
	v_mfma_f32_16x16x32_bf16 v[40:43], v[186:189], v[202:205], v[40:43]
	ds_read_b128 v[170:173], v226 offset:8192
	ds_read_b128 v[174:177], v226 offset:10240
	ds_read_b128 v[182:185], v226 offset:12288
	ds_read_b128 v[186:189], v226 offset:14336
	s_waitcnt lgkmcnt(4)
	v_mfma_f32_16x16x32_bf16 v[124:127], v[154:157], v[206:209], v[124:127]
	v_mfma_f32_16x16x32_bf16 v[120:123], v[154:157], v[210:213], v[120:123]
	v_mfma_f32_16x16x32_bf16 v[116:119], v[154:157], v[214:217], v[116:119]
	v_mfma_f32_16x16x32_bf16 v[112:115], v[154:157], v[218:221], v[112:115]
	v_mfma_f32_16x16x32_bf16 v[108:111], v[158:161], v[206:209], v[108:111]
	v_mfma_f32_16x16x32_bf16 v[104:107], v[158:161], v[210:213], v[104:107]
	v_mfma_f32_16x16x32_bf16 v[100:103], v[158:161], v[214:217], v[100:103]
	v_mfma_f32_16x16x32_bf16 v[96:99], v[158:161], v[218:221], v[96:99]
	v_mfma_f32_16x16x32_bf16 v[92:95], v[162:165], v[206:209], v[92:95]
	v_mfma_f32_16x16x32_bf16 v[88:91], v[162:165], v[210:213], v[88:91]
	v_mfma_f32_16x16x32_bf16 v[84:87], v[162:165], v[214:217], v[84:87]
	v_mfma_f32_16x16x32_bf16 v[80:83], v[162:165], v[218:221], v[80:83]
	v_mfma_f32_16x16x32_bf16 v[76:79], v[166:169], v[206:209], v[76:79]
	v_mfma_f32_16x16x32_bf16 v[72:75], v[166:169], v[210:213], v[72:75]
	v_mfma_f32_16x16x32_bf16 v[68:71], v[166:169], v[214:217], v[68:71]
	v_mfma_f32_16x16x32_bf16 v[64:67], v[166:169], v[218:221], v[64:67]
	s_add_u32 s60, s60, 0x80
	s_addc_u32 s61, s61, 0
	s_add_i32 s57, s57, 1
	s_branch .Lg8_top
.Lg8_last:
	s_waitcnt lgkmcnt(0)
	v_mfma_f32_16x16x32_bf16 v[60:63], v[170:173], v[206:209], v[60:63]
	v_mfma_f32_16x16x32_bf16 v[56:59], v[170:173], v[210:213], v[56:59]
	v_mfma_f32_16x16x32_bf16 v[52:55], v[170:173], v[214:217], v[52:55]
	v_mfma_f32_16x16x32_bf16 v[44:47], v[170:173], v[218:221], v[44:47]
	s_waitcnt vmcnt(0)
	s_barrier
	s_xor_b32 s59, s59, 0x10000
	ds_read_b128 v[154:157], v225
	ds_read_b128 v[158:161], v225 offset:2048
	ds_read_b128 v[162:165], v225 offset:4096
	ds_read_b128 v[166:169], v225 offset:6144
	ds_read_b128 v[190:193], v227 offset:32768
	ds_read_b128 v[194:197], v227 offset:34816
	ds_read_b128 v[198:201], v227 offset:36864
	ds_read_b128 v[202:205], v227 offset:38912
	v_mfma_f32_16x16x32_bf16 v[36:39], v[174:177], v[206:209], v[36:39]
	v_mfma_f32_16x16x32_bf16 v[32:35], v[174:177], v[210:213], v[32:35]
	v_mfma_f32_16x16x32_bf16 v[28:31], v[174:177], v[214:217], v[28:31]
	v_mfma_f32_16x16x32_bf16 v[24:27], v[174:177], v[218:221], v[24:27]
	v_mfma_f32_16x16x32_bf16 v[20:23], v[182:185], v[206:209], v[20:23]
	v_mfma_f32_16x16x32_bf16 v[16:19], v[182:185], v[210:213], v[16:19]
	v_mfma_f32_16x16x32_bf16 v[12:15], v[182:185], v[214:217], v[12:15]
	v_mfma_f32_16x16x32_bf16 v[8:11], v[182:185], v[218:221], v[8:11]
	v_mfma_f32_16x16x32_bf16 v[4:7], v[186:189], v[206:209], v[4:7]
	v_mfma_f32_16x16x32_bf16 v[0:3], v[186:189], v[210:213], v[0:3]
	v_mfma_f32_16x16x32_bf16 v[48:51], v[186:189], v[214:217], v[48:51]
	v_mfma_f32_16x16x32_bf16 v[40:43], v[186:189], v[218:221], v[40:43]
	ds_read_b128 v[170:173], v225 offset:8192
	ds_read_b128 v[174:177], v225 offset:10240
	ds_read_b128 v[182:185], v225 offset:12288
	ds_read_b128 v[186:189], v225 offset:14336
	s_waitcnt lgkmcnt(4)
	v_mfma_f32_16x16x32_bf16 v[124:127], v[154:157], v[190:193], v[124:127]
	v_mfma_f32_16x16x32_bf16 v[120:123], v[154:157], v[194:197], v[120:123]
	v_mfma_f32_16x16x32_bf16 v[116:119], v[154:157], v[198:201], v[116:119]
	v_mfma_f32_16x16x32_bf16 v[112:115], v[154:157], v[202:205], v[112:115]
	v_mfma_f32_16x16x32_bf16 v[108:111], v[158:161], v[190:193], v[108:111]
	v_mfma_f32_16x16x32_bf16 v[104:107], v[158:161], v[194:197], v[104:107]
	v_mfma_f32_16x16x32_bf16 v[100:103], v[158:161], v[198:201], v[100:103]
	v_mfma_f32_16x16x32_bf16 v[96:99], v[158:161], v[202:205], v[96:99]
	v_mfma_f32_16x16x32_bf16 v[92:95], v[162:165], v[190:193], v[92:95]
	v_mfma_f32_16x16x32_bf16 v[88:91], v[162:165], v[194:197], v[88:91]
	v_mfma_f32_16x16x32_bf16 v[84:87], v[162:165], v[198:201], v[84:87]
	v_mfma_f32_16x16x32_bf16 v[80:83], v[162:165], v[202:205], v[80:83]
	v_mfma_f32_16x16x32_bf16 v[76:79], v[166:169], v[190:193], v[76:79]
	v_mfma_f32_16x16x32_bf16 v[72:75], v[166:169], v[194:197], v[72:75]
	v_mfma_f32_16x16x32_bf16 v[68:71], v[166:169], v[198:201], v[68:71]
	v_mfma_f32_16x16x32_bf16 v[64:67], v[166:169], v[202:205], v[64:67]
	ds_read_b128 v[154:157], v226
	ds_read_b128 v[158:161], v226 offset:2048
	ds_read_b128 v[162:165], v226 offset:4096
	ds_read_b128 v[166:169], v226 offset:6144
	ds_read_b128 v[206:209], v228 offset:32768
	ds_read_b128 v[210:213], v228 offset:34816
	ds_read_b128 v[214:217], v228 offset:36864
	ds_read_b128 v[218:221], v228 offset:38912
	s_waitcnt lgkmcnt(8)
	v_mfma_f32_16x16x32_bf16 v[60:63], v[170:173], v[190:193], v[60:63]
	v_mfma_f32_16x16x32_bf16 v[56:59], v[170:173], v[194:197], v[56:59]
	v_mfma_f32_16x16x32_bf16 v[52:55], v[170:173], v[198:201], v[52:55]
	v_mfma_f32_16x16x32_bf16 v[44:47], v[170:173], v[202:205], v[44:47]
	v_mfma_f32_16x16x32_bf16 v[36:39], v[174:177], v[190:193], v[36:39]
	v_mfma_f32_16x16x32_bf16 v[32:35], v[174:177], v[194:197], v[32:35]
	v_mfma_f32_16x16x32_bf16 v[28:31], v[174:177], v[198:201], v[28:31]
	v_mfma_f32_16x16x32_bf16 v[24:27], v[174:177], v[202:205], v[24:27]
	v_mfma_f32_16x16x32_bf16 v[20:23], v[182:185], v[190:193], v[20:23]
	v_mfma_f32_16x16x32_bf16 v[16:19], v[182:185], v[194:197], v[16:19]
	v_mfma_f32_16x16x32_bf16 v[12:15], v[182:185], v[198:201], v[12:15]
	v_mfma_f32_16x16x32_bf16 v[8:11], v[182:185], v[202:205], v[8:11]
	v_mfma_f32_16x16x32_bf16 v[4:7], v[186:189], v[190:193], v[4:7]
	v_mfma_f32_16x16x32_bf16 v[0:3], v[186:189], v[194:197], v[0:3]
	v_mfma_f32_16x16x32_bf16 v[48:51], v[186:189], v[198:201], v[48:51]
	v_mfma_f32_16x16x32_bf16 v[40:43], v[186:189], v[202:205], v[40:43]
	ds_read_b128 v[170:173], v226 offset:8192
	ds_read_b128 v[174:177], v226 offset:10240
	ds_read_b128 v[182:185], v226 offset:12288
	ds_read_b128 v[186:189], v226 offset:14336
	s_waitcnt lgkmcnt(4)
	v_mfma_f32_16x16x32_bf16 v[124:127], v[154:157], v[206:209], v[124:127]
	v_mfma_f32_16x16x32_bf16 v[120:123], v[154:157], v[210:213], v[120:123]
	v_mfma_f32_16x16x32_bf16 v[116:119], v[154:157], v[214:217], v[116:119]
	v_mfma_f32_16x16x32_bf16 v[112:115], v[154:157], v[218:221], v[112:115]
	v_mfma_f32_16x16x32_bf16 v[108:111], v[158:161], v[206:209], v[108:111]
	v_mfma_f32_16x16x32_bf16 v[104:107], v[158:161], v[210:213], v[104:107]
	v_mfma_f32_16x16x32_bf16 v[100:103], v[158:161], v[214:217], v[100:103]
	v_mfma_f32_16x16x32_bf16 v[96:99], v[158:161], v[218:221], v[96:99]
	v_mfma_f32_16x16x32_bf16 v[92:95], v[162:165], v[206:209], v[92:95]
	v_mfma_f32_16x16x32_bf16 v[88:91], v[162:165], v[210:213], v[88:91]
	v_mfma_f32_16x16x32_bf16 v[84:87], v[162:165], v[214:217], v[84:87]
	v_mfma_f32_16x16x32_bf16 v[80:83], v[162:165], v[218:221], v[80:83]
	v_mfma_f32_16x16x32_bf16 v[76:79], v[166:169], v[206:209], v[76:79]
	v_mfma_f32_16x16x32_bf16 v[72:75], v[166:169], v[210:213], v[72:75]
	v_mfma_f32_16x16x32_bf16 v[68:71], v[166:169], v[214:217], v[68:71]
	v_mfma_f32_16x16x32_bf16 v[64:67], v[166:169], v[218:221], v[64:67]
	s_add_u32 s60, s60, 0x80
	s_addc_u32 s61, s61, 0
	s_add_i32 s57, s57, 1
	s_waitcnt lgkmcnt(0)
	s_waitcnt vmcnt(0)
	s_barrier
	v_mfma_f32_16x16x32_bf16 v[60:63], v[170:173], v[206:209], v[60:63]
	v_mfma_f32_16x16x32_bf16 v[56:59], v[170:173], v[210:213], v[56:59]
	v_mfma_f32_16x16x32_bf16 v[52:55], v[170:173], v[214:217], v[52:55]
	v_mfma_f32_16x16x32_bf16 v[44:47], v[170:173], v[218:221], v[44:47]
	v_mfma_f32_16x16x32_bf16 v[36:39], v[174:177], v[206:209], v[36:39]
	v_mfma_f32_16x16x32_bf16 v[32:35], v[174:177], v[210:213], v[32:35]
	v_mfma_f32_16x16x32_bf16 v[28:31], v[174:177], v[214:217], v[28:31]
	v_mfma_f32_16x16x32_bf16 v[24:27], v[174:177], v[218:221], v[24:27]
	v_mfma_f32_16x16x32_bf16 v[20:23], v[182:185], v[206:209], v[20:23]
	v_mfma_f32_16x16x32_bf16 v[16:19], v[182:185], v[210:213], v[16:19]
	v_mfma_f32_16x16x32_bf16 v[12:15], v[182:185], v[214:217], v[12:15]
	v_mfma_f32_16x16x32_bf16 v[8:11], v[182:185], v[218:221], v[8:11]
	v_mfma_f32_16x16x32_bf16 v[4:7], v[186:189], v[206:209], v[4:7]
	v_mfma_f32_16x16x32_bf16 v[0:3], v[186:189], v[210:213], v[0:3]
	v_mfma_f32_16x16x32_bf16 v[48:51], v[186:189], v[214:217], v[48:51]
	v_mfma_f32_16x16x32_bf16 v[40:43], v[186:189], v[218:221], v[40:43]
	s_nop 7
	s_nop 7
	s_sub_u32 s60, s60, s34
	s_subb_u32 s61, s61, s35
	s_mov_b32 s59, 0x80000
	s_mov_b32 s65, 0x80000
	s_mov_b64 s[62:63], 0
	s_mov_b64 vcc, exec
	s_branch .LBB0_939

.Lg9_top:
	s_waitcnt lgkmcnt(0)
	v_mfma_f32_16x16x32_bf16 v[60:63], v[158:161], v[194:197], v[60:63]
	v_mfma_f32_16x16x32_bf16 v[56:59], v[158:161], v[198:201], v[56:59]
	v_mfma_f32_16x16x32_bf16 v[52:55], v[158:161], v[202:205], v[52:55]
	v_mfma_f32_16x16x32_bf16 v[48:51], v[158:161], v[206:209], v[48:51]
	s_waitcnt vmcnt(0)
	s_barrier
	s_xor_b32 s59, s59, 0x10000
	s_mov_b32 m0, s59
	s_add_u32 s46, s44, s12
	s_addc_u32 s47, s45, s13
	global_load_lds_dwordx4 v178, s[46:47]
	ds_read_b128 v[142:145], v141
	ds_read_b128 v[146:149], v141 offset:2048
	ds_read_b128 v[150:153], v141 offset:4096
	ds_read_b128 v[154:157], v141 offset:6144
	ds_read_b128 v[174:177], v210 offset:32768
	ds_read_b128 v[182:185], v210 offset:34816
	ds_read_b128 v[186:189], v210 offset:36864
	ds_read_b128 v[190:193], v210 offset:38912
	v_mfma_f32_16x16x32_bf16 v[44:47], v[162:165], v[194:197], v[44:47]
	v_mfma_f32_16x16x32_bf16 v[32:35], v[162:165], v[198:201], v[32:35]
	s_add_u32 m0, s59, 0x2000
	s_add_u32 s46, s44, s14
	s_addc_u32 s47, s45, s15
	global_load_lds_dwordx4 v178, s[46:47]
	v_mfma_f32_16x16x32_bf16 v[28:31], v[162:165], v[202:205], v[28:31]
	v_mfma_f32_16x16x32_bf16 v[24:27], v[162:165], v[206:209], v[24:27]
	s_add_u32 m0, s59, 0x4000
	s_add_u32 s46, s44, s16
	s_addc_u32 s47, s45, s17
	global_load_lds_dwordx4 v178, s[46:47]
	v_mfma_f32_16x16x32_bf16 v[20:23], v[166:169], v[194:197], v[20:23]
	v_mfma_f32_16x16x32_bf16 v[16:19], v[166:169], v[198:201], v[16:19]
	s_add_u32 m0, s59, 0x6000
	s_add_u32 s46, s44, s18
	s_addc_u32 s47, s45, s19
	global_load_lds_dwordx4 v178, s[46:47]
	v_mfma_f32_16x16x32_bf16 v[12:15], v[166:169], v[202:205], v[12:15]
	v_mfma_f32_16x16x32_bf16 v[8:11], v[166:169], v[206:209], v[8:11]
	s_add_u32 m0, s59, 0x8000
	s_add_u32 s46, s44, s22
	s_addc_u32 s47, s45, s23
	global_load_lds_dwordx4 v179, s[46:47]
	v_mfma_f32_16x16x32_bf16 v[4:7], v[170:173], v[194:197], v[4:7]
	v_mfma_f32_16x16x32_bf16 v[0:3], v[170:173], v[198:201], v[0:3]
	s_add_u32 m0, s59, 0xa000
	s_add_u32 s46, s44, s36
	s_addc_u32 s47, s45, s37
	global_load_lds_dwordx4 v179, s[46:47]
	v_mfma_f32_16x16x32_bf16 v[40:43], v[170:173], v[202:205], v[40:43]
	v_mfma_f32_16x16x32_bf16 v[36:39], v[170:173], v[206:209], v[36:39]
	s_add_u32 m0, s59, 0xc000
	s_add_u32 s46, s44, s38
	s_addc_u32 s47, s45, s39
	global_load_lds_dwordx4 v179, s[46:47]
.Lg9_entry:
	ds_read_b128 v[158:161], v141 offset:8192
	ds_read_b128 v[162:165], v141 offset:10240
	ds_read_b128 v[166:169], v141 offset:12288
	ds_read_b128 v[170:173], v141 offset:14336
	s_waitcnt lgkmcnt(4)
	v_mfma_f32_16x16x32_bf16 v[124:127], v[142:145], v[174:177], v[124:127]
	v_mfma_f32_16x16x32_bf16 v[120:123], v[142:145], v[182:185], v[120:123]
	s_add_u32 m0, s59, 0xe000
	s_add_u32 s46, s44, s40
	s_addc_u32 s47, s45, s41
	global_load_lds_dwordx4 v179, s[46:47]
	v_mfma_f32_16x16x32_bf16 v[116:119], v[142:145], v[186:189], v[116:119]
	v_mfma_f32_16x16x32_bf16 v[112:115], v[142:145], v[190:193], v[112:115]
	v_mfma_f32_16x16x32_bf16 v[108:111], v[146:149], v[174:177], v[108:111]
	v_mfma_f32_16x16x32_bf16 v[104:107], v[146:149], v[182:185], v[104:107]
	v_mfma_f32_16x16x32_bf16 v[100:103], v[146:149], v[186:189], v[100:103]
	v_mfma_f32_16x16x32_bf16 v[96:99], v[146:149], v[190:193], v[96:99]
	v_mfma_f32_16x16x32_bf16 v[92:95], v[150:153], v[174:177], v[92:95]
	v_mfma_f32_16x16x32_bf16 v[88:91], v[150:153], v[182:185], v[88:91]
	v_mfma_f32_16x16x32_bf16 v[84:87], v[150:153], v[186:189], v[84:87]
	v_mfma_f32_16x16x32_bf16 v[80:83], v[150:153], v[190:193], v[80:83]
	v_mfma_f32_16x16x32_bf16 v[76:79], v[154:157], v[174:177], v[76:79]
	v_mfma_f32_16x16x32_bf16 v[72:75], v[154:157], v[182:185], v[72:75]
	v_mfma_f32_16x16x32_bf16 v[68:71], v[154:157], v[186:189], v[68:71]
	v_mfma_f32_16x16x32_bf16 v[64:67], v[154:157], v[190:193], v[64:67]
	ds_read_b128 v[142:145], v180
	ds_read_b128 v[146:149], v180 offset:2048
	ds_read_b128 v[150:153], v180 offset:4096
	ds_read_b128 v[154:157], v180 offset:6144
	ds_read_b128 v[194:197], v211 offset:32768
	ds_read_b128 v[198:201], v211 offset:34816
	ds_read_b128 v[202:205], v211 offset:36864
	ds_read_b128 v[206:209], v211 offset:38912
	s_waitcnt lgkmcnt(8)
	v_mfma_f32_16x16x32_bf16 v[60:63], v[158:161], v[174:177], v[60:63]
	v_mfma_f32_16x16x32_bf16 v[56:59], v[158:161], v[182:185], v[56:59]
	v_mfma_f32_16x16x32_bf16 v[52:55], v[158:161], v[186:189], v[52:55]
	v_mfma_f32_16x16x32_bf16 v[48:51], v[158:161], v[190:193], v[48:51]
	v_mfma_f32_16x16x32_bf16 v[44:47], v[162:165], v[174:177], v[44:47]
	v_mfma_f32_16x16x32_bf16 v[32:35], v[162:165], v[182:185], v[32:35]
	v_mfma_f32_16x16x32_bf16 v[28:31], v[162:165], v[186:189], v[28:31]
	v_mfma_f32_16x16x32_bf16 v[24:27], v[162:165], v[190:193], v[24:27]
	v_mfma_f32_16x16x32_bf16 v[20:23], v[166:169], v[174:177], v[20:23]
	v_mfma_f32_16x16x32_bf16 v[16:19], v[166:169], v[182:185], v[16:19]
	v_mfma_f32_16x16x32_bf16 v[12:15], v[166:169], v[186:189], v[12:15]
	v_mfma_f32_16x16x32_bf16 v[8:11], v[166:169], v[190:193], v[8:11]
	v_mfma_f32_16x16x32_bf16 v[4:7], v[170:173], v[174:177], v[4:7]
	v_mfma_f32_16x16x32_bf16 v[0:3], v[170:173], v[182:185], v[0:3]
	v_mfma_f32_16x16x32_bf16 v[40:43], v[170:173], v[186:189], v[40:43]
	v_mfma_f32_16x16x32_bf16 v[36:39], v[170:173], v[190:193], v[36:39]
	ds_read_b128 v[158:161], v180 offset:8192
	ds_read_b128 v[162:165], v180 offset:10240
	ds_read_b128 v[166:169], v180 offset:12288
	ds_read_b128 v[170:173], v180 offset:14336
	s_waitcnt lgkmcnt(4)
	v_mfma_f32_16x16x32_bf16 v[124:127], v[142:145], v[194:197], v[124:127]
	v_mfma_f32_16x16x32_bf16 v[120:123], v[142:145], v[198:201], v[120:123]
	v_mfma_f32_16x16x32_bf16 v[116:119], v[142:145], v[202:205], v[116:119]
	v_mfma_f32_16x16x32_bf16 v[112:115], v[142:145], v[206:209], v[112:115]
	v_mfma_f32_16x16x32_bf16 v[108:111], v[146:149], v[194:197], v[108:111]
	v_mfma_f32_16x16x32_bf16 v[104:107], v[146:149], v[198:201], v[104:107]
	v_mfma_f32_16x16x32_bf16 v[100:103], v[146:149], v[202:205], v[100:103]
	v_mfma_f32_16x16x32_bf16 v[96:99], v[146:149], v[206:209], v[96:99]
	v_mfma_f32_16x16x32_bf16 v[92:95], v[150:153], v[194:197], v[92:95]
	v_mfma_f32_16x16x32_bf16 v[88:91], v[150:153], v[198:201], v[88:91]
	v_mfma_f32_16x16x32_bf16 v[84:87], v[150:153], v[202:205], v[84:87]
	v_mfma_f32_16x16x32_bf16 v[80:83], v[150:153], v[206:209], v[80:83]
	v_mfma_f32_16x16x32_bf16 v[76:79], v[154:157], v[194:197], v[76:79]
	v_mfma_f32_16x16x32_bf16 v[72:75], v[154:157], v[198:201], v[72:75]
	v_mfma_f32_16x16x32_bf16 v[68:71], v[154:157], v[202:205], v[68:71]
	v_mfma_f32_16x16x32_bf16 v[64:67], v[154:157], v[206:209], v[64:67]
	s_add_u32 s44, s44, 0x80
	s_addc_u32 s45, s45, 0
	s_add_i32 s43, s43, 1
	s_cmp_lt_u32 s43, 31
	s_cbranch_scc0 .Lg9_last
	s_waitcnt lgkmcnt(0)
	v_mfma_f32_16x16x32_bf16 v[60:63], v[158:161], v[194:197], v[60:63]
	v_mfma_f32_16x16x32_bf16 v[56:59], v[158:161], v[198:201], v[56:59]
	v_mfma_f32_16x16x32_bf16 v[52:55], v[158:161], v[202:205], v[52:55]
	v_mfma_f32_16x16x32_bf16 v[48:51], v[158:161], v[206:209], v[48:51]
	s_waitcnt vmcnt(0)
	s_barrier
	s_xor_b32 s59, s59, 0x10000
	s_mov_b32 m0, s59
	s_add_u32 s46, s44, s12
	s_addc_u32 s47, s45, s13
	global_load_lds_dwordx4 v178, s[46:47]
	ds_read_b128 v[142:145], v212
	ds_read_b128 v[146:149], v212 offset:2048
	ds_read_b128 v[150:153], v212 offset:4096
	ds_read_b128 v[154:157], v212 offset:6144
	ds_read_b128 v[174:177], v214 offset:32768
	ds_read_b128 v[182:185], v214 offset:34816
	ds_read_b128 v[186:189], v214 offset:36864
	ds_read_b128 v[190:193], v214 offset:38912
	v_mfma_f32_16x16x32_bf16 v[44:47], v[162:165], v[194:197], v[44:47]
	v_mfma_f32_16x16x32_bf16 v[32:35], v[162:165], v[198:201], v[32:35]
	s_add_u32 m0, s59, 0x2000
	s_add_u32 s46, s44, s14
	s_addc_u32 s47, s45, s15
	global_load_lds_dwordx4 v178, s[46:47]
	v_mfma_f32_16x16x32_bf16 v[28:31], v[162:165], v[202:205], v[28:31]
	v_mfma_f32_16x16x32_bf16 v[24:27], v[162:165], v[206:209], v[24:27]
	s_add_u32 m0, s59, 0x4000
	s_add_u32 s46, s44, s16
	s_addc_u32 s47, s45, s17
	global_load_lds_dwordx4 v178, s[46:47]
	v_mfma_f32_16x16x32_bf16 v[20:23], v[166:169], v[194:197], v[20:23]
	v_mfma_f32_16x16x32_bf16 v[16:19], v[166:169], v[198:201], v[16:19]
	s_add_u32 m0, s59, 0x6000
	s_add_u32 s46, s44, s18
	s_addc_u32 s47, s45, s19
	global_load_lds_dwordx4 v178, s[46:47]
	v_mfma_f32_16x16x32_bf16 v[12:15], v[166:169], v[202:205], v[12:15]
	v_mfma_f32_16x16x32_bf16 v[8:11], v[166:169], v[206:209], v[8:11]
	s_add_u32 m0, s59, 0x8000
	s_add_u32 s46, s44, s22
	s_addc_u32 s47, s45, s23
	global_load_lds_dwordx4 v179, s[46:47]
	v_mfma_f32_16x16x32_bf16 v[4:7], v[170:173], v[194:197], v[4:7]
	v_mfma_f32_16x16x32_bf16 v[0:3], v[170:173], v[198:201], v[0:3]
	s_add_u32 m0, s59, 0xa000
	s_add_u32 s46, s44, s36
	s_addc_u32 s47, s45, s37
	global_load_lds_dwordx4 v179, s[46:47]
	v_mfma_f32_16x16x32_bf16 v[40:43], v[170:173], v[202:205], v[40:43]
	v_mfma_f32_16x16x32_bf16 v[36:39], v[170:173], v[206:209], v[36:39]
	s_add_u32 m0, s59, 0xc000
	s_add_u32 s46, s44, s38
	s_addc_u32 s47, s45, s39
	global_load_lds_dwordx4 v179, s[46:47]
	ds_read_b128 v[158:161], v212 offset:8192
	ds_read_b128 v[162:165], v212 offset:10240
	ds_read_b128 v[166:169], v212 offset:12288
	ds_read_b128 v[170:173], v212 offset:14336
	s_waitcnt lgkmcnt(4)
	v_mfma_f32_16x16x32_bf16 v[124:127], v[142:145], v[174:177], v[124:127]
	v_mfma_f32_16x16x32_bf16 v[120:123], v[142:145], v[182:185], v[120:123]
	s_add_u32 m0, s59, 0xe000
	s_add_u32 s46, s44, s40
	s_addc_u32 s47, s45, s41
	global_load_lds_dwordx4 v179, s[46:47]
	v_mfma_f32_16x16x32_bf16 v[116:119], v[142:145], v[186:189], v[116:119]
	v_mfma_f32_16x16x32_bf16 v[112:115], v[142:145], v[190:193], v[112:115]
	v_mfma_f32_16x16x32_bf16 v[108:111], v[146:149], v[174:177], v[108:111]
	v_mfma_f32_16x16x32_bf16 v[104:107], v[146:149], v[182:185], v[104:107]
	v_mfma_f32_16x16x32_bf16 v[100:103], v[146:149], v[186:189], v[100:103]
	v_mfma_f32_16x16x32_bf16 v[96:99], v[146:149], v[190:193], v[96:99]
	v_mfma_f32_16x16x32_bf16 v[92:95], v[150:153], v[174:177], v[92:95]
	v_mfma_f32_16x16x32_bf16 v[88:91], v[150:153], v[182:185], v[88:91]
	v_mfma_f32_16x16x32_bf16 v[84:87], v[150:153], v[186:189], v[84:87]
	v_mfma_f32_16x16x32_bf16 v[80:83], v[150:153], v[190:193], v[80:83]
	v_mfma_f32_16x16x32_bf16 v[76:79], v[154:157], v[174:177], v[76:79]
	v_mfma_f32_16x16x32_bf16 v[72:75], v[154:157], v[182:185], v[72:75]
	v_mfma_f32_16x16x32_bf16 v[68:71], v[154:157], v[186:189], v[68:71]
	v_mfma_f32_16x16x32_bf16 v[64:67], v[154:157], v[190:193], v[64:67]
	ds_read_b128 v[142:145], v213
	ds_read_b128 v[146:149], v213 offset:2048
	ds_read_b128 v[150:153], v213 offset:4096
	ds_read_b128 v[154:157], v213 offset:6144
	ds_read_b128 v[194:197], v215 offset:32768
	ds_read_b128 v[198:201], v215 offset:34816
	ds_read_b128 v[202:205], v215 offset:36864
	ds_read_b128 v[206:209], v215 offset:38912
	s_waitcnt lgkmcnt(8)
	v_mfma_f32_16x16x32_bf16 v[60:63], v[158:161], v[174:177], v[60:63]
	v_mfma_f32_16x16x32_bf16 v[56:59], v[158:161], v[182:185], v[56:59]
	v_mfma_f32_16x16x32_bf16 v[52:55], v[158:161], v[186:189], v[52:55]
	v_mfma_f32_16x16x32_bf16 v[48:51], v[158:161], v[190:193], v[48:51]
	v_mfma_f32_16x16x32_bf16 v[44:47], v[162:165], v[174:177], v[44:47]
	v_mfma_f32_16x16x32_bf16 v[32:35], v[162:165], v[182:185], v[32:35]
	v_mfma_f32_16x16x32_bf16 v[28:31], v[162:165], v[186:189], v[28:31]
	v_mfma_f32_16x16x32_bf16 v[24:27], v[162:165], v[190:193], v[24:27]
	v_mfma_f32_16x16x32_bf16 v[20:23], v[166:169], v[174:177], v[20:23]
	v_mfma_f32_16x16x32_bf16 v[16:19], v[166:169], v[182:185], v[16:19]
	v_mfma_f32_16x16x32_bf16 v[12:15], v[166:169], v[186:189], v[12:15]
	v_mfma_f32_16x16x32_bf16 v[8:11], v[166:169], v[190:193], v[8:11]
	v_mfma_f32_16x16x32_bf16 v[4:7], v[170:173], v[174:177], v[4:7]
	v_mfma_f32_16x16x32_bf16 v[0:3], v[170:173], v[182:185], v[0:3]
	v_mfma_f32_16x16x32_bf16 v[40:43], v[170:173], v[186:189], v[40:43]
	v_mfma_f32_16x16x32_bf16 v[36:39], v[170:173], v[190:193], v[36:39]
	ds_read_b128 v[158:161], v213 offset:8192
	ds_read_b128 v[162:165], v213 offset:10240
	ds_read_b128 v[166:169], v213 offset:12288
	ds_read_b128 v[170:173], v213 offset:14336
	s_waitcnt lgkmcnt(4)
	v_mfma_f32_16x16x32_bf16 v[124:127], v[142:145], v[194:197], v[124:127]
	v_mfma_f32_16x16x32_bf16 v[120:123], v[142:145], v[198:201], v[120:123]
	v_mfma_f32_16x16x32_bf16 v[116:119], v[142:145], v[202:205], v[116:119]
	v_mfma_f32_16x16x32_bf16 v[112:115], v[142:145], v[206:209], v[112:115]
	v_mfma_f32_16x16x32_bf16 v[108:111], v[146:149], v[194:197], v[108:111]
	v_mfma_f32_16x16x32_bf16 v[104:107], v[146:149], v[198:201], v[104:107]
	v_mfma_f32_16x16x32_bf16 v[100:103], v[146:149], v[202:205], v[100:103]
	v_mfma_f32_16x16x32_bf16 v[96:99], v[146:149], v[206:209], v[96:99]
	v_mfma_f32_16x16x32_bf16 v[92:95], v[150:153], v[194:197], v[92:95]
	v_mfma_f32_16x16x32_bf16 v[88:91], v[150:153], v[198:201], v[88:91]
	v_mfma_f32_16x16x32_bf16 v[84:87], v[150:153], v[202:205], v[84:87]
	v_mfma_f32_16x16x32_bf16 v[80:83], v[150:153], v[206:209], v[80:83]
	v_mfma_f32_16x16x32_bf16 v[76:79], v[154:157], v[194:197], v[76:79]
	v_mfma_f32_16x16x32_bf16 v[72:75], v[154:157], v[198:201], v[72:75]
	v_mfma_f32_16x16x32_bf16 v[68:71], v[154:157], v[202:205], v[68:71]
	v_mfma_f32_16x16x32_bf16 v[64:67], v[154:157], v[206:209], v[64:67]
	s_add_u32 s44, s44, 0x80
	s_addc_u32 s45, s45, 0
	s_add_i32 s43, s43, 1
	s_branch .Lg9_top
.Lg9_last:
	s_waitcnt lgkmcnt(0)
	v_mfma_f32_16x16x32_bf16 v[60:63], v[158:161], v[194:197], v[60:63]
	v_mfma_f32_16x16x32_bf16 v[56:59], v[158:161], v[198:201], v[56:59]
	v_mfma_f32_16x16x32_bf16 v[52:55], v[158:161], v[202:205], v[52:55]
	v_mfma_f32_16x16x32_bf16 v[48:51], v[158:161], v[206:209], v[48:51]
	s_waitcnt vmcnt(0)
	s_barrier
	s_xor_b32 s59, s59, 0x10000
	ds_read_b128 v[142:145], v212
	ds_read_b128 v[146:149], v212 offset:2048
	ds_read_b128 v[150:153], v212 offset:4096
	ds_read_b128 v[154:157], v212 offset:6144
	ds_read_b128 v[174:177], v214 offset:32768
	ds_read_b128 v[182:185], v214 offset:34816
	ds_read_b128 v[186:189], v214 offset:36864
	ds_read_b128 v[190:193], v214 offset:38912
	v_mfma_f32_16x16x32_bf16 v[44:47], v[162:165], v[194:197], v[44:47]
	v_mfma_f32_16x16x32_bf16 v[32:35], v[162:165], v[198:201], v[32:35]
	v_mfma_f32_16x16x32_bf16 v[28:31], v[162:165], v[202:205], v[28:31]
	v_mfma_f32_16x16x32_bf16 v[24:27], v[162:165], v[206:209], v[24:27]
	v_mfma_f32_16x16x32_bf16 v[20:23], v[166:169], v[194:197], v[20:23]
	v_mfma_f32_16x16x32_bf16 v[16:19], v[166:169], v[198:201], v[16:19]
	v_mfma_f32_16x16x32_bf16 v[12:15], v[166:169], v[202:205], v[12:15]
	v_mfma_f32_16x16x32_bf16 v[8:11], v[166:169], v[206:209], v[8:11]
	v_mfma_f32_16x16x32_bf16 v[4:7], v[170:173], v[194:197], v[4:7]
	v_mfma_f32_16x16x32_bf16 v[0:3], v[170:173], v[198:201], v[0:3]
	v_mfma_f32_16x16x32_bf16 v[40:43], v[170:173], v[202:205], v[40:43]
	v_mfma_f32_16x16x32_bf16 v[36:39], v[170:173], v[206:209], v[36:39]
	ds_read_b128 v[158:161], v212 offset:8192
	ds_read_b128 v[162:165], v212 offset:10240
	ds_read_b128 v[166:169], v212 offset:12288
	ds_read_b128 v[170:173], v212 offset:14336
	s_waitcnt lgkmcnt(4)
	v_mfma_f32_16x16x32_bf16 v[124:127], v[142:145], v[174:177], v[124:127]
	v_mfma_f32_16x16x32_bf16 v[120:123], v[142:145], v[182:185], v[120:123]
	v_mfma_f32_16x16x32_bf16 v[116:119], v[142:145], v[186:189], v[116:119]
	v_mfma_f32_16x16x32_bf16 v[112:115], v[142:145], v[190:193], v[112:115]
	v_mfma_f32_16x16x32_bf16 v[108:111], v[146:149], v[174:177], v[108:111]
	v_mfma_f32_16x16x32_bf16 v[104:107], v[146:149], v[182:185], v[104:107]
	v_mfma_f32_16x16x32_bf16 v[100:103], v[146:149], v[186:189], v[100:103]
	v_mfma_f32_16x16x32_bf16 v[96:99], v[146:149], v[190:193], v[96:99]
	v_mfma_f32_16x16x32_bf16 v[92:95], v[150:153], v[174:177], v[92:95]
	v_mfma_f32_16x16x32_bf16 v[88:91], v[150:153], v[182:185], v[88:91]
	v_mfma_f32_16x16x32_bf16 v[84:87], v[150:153], v[186:189], v[84:87]
	v_mfma_f32_16x16x32_bf16 v[80:83], v[150:153], v[190:193], v[80:83]
	v_mfma_f32_16x16x32_bf16 v[76:79], v[154:157], v[174:177], v[76:79]
	v_mfma_f32_16x16x32_bf16 v[72:75], v[154:157], v[182:185], v[72:75]
	v_mfma_f32_16x16x32_bf16 v[68:71], v[154:157], v[186:189], v[68:71]
	v_mfma_f32_16x16x32_bf16 v[64:67], v[154:157], v[190:193], v[64:67]
	ds_read_b128 v[142:145], v213
	ds_read_b128 v[146:149], v213 offset:2048
	ds_read_b128 v[150:153], v213 offset:4096
	ds_read_b128 v[154:157], v213 offset:6144
	ds_read_b128 v[194:197], v215 offset:32768
	ds_read_b128 v[198:201], v215 offset:34816
	ds_read_b128 v[202:205], v215 offset:36864
	ds_read_b128 v[206:209], v215 offset:38912
	s_waitcnt lgkmcnt(8)
	v_mfma_f32_16x16x32_bf16 v[60:63], v[158:161], v[174:177], v[60:63]
	v_mfma_f32_16x16x32_bf16 v[56:59], v[158:161], v[182:185], v[56:59]
	v_mfma_f32_16x16x32_bf16 v[52:55], v[158:161], v[186:189], v[52:55]
	v_mfma_f32_16x16x32_bf16 v[48:51], v[158:161], v[190:193], v[48:51]
	v_mfma_f32_16x16x32_bf16 v[44:47], v[162:165], v[174:177], v[44:47]
	v_mfma_f32_16x16x32_bf16 v[32:35], v[162:165], v[182:185], v[32:35]
	v_mfma_f32_16x16x32_bf16 v[28:31], v[162:165], v[186:189], v[28:31]
	v_mfma_f32_16x16x32_bf16 v[24:27], v[162:165], v[190:193], v[24:27]
	v_mfma_f32_16x16x32_bf16 v[20:23], v[166:169], v[174:177], v[20:23]
	v_mfma_f32_16x16x32_bf16 v[16:19], v[166:169], v[182:185], v[16:19]
	v_mfma_f32_16x16x32_bf16 v[12:15], v[166:169], v[186:189], v[12:15]
	v_mfma_f32_16x16x32_bf16 v[8:11], v[166:169], v[190:193], v[8:11]
	v_mfma_f32_16x16x32_bf16 v[4:7], v[170:173], v[174:177], v[4:7]
	v_mfma_f32_16x16x32_bf16 v[0:3], v[170:173], v[182:185], v[0:3]
	v_mfma_f32_16x16x32_bf16 v[40:43], v[170:173], v[186:189], v[40:43]
	v_mfma_f32_16x16x32_bf16 v[36:39], v[170:173], v[190:193], v[36:39]
	ds_read_b128 v[158:161], v213 offset:8192
	ds_read_b128 v[162:165], v213 offset:10240
	ds_read_b128 v[166:169], v213 offset:12288
	ds_read_b128 v[170:173], v213 offset:14336
	s_waitcnt lgkmcnt(4)
	v_mfma_f32_16x16x32_bf16 v[124:127], v[142:145], v[194:197], v[124:127]
	v_mfma_f32_16x16x32_bf16 v[120:123], v[142:145], v[198:201], v[120:123]
	v_mfma_f32_16x16x32_bf16 v[116:119], v[142:145], v[202:205], v[116:119]
	v_mfma_f32_16x16x32_bf16 v[112:115], v[142:145], v[206:209], v[112:115]
	v_mfma_f32_16x16x32_bf16 v[108:111], v[146:149], v[194:197], v[108:111]
	v_mfma_f32_16x16x32_bf16 v[104:107], v[146:149], v[198:201], v[104:107]
	v_mfma_f32_16x16x32_bf16 v[100:103], v[146:149], v[202:205], v[100:103]
	v_mfma_f32_16x16x32_bf16 v[96:99], v[146:149], v[206:209], v[96:99]
	v_mfma_f32_16x16x32_bf16 v[92:95], v[150:153], v[194:197], v[92:95]
	v_mfma_f32_16x16x32_bf16 v[88:91], v[150:153], v[198:201], v[88:91]
	v_mfma_f32_16x16x32_bf16 v[84:87], v[150:153], v[202:205], v[84:87]
	v_mfma_f32_16x16x32_bf16 v[80:83], v[150:153], v[206:209], v[80:83]
	v_mfma_f32_16x16x32_bf16 v[76:79], v[154:157], v[194:197], v[76:79]
	v_mfma_f32_16x16x32_bf16 v[72:75], v[154:157], v[198:201], v[72:75]
	v_mfma_f32_16x16x32_bf16 v[68:71], v[154:157], v[202:205], v[68:71]
	v_mfma_f32_16x16x32_bf16 v[64:67], v[154:157], v[206:209], v[64:67]
	s_add_u32 s44, s44, 0x80
	s_addc_u32 s45, s45, 0
	s_add_i32 s43, s43, 1
	s_waitcnt lgkmcnt(0)
	s_waitcnt vmcnt(0)
	s_barrier
	v_mfma_f32_16x16x32_bf16 v[60:63], v[158:161], v[194:197], v[60:63]
	v_mfma_f32_16x16x32_bf16 v[56:59], v[158:161], v[198:201], v[56:59]
	v_mfma_f32_16x16x32_bf16 v[52:55], v[158:161], v[202:205], v[52:55]
	v_mfma_f32_16x16x32_bf16 v[48:51], v[158:161], v[206:209], v[48:51]
	v_mfma_f32_16x16x32_bf16 v[44:47], v[162:165], v[194:197], v[44:47]
	v_mfma_f32_16x16x32_bf16 v[32:35], v[162:165], v[198:201], v[32:35]
	v_mfma_f32_16x16x32_bf16 v[28:31], v[162:165], v[202:205], v[28:31]
	v_mfma_f32_16x16x32_bf16 v[24:27], v[162:165], v[206:209], v[24:27]
	v_mfma_f32_16x16x32_bf16 v[20:23], v[166:169], v[194:197], v[20:23]
	v_mfma_f32_16x16x32_bf16 v[16:19], v[166:169], v[198:201], v[16:19]
	v_mfma_f32_16x16x32_bf16 v[12:15], v[166:169], v[202:205], v[12:15]
	v_mfma_f32_16x16x32_bf16 v[8:11], v[166:169], v[206:209], v[8:11]
	v_mfma_f32_16x16x32_bf16 v[4:7], v[170:173], v[194:197], v[4:7]
	v_mfma_f32_16x16x32_bf16 v[0:3], v[170:173], v[198:201], v[0:3]
	v_mfma_f32_16x16x32_bf16 v[40:43], v[170:173], v[202:205], v[40:43]
	v_mfma_f32_16x16x32_bf16 v[36:39], v[170:173], v[206:209], v[36:39]
	s_nop 7
	s_nop 7
	s_sub_u32 s44, s44, s34
	s_subb_u32 s45, s45, s35
	s_mov_b32 s59, 0x100000
	s_mov_b32 s60, 0x100000
	s_mov_b64 s[46:47], 0
	s_mov_b64 vcc, exec
	s_branch .LBB0_1330

.Lg10_top:
	s_waitcnt lgkmcnt(0)
	v_mfma_f32_16x16x32_bf16 v[60:63], v[172:175], v[206:209], v[60:63]
	v_mfma_f32_16x16x32_bf16 v[52:55], v[172:175], v[210:213], v[52:55]
	v_mfma_f32_16x16x32_bf16 v[56:59], v[172:175], v[214:217], v[56:59]
	v_mfma_f32_16x16x32_bf16 v[48:51], v[172:175], v[218:221], v[48:51]
	s_waitcnt vmcnt(0)
	s_barrier
	s_xor_b32 s57, s57, 0x10000
	s_mov_b32 m0, s57
	s_add_u32 s46, s44, s14
	s_addc_u32 s47, s45, s15
	global_load_lds_dwordx4 v144, s[46:47]
	ds_read_b128 v[156:159], v143
	ds_read_b128 v[160:163], v143 offset:2048
	ds_read_b128 v[164:167], v143 offset:4096
	ds_read_b128 v[168:171], v143 offset:6144
	ds_read_b128 v[190:193], v180 offset:32768
	ds_read_b128 v[194:197], v180 offset:34816
	ds_read_b128 v[198:201], v180 offset:36864
	ds_read_b128 v[202:205], v180 offset:38912
	v_mfma_f32_16x16x32_bf16 v[44:47], v[176:179], v[206:209], v[44:47]
	v_mfma_f32_16x16x32_bf16 v[36:39], v[176:179], v[210:213], v[36:39]
	s_add_u32 m0, s57, 0x2000
	s_add_u32 s46, s44, s16
	s_addc_u32 s47, s45, s17
	global_load_lds_dwordx4 v144, s[46:47]
	v_mfma_f32_16x16x32_bf16 v[40:43], v[176:179], v[214:217], v[40:43]
	v_mfma_f32_16x16x32_bf16 v[32:35], v[176:179], v[218:221], v[32:35]
	s_add_u32 m0, s57, 0x4000
	s_add_u32 s46, s44, s18
	s_addc_u32 s47, s45, s19
	global_load_lds_dwordx4 v144, s[46:47]
	v_mfma_f32_16x16x32_bf16 v[28:31], v[182:185], v[206:209], v[28:31]
	v_mfma_f32_16x16x32_bf16 v[16:19], v[182:185], v[210:213], v[16:19]
	s_add_u32 m0, s57, 0x6000
	s_add_u32 s46, s44, s22
	s_addc_u32 s47, s45, s23
	global_load_lds_dwordx4 v144, s[46:47]
	v_mfma_f32_16x16x32_bf16 v[24:27], v[182:185], v[214:217], v[24:27]
	v_mfma_f32_16x16x32_bf16 v[12:15], v[182:185], v[218:221], v[12:15]
	s_add_u32 m0, s57, 0x8000
	s_add_u32 s46, s44, s30
	s_addc_u32 s47, s45, s31
	global_load_lds_dwordx4 v145, s[46:47]
	v_mfma_f32_16x16x32_bf16 v[4:7], v[186:189], v[206:209], v[4:7]
	v_mfma_f32_16x16x32_bf16 v[0:3], v[186:189], v[210:213], v[0:3]
	s_add_u32 m0, s57, 0xa000
	s_add_u32 s46, s44, s36
	s_addc_u32 s47, s45, s37
	global_load_lds_dwordx4 v145, s[46:47]
	v_mfma_f32_16x16x32_bf16 v[20:23], v[186:189], v[214:217], v[20:23]
	v_mfma_f32_16x16x32_bf16 v[8:11], v[186:189], v[218:221], v[8:11]
	s_add_u32 m0, s57, 0xc000
	s_add_u32 s46, s44, s38
	s_addc_u32 s47, s45, s39
	global_load_lds_dwordx4 v145, s[46:47]
.Lg10_entry:
	ds_read_b128 v[172:175], v143 offset:8192
	ds_read_b128 v[176:179], v143 offset:10240
	ds_read_b128 v[182:185], v143 offset:12288
	ds_read_b128 v[186:189], v143 offset:14336
	s_waitcnt lgkmcnt(4)
	v_mfma_f32_16x16x32_bf16 v[124:127], v[156:159], v[190:193], v[124:127]
	v_mfma_f32_16x16x32_bf16 v[116:119], v[156:159], v[194:197], v[116:119]
	s_add_u32 m0, s57, 0xe000
	s_add_u32 s46, s44, s40
	s_addc_u32 s47, s45, s41
	global_load_lds_dwordx4 v145, s[46:47]
	v_mfma_f32_16x16x32_bf16 v[120:123], v[156:159], v[198:201], v[120:123]
	v_mfma_f32_16x16x32_bf16 v[112:115], v[156:159], v[202:205], v[112:115]
	v_mfma_f32_16x16x32_bf16 v[108:111], v[160:163], v[190:193], v[108:111]
	v_mfma_f32_16x16x32_bf16 v[100:103], v[160:163], v[194:197], v[100:103]
	v_mfma_f32_16x16x32_bf16 v[104:107], v[160:163], v[198:201], v[104:107]
	v_mfma_f32_16x16x32_bf16 v[96:99], v[160:163], v[202:205], v[96:99]
	v_mfma_f32_16x16x32_bf16 v[92:95], v[164:167], v[190:193], v[92:95]
	v_mfma_f32_16x16x32_bf16 v[84:87], v[164:167], v[194:197], v[84:87]
	v_mfma_f32_16x16x32_bf16 v[88:91], v[164:167], v[198:201], v[88:91]
	v_mfma_f32_16x16x32_bf16 v[80:83], v[164:167], v[202:205], v[80:83]
	v_mfma_f32_16x16x32_bf16 v[76:79], v[168:171], v[190:193], v[76:79]
	v_mfma_f32_16x16x32_bf16 v[68:71], v[168:171], v[194:197], v[68:71]
	v_mfma_f32_16x16x32_bf16 v[72:75], v[168:171], v[198:201], v[72:75]
	v_mfma_f32_16x16x32_bf16 v[64:67], v[168:171], v[202:205], v[64:67]
	ds_read_b128 v[156:159], v155
	ds_read_b128 v[160:163], v155 offset:2048
	ds_read_b128 v[164:167], v155 offset:4096
	ds_read_b128 v[168:171], v155 offset:6144
	ds_read_b128 v[206:209], v222 offset:32768
	ds_read_b128 v[210:213], v222 offset:34816
	ds_read_b128 v[214:217], v222 offset:36864
	ds_read_b128 v[218:221], v222 offset:38912
	s_waitcnt lgkmcnt(8)
	v_mfma_f32_16x16x32_bf16 v[60:63], v[172:175], v[190:193], v[60:63]
	v_mfma_f32_16x16x32_bf16 v[52:55], v[172:175], v[194:197], v[52:55]
	v_mfma_f32_16x16x32_bf16 v[56:59], v[172:175], v[198:201], v[56:59]
	v_mfma_f32_16x16x32_bf16 v[48:51], v[172:175], v[202:205], v[48:51]
	v_mfma_f32_16x16x32_bf16 v[44:47], v[176:179], v[190:193], v[44:47]
	v_mfma_f32_16x16x32_bf16 v[36:39], v[176:179], v[194:197], v[36:39]
	v_mfma_f32_16x16x32_bf16 v[40:43], v[176:179], v[198:201], v[40:43]
	v_mfma_f32_16x16x32_bf16 v[32:35], v[176:179], v[202:205], v[32:35]
	v_mfma_f32_16x16x32_bf16 v[28:31], v[182:185], v[190:193], v[28:31]
	v_mfma_f32_16x16x32_bf16 v[16:19], v[182:185], v[194:197], v[16:19]
	v_mfma_f32_16x16x32_bf16 v[24:27], v[182:185], v[198:201], v[24:27]
	v_mfma_f32_16x16x32_bf16 v[12:15], v[182:185], v[202:205], v[12:15]
	v_mfma_f32_16x16x32_bf16 v[4:7], v[186:189], v[190:193], v[4:7]
	v_mfma_f32_16x16x32_bf16 v[0:3], v[186:189], v[194:197], v[0:3]
	v_mfma_f32_16x16x32_bf16 v[20:23], v[186:189], v[198:201], v[20:23]
	v_mfma_f32_16x16x32_bf16 v[8:11], v[186:189], v[202:205], v[8:11]
	ds_read_b128 v[172:175], v155 offset:8192
	ds_read_b128 v[176:179], v155 offset:10240
	ds_read_b128 v[182:185], v155 offset:12288
	ds_read_b128 v[186:189], v155 offset:14336
	s_waitcnt lgkmcnt(4)
	v_mfma_f32_16x16x32_bf16 v[124:127], v[156:159], v[206:209], v[124:127]
	v_mfma_f32_16x16x32_bf16 v[116:119], v[156:159], v[210:213], v[116:119]
	v_mfma_f32_16x16x32_bf16 v[120:123], v[156:159], v[214:217], v[120:123]
	v_mfma_f32_16x16x32_bf16 v[112:115], v[156:159], v[218:221], v[112:115]
	v_mfma_f32_16x16x32_bf16 v[108:111], v[160:163], v[206:209], v[108:111]
	v_mfma_f32_16x16x32_bf16 v[100:103], v[160:163], v[210:213], v[100:103]
	v_mfma_f32_16x16x32_bf16 v[104:107], v[160:163], v[214:217], v[104:107]
	v_mfma_f32_16x16x32_bf16 v[96:99], v[160:163], v[218:221], v[96:99]
	v_mfma_f32_16x16x32_bf16 v[92:95], v[164:167], v[206:209], v[92:95]
	v_mfma_f32_16x16x32_bf16 v[84:87], v[164:167], v[210:213], v[84:87]
	v_mfma_f32_16x16x32_bf16 v[88:91], v[164:167], v[214:217], v[88:91]
	v_mfma_f32_16x16x32_bf16 v[80:83], v[164:167], v[218:221], v[80:83]
	v_mfma_f32_16x16x32_bf16 v[76:79], v[168:171], v[206:209], v[76:79]
	v_mfma_f32_16x16x32_bf16 v[68:71], v[168:171], v[210:213], v[68:71]
	v_mfma_f32_16x16x32_bf16 v[72:75], v[168:171], v[214:217], v[72:75]
	v_mfma_f32_16x16x32_bf16 v[64:67], v[168:171], v[218:221], v[64:67]
	s_add_u32 s44, s44, 0x80
	s_addc_u32 s45, s45, 0
	s_add_i32 s43, s43, 1
	s_cmp_lt_u32 s43, 15
	s_cbranch_scc0 .Lg10_last
	s_waitcnt lgkmcnt(0)
	v_mfma_f32_16x16x32_bf16 v[60:63], v[172:175], v[206:209], v[60:63]
	v_mfma_f32_16x16x32_bf16 v[52:55], v[172:175], v[210:213], v[52:55]
	v_mfma_f32_16x16x32_bf16 v[56:59], v[172:175], v[214:217], v[56:59]
	v_mfma_f32_16x16x32_bf16 v[48:51], v[172:175], v[218:221], v[48:51]
	s_waitcnt vmcnt(0)
	s_barrier
	s_xor_b32 s57, s57, 0x10000
	s_mov_b32 m0, s57
	s_add_u32 s46, s44, s14
	s_addc_u32 s47, s45, s15
	global_load_lds_dwordx4 v144, s[46:47]
	ds_read_b128 v[156:159], v223
	ds_read_b128 v[160:163], v223 offset:2048
	ds_read_b128 v[164:167], v223 offset:4096
	ds_read_b128 v[168:171], v223 offset:6144
	ds_read_b128 v[190:193], v225 offset:32768
	ds_read_b128 v[194:197], v225 offset:34816
	ds_read_b128 v[198:201], v225 offset:36864
	ds_read_b128 v[202:205], v225 offset:38912
	v_mfma_f32_16x16x32_bf16 v[44:47], v[176:179], v[206:209], v[44:47]
	v_mfma_f32_16x16x32_bf16 v[36:39], v[176:179], v[210:213], v[36:39]
	s_add_u32 m0, s57, 0x2000
	s_add_u32 s46, s44, s16
	s_addc_u32 s47, s45, s17
	global_load_lds_dwordx4 v144, s[46:47]
	v_mfma_f32_16x16x32_bf16 v[40:43], v[176:179], v[214:217], v[40:43]
	v_mfma_f32_16x16x32_bf16 v[32:35], v[176:179], v[218:221], v[32:35]
	s_add_u32 m0, s57, 0x4000
	s_add_u32 s46, s44, s18
	s_addc_u32 s47, s45, s19
	global_load_lds_dwordx4 v144, s[46:47]
	v_mfma_f32_16x16x32_bf16 v[28:31], v[182:185], v[206:209], v[28:31]
	v_mfma_f32_16x16x32_bf16 v[16:19], v[182:185], v[210:213], v[16:19]
	s_add_u32 m0, s57, 0x6000
	s_add_u32 s46, s44, s22
	s_addc_u32 s47, s45, s23
	global_load_lds_dwordx4 v144, s[46:47]
	v_mfma_f32_16x16x32_bf16 v[24:27], v[182:185], v[214:217], v[24:27]
	v_mfma_f32_16x16x32_bf16 v[12:15], v[182:185], v[218:221], v[12:15]
	s_add_u32 m0, s57, 0x8000
	s_add_u32 s46, s44, s30
	s_addc_u32 s47, s45, s31
	global_load_lds_dwordx4 v145, s[46:47]
	v_mfma_f32_16x16x32_bf16 v[4:7], v[186:189], v[206:209], v[4:7]
	v_mfma_f32_16x16x32_bf16 v[0:3], v[186:189], v[210:213], v[0:3]
	s_add_u32 m0, s57, 0xa000
	s_add_u32 s46, s44, s36
	s_addc_u32 s47, s45, s37
	global_load_lds_dwordx4 v145, s[46:47]
	v_mfma_f32_16x16x32_bf16 v[20:23], v[186:189], v[214:217], v[20:23]
	v_mfma_f32_16x16x32_bf16 v[8:11], v[186:189], v[218:221], v[8:11]
	s_add_u32 m0, s57, 0xc000
	s_add_u32 s46, s44, s38
	s_addc_u32 s47, s45, s39
	global_load_lds_dwordx4 v145, s[46:47]
	ds_read_b128 v[172:175], v223 offset:8192
	ds_read_b128 v[176:179], v223 offset:10240
	ds_read_b128 v[182:185], v223 offset:12288
	ds_read_b128 v[186:189], v223 offset:14336
	s_waitcnt lgkmcnt(4)
	v_mfma_f32_16x16x32_bf16 v[124:127], v[156:159], v[190:193], v[124:127]
	v_mfma_f32_16x16x32_bf16 v[116:119], v[156:159], v[194:197], v[116:119]
	s_add_u32 m0, s57, 0xe000
	s_add_u32 s46, s44, s40
	s_addc_u32 s47, s45, s41
	global_load_lds_dwordx4 v145, s[46:47]
	v_mfma_f32_16x16x32_bf16 v[120:123], v[156:159], v[198:201], v[120:123]
	v_mfma_f32_16x16x32_bf16 v[112:115], v[156:159], v[202:205], v[112:115]
	v_mfma_f32_16x16x32_bf16 v[108:111], v[160:163], v[190:193], v[108:111]
	v_mfma_f32_16x16x32_bf16 v[100:103], v[160:163], v[194:197], v[100:103]
	v_mfma_f32_16x16x32_bf16 v[104:107], v[160:163], v[198:201], v[104:107]
	v_mfma_f32_16x16x32_bf16 v[96:99], v[160:163], v[202:205], v[96:99]
	v_mfma_f32_16x16x32_bf16 v[92:95], v[164:167], v[190:193], v[92:95]
	v_mfma_f32_16x16x32_bf16 v[84:87], v[164:167], v[194:197], v[84:87]
	v_mfma_f32_16x16x32_bf16 v[88:91], v[164:167], v[198:201], v[88:91]
	v_mfma_f32_16x16x32_bf16 v[80:83], v[164:167], v[202:205], v[80:83]
	v_mfma_f32_16x16x32_bf16 v[76:79], v[168:171], v[190:193], v[76:79]
	v_mfma_f32_16x16x32_bf16 v[68:71], v[168:171], v[194:197], v[68:71]
	v_mfma_f32_16x16x32_bf16 v[72:75], v[168:171], v[198:201], v[72:75]
	v_mfma_f32_16x16x32_bf16 v[64:67], v[168:171], v[202:205], v[64:67]
	ds_read_b128 v[156:159], v224
	ds_read_b128 v[160:163], v224 offset:2048
	ds_read_b128 v[164:167], v224 offset:4096
	ds_read_b128 v[168:171], v224 offset:6144
	ds_read_b128 v[206:209], v226 offset:32768
	ds_read_b128 v[210:213], v226 offset:34816
	ds_read_b128 v[214:217], v226 offset:36864
	ds_read_b128 v[218:221], v226 offset:38912
	s_waitcnt lgkmcnt(8)
	v_mfma_f32_16x16x32_bf16 v[60:63], v[172:175], v[190:193], v[60:63]
	v_mfma_f32_16x16x32_bf16 v[52:55], v[172:175], v[194:197], v[52:55]
	v_mfma_f32_16x16x32_bf16 v[56:59], v[172:175], v[198:201], v[56:59]
	v_mfma_f32_16x16x32_bf16 v[48:51], v[172:175], v[202:205], v[48:51]
	v_mfma_f32_16x16x32_bf16 v[44:47], v[176:179], v[190:193], v[44:47]
	v_mfma_f32_16x16x32_bf16 v[36:39], v[176:179], v[194:197], v[36:39]
	v_mfma_f32_16x16x32_bf16 v[40:43], v[176:179], v[198:201], v[40:43]
	v_mfma_f32_16x16x32_bf16 v[32:35], v[176:179], v[202:205], v[32:35]
	v_mfma_f32_16x16x32_bf16 v[28:31], v[182:185], v[190:193], v[28:31]
	v_mfma_f32_16x16x32_bf16 v[16:19], v[182:185], v[194:197], v[16:19]
	v_mfma_f32_16x16x32_bf16 v[24:27], v[182:185], v[198:201], v[24:27]
	v_mfma_f32_16x16x32_bf16 v[12:15], v[182:185], v[202:205], v[12:15]
	v_mfma_f32_16x16x32_bf16 v[4:7], v[186:189], v[190:193], v[4:7]
	v_mfma_f32_16x16x32_bf16 v[0:3], v[186:189], v[194:197], v[0:3]
	v_mfma_f32_16x16x32_bf16 v[20:23], v[186:189], v[198:201], v[20:23]
	v_mfma_f32_16x16x32_bf16 v[8:11], v[186:189], v[202:205], v[8:11]
	ds_read_b128 v[172:175], v224 offset:8192
	ds_read_b128 v[176:179], v224 offset:10240
	ds_read_b128 v[182:185], v224 offset:12288
	ds_read_b128 v[186:189], v224 offset:14336
	s_waitcnt lgkmcnt(4)
	v_mfma_f32_16x16x32_bf16 v[124:127], v[156:159], v[206:209], v[124:127]
	v_mfma_f32_16x16x32_bf16 v[116:119], v[156:159], v[210:213], v[116:119]
	v_mfma_f32_16x16x32_bf16 v[120:123], v[156:159], v[214:217], v[120:123]
	v_mfma_f32_16x16x32_bf16 v[112:115], v[156:159], v[218:221], v[112:115]
	v_mfma_f32_16x16x32_bf16 v[108:111], v[160:163], v[206:209], v[108:111]
	v_mfma_f32_16x16x32_bf16 v[100:103], v[160:163], v[210:213], v[100:103]
	v_mfma_f32_16x16x32_bf16 v[104:107], v[160:163], v[214:217], v[104:107]
	v_mfma_f32_16x16x32_bf16 v[96:99], v[160:163], v[218:221], v[96:99]
	v_mfma_f32_16x16x32_bf16 v[92:95], v[164:167], v[206:209], v[92:95]
	v_mfma_f32_16x16x32_bf16 v[84:87], v[164:167], v[210:213], v[84:87]
	v_mfma_f32_16x16x32_bf16 v[88:91], v[164:167], v[214:217], v[88:91]
	v_mfma_f32_16x16x32_bf16 v[80:83], v[164:167], v[218:221], v[80:83]
	v_mfma_f32_16x16x32_bf16 v[76:79], v[168:171], v[206:209], v[76:79]
	v_mfma_f32_16x16x32_bf16 v[68:71], v[168:171], v[210:213], v[68:71]
	v_mfma_f32_16x16x32_bf16 v[72:75], v[168:171], v[214:217], v[72:75]
	v_mfma_f32_16x16x32_bf16 v[64:67], v[168:171], v[218:221], v[64:67]
	s_add_u32 s44, s44, 0x80
	s_addc_u32 s45, s45, 0
	s_add_i32 s43, s43, 1
	s_branch .Lg10_top
.Lg10_last:
	s_waitcnt lgkmcnt(0)
	v_mfma_f32_16x16x32_bf16 v[60:63], v[172:175], v[206:209], v[60:63]
	v_mfma_f32_16x16x32_bf16 v[52:55], v[172:175], v[210:213], v[52:55]
	v_mfma_f32_16x16x32_bf16 v[56:59], v[172:175], v[214:217], v[56:59]
	v_mfma_f32_16x16x32_bf16 v[48:51], v[172:175], v[218:221], v[48:51]
	s_waitcnt vmcnt(0)
	s_barrier
	s_xor_b32 s57, s57, 0x10000
	ds_read_b128 v[156:159], v223
	ds_read_b128 v[160:163], v223 offset:2048
	ds_read_b128 v[164:167], v223 offset:4096
	ds_read_b128 v[168:171], v223 offset:6144
	ds_read_b128 v[190:193], v225 offset:32768
	ds_read_b128 v[194:197], v225 offset:34816
	ds_read_b128 v[198:201], v225 offset:36864
	ds_read_b128 v[202:205], v225 offset:38912
	v_mfma_f32_16x16x32_bf16 v[44:47], v[176:179], v[206:209], v[44:47]
	v_mfma_f32_16x16x32_bf16 v[36:39], v[176:179], v[210:213], v[36:39]
	v_mfma_f32_16x16x32_bf16 v[40:43], v[176:179], v[214:217], v[40:43]
	v_mfma_f32_16x16x32_bf16 v[32:35], v[176:179], v[218:221], v[32:35]
	v_mfma_f32_16x16x32_bf16 v[28:31], v[182:185], v[206:209], v[28:31]
	v_mfma_f32_16x16x32_bf16 v[16:19], v[182:185], v[210:213], v[16:19]
	v_mfma_f32_16x16x32_bf16 v[24:27], v[182:185], v[214:217], v[24:27]
	v_mfma_f32_16x16x32_bf16 v[12:15], v[182:185], v[218:221], v[12:15]
	v_mfma_f32_16x16x32_bf16 v[4:7], v[186:189], v[206:209], v[4:7]
	v_mfma_f32_16x16x32_bf16 v[0:3], v[186:189], v[210:213], v[0:3]
	v_mfma_f32_16x16x32_bf16 v[20:23], v[186:189], v[214:217], v[20:23]
	v_mfma_f32_16x16x32_bf16 v[8:11], v[186:189], v[218:221], v[8:11]
	ds_read_b128 v[172:175], v223 offset:8192
	ds_read_b128 v[176:179], v223 offset:10240
	ds_read_b128 v[182:185], v223 offset:12288
	ds_read_b128 v[186:189], v223 offset:14336
	s_waitcnt lgkmcnt(4)
	v_mfma_f32_16x16x32_bf16 v[124:127], v[156:159], v[190:193], v[124:127]
	v_mfma_f32_16x16x32_bf16 v[116:119], v[156:159], v[194:197], v[116:119]
	v_mfma_f32_16x16x32_bf16 v[120:123], v[156:159], v[198:201], v[120:123]
	v_mfma_f32_16x16x32_bf16 v[112:115], v[156:159], v[202:205], v[112:115]
	v_mfma_f32_16x16x32_bf16 v[108:111], v[160:163], v[190:193], v[108:111]
	v_mfma_f32_16x16x32_bf16 v[100:103], v[160:163], v[194:197], v[100:103]
	v_mfma_f32_16x16x32_bf16 v[104:107], v[160:163], v[198:201], v[104:107]
	v_mfma_f32_16x16x32_bf16 v[96:99], v[160:163], v[202:205], v[96:99]
	v_mfma_f32_16x16x32_bf16 v[92:95], v[164:167], v[190:193], v[92:95]
	v_mfma_f32_16x16x32_bf16 v[84:87], v[164:167], v[194:197], v[84:87]
	v_mfma_f32_16x16x32_bf16 v[88:91], v[164:167], v[198:201], v[88:91]
	v_mfma_f32_16x16x32_bf16 v[80:83], v[164:167], v[202:205], v[80:83]
	v_mfma_f32_16x16x32_bf16 v[76:79], v[168:171], v[190:193], v[76:79]
	v_mfma_f32_16x16x32_bf16 v[68:71], v[168:171], v[194:197], v[68:71]
	v_mfma_f32_16x16x32_bf16 v[72:75], v[168:171], v[198:201], v[72:75]
	v_mfma_f32_16x16x32_bf16 v[64:67], v[168:171], v[202:205], v[64:67]
	ds_read_b128 v[156:159], v224
	ds_read_b128 v[160:163], v224 offset:2048
	ds_read_b128 v[164:167], v224 offset:4096
	ds_read_b128 v[168:171], v224 offset:6144
	ds_read_b128 v[206:209], v226 offset:32768
	ds_read_b128 v[210:213], v226 offset:34816
	ds_read_b128 v[214:217], v226 offset:36864
	ds_read_b128 v[218:221], v226 offset:38912
	s_waitcnt lgkmcnt(8)
	v_mfma_f32_16x16x32_bf16 v[60:63], v[172:175], v[190:193], v[60:63]
	v_mfma_f32_16x16x32_bf16 v[52:55], v[172:175], v[194:197], v[52:55]
	v_mfma_f32_16x16x32_bf16 v[56:59], v[172:175], v[198:201], v[56:59]
	v_mfma_f32_16x16x32_bf16 v[48:51], v[172:175], v[202:205], v[48:51]
	v_mfma_f32_16x16x32_bf16 v[44:47], v[176:179], v[190:193], v[44:47]
	v_mfma_f32_16x16x32_bf16 v[36:39], v[176:179], v[194:197], v[36:39]
	v_mfma_f32_16x16x32_bf16 v[40:43], v[176:179], v[198:201], v[40:43]
	v_mfma_f32_16x16x32_bf16 v[32:35], v[176:179], v[202:205], v[32:35]
	v_mfma_f32_16x16x32_bf16 v[28:31], v[182:185], v[190:193], v[28:31]
	v_mfma_f32_16x16x32_bf16 v[16:19], v[182:185], v[194:197], v[16:19]
	v_mfma_f32_16x16x32_bf16 v[24:27], v[182:185], v[198:201], v[24:27]
	v_mfma_f32_16x16x32_bf16 v[12:15], v[182:185], v[202:205], v[12:15]
	v_mfma_f32_16x16x32_bf16 v[4:7], v[186:189], v[190:193], v[4:7]
	v_mfma_f32_16x16x32_bf16 v[0:3], v[186:189], v[194:197], v[0:3]
	v_mfma_f32_16x16x32_bf16 v[20:23], v[186:189], v[198:201], v[20:23]
	v_mfma_f32_16x16x32_bf16 v[8:11], v[186:189], v[202:205], v[8:11]
	ds_read_b128 v[172:175], v224 offset:8192
	ds_read_b128 v[176:179], v224 offset:10240
	ds_read_b128 v[182:185], v224 offset:12288
	ds_read_b128 v[186:189], v224 offset:14336
	s_waitcnt lgkmcnt(4)
	v_mfma_f32_16x16x32_bf16 v[124:127], v[156:159], v[206:209], v[124:127]
	v_mfma_f32_16x16x32_bf16 v[116:119], v[156:159], v[210:213], v[116:119]
	v_mfma_f32_16x16x32_bf16 v[120:123], v[156:159], v[214:217], v[120:123]
	v_mfma_f32_16x16x32_bf16 v[112:115], v[156:159], v[218:221], v[112:115]
	v_mfma_f32_16x16x32_bf16 v[108:111], v[160:163], v[206:209], v[108:111]
	v_mfma_f32_16x16x32_bf16 v[100:103], v[160:163], v[210:213], v[100:103]
	v_mfma_f32_16x16x32_bf16 v[104:107], v[160:163], v[214:217], v[104:107]
	v_mfma_f32_16x16x32_bf16 v[96:99], v[160:163], v[218:221], v[96:99]
	v_mfma_f32_16x16x32_bf16 v[92:95], v[164:167], v[206:209], v[92:95]
	v_mfma_f32_16x16x32_bf16 v[84:87], v[164:167], v[210:213], v[84:87]
	v_mfma_f32_16x16x32_bf16 v[88:91], v[164:167], v[214:217], v[88:91]
	v_mfma_f32_16x16x32_bf16 v[80:83], v[164:167], v[218:221], v[80:83]
	v_mfma_f32_16x16x32_bf16 v[76:79], v[168:171], v[206:209], v[76:79]
	v_mfma_f32_16x16x32_bf16 v[68:71], v[168:171], v[210:213], v[68:71]
	v_mfma_f32_16x16x32_bf16 v[72:75], v[168:171], v[214:217], v[72:75]
	v_mfma_f32_16x16x32_bf16 v[64:67], v[168:171], v[218:221], v[64:67]
	s_add_u32 s44, s44, 0x80
	s_addc_u32 s45, s45, 0
	s_add_i32 s43, s43, 1
	s_waitcnt lgkmcnt(0)
	s_waitcnt vmcnt(0)
	s_barrier
	v_mfma_f32_16x16x32_bf16 v[60:63], v[172:175], v[206:209], v[60:63]
	v_mfma_f32_16x16x32_bf16 v[52:55], v[172:175], v[210:213], v[52:55]
	v_mfma_f32_16x16x32_bf16 v[56:59], v[172:175], v[214:217], v[56:59]
	v_mfma_f32_16x16x32_bf16 v[48:51], v[172:175], v[218:221], v[48:51]
	v_mfma_f32_16x16x32_bf16 v[44:47], v[176:179], v[206:209], v[44:47]
	v_mfma_f32_16x16x32_bf16 v[36:39], v[176:179], v[210:213], v[36:39]
	v_mfma_f32_16x16x32_bf16 v[40:43], v[176:179], v[214:217], v[40:43]
	v_mfma_f32_16x16x32_bf16 v[32:35], v[176:179], v[218:221], v[32:35]
	v_mfma_f32_16x16x32_bf16 v[28:31], v[182:185], v[206:209], v[28:31]
	v_mfma_f32_16x16x32_bf16 v[16:19], v[182:185], v[210:213], v[16:19]
	v_mfma_f32_16x16x32_bf16 v[24:27], v[182:185], v[214:217], v[24:27]
	v_mfma_f32_16x16x32_bf16 v[12:15], v[182:185], v[218:221], v[12:15]
	v_mfma_f32_16x16x32_bf16 v[4:7], v[186:189], v[206:209], v[4:7]
	v_mfma_f32_16x16x32_bf16 v[0:3], v[186:189], v[210:213], v[0:3]
	v_mfma_f32_16x16x32_bf16 v[20:23], v[186:189], v[214:217], v[20:23]
	v_mfma_f32_16x16x32_bf16 v[8:11], v[186:189], v[218:221], v[8:11]
	s_nop 7
	s_nop 7
	s_sub_u32 s44, s44, s34
	s_subb_u32 s45, s45, s35
	s_mov_b32 s57, 0x80000
	s_mov_b32 s58, 0x80000
	s_mov_b64 s[46:47], 0
	s_mov_b64 vcc, exec
	s_branch .LBB0_1494

.Lg11_top:
	s_waitcnt lgkmcnt(0)
	v_mfma_f32_16x16x32_bf16 v[60:63], v[158:161], v[194:197], v[60:63]
	v_mfma_f32_16x16x32_bf16 v[56:59], v[158:161], v[198:201], v[56:59]
	v_mfma_f32_16x16x32_bf16 v[52:55], v[158:161], v[202:205], v[52:55]
	v_mfma_f32_16x16x32_bf16 v[48:51], v[158:161], v[206:209], v[48:51]
	s_waitcnt vmcnt(0)
	s_barrier
	s_xor_b32 s45, s45, 0x10000
	s_mov_b32 m0, s45
	s_add_u32 s38, s36, s12
	s_addc_u32 s39, s37, s13
	global_load_lds_dwordx4 v178, s[38:39]
	ds_read_b128 v[142:145], v141
	ds_read_b128 v[146:149], v141 offset:2048
	ds_read_b128 v[150:153], v141 offset:4096
	ds_read_b128 v[154:157], v141 offset:6144
	ds_read_b128 v[174:177], v210 offset:32768
	ds_read_b128 v[182:185], v210 offset:34816
	ds_read_b128 v[186:189], v210 offset:36864
	ds_read_b128 v[190:193], v210 offset:38912
	v_mfma_f32_16x16x32_bf16 v[44:47], v[162:165], v[194:197], v[44:47]
	v_mfma_f32_16x16x32_bf16 v[32:35], v[162:165], v[198:201], v[32:35]
	s_add_u32 m0, s45, 0x2000
	s_add_u32 s38, s36, s14
	s_addc_u32 s39, s37, s15
	global_load_lds_dwordx4 v178, s[38:39]
	v_mfma_f32_16x16x32_bf16 v[28:31], v[162:165], v[202:205], v[28:31]
	v_mfma_f32_16x16x32_bf16 v[24:27], v[162:165], v[206:209], v[24:27]
	s_add_u32 m0, s45, 0x4000
	s_add_u32 s38, s36, s16
	s_addc_u32 s39, s37, s17
	global_load_lds_dwordx4 v178, s[38:39]
	v_mfma_f32_16x16x32_bf16 v[20:23], v[166:169], v[194:197], v[20:23]
	v_mfma_f32_16x16x32_bf16 v[16:19], v[166:169], v[198:201], v[16:19]
	s_add_u32 m0, s45, 0x6000
	s_add_u32 s38, s36, s18
	s_addc_u32 s39, s37, s19
	global_load_lds_dwordx4 v178, s[38:39]
	v_mfma_f32_16x16x32_bf16 v[12:15], v[166:169], v[202:205], v[12:15]
	v_mfma_f32_16x16x32_bf16 v[8:11], v[166:169], v[206:209], v[8:11]
	s_add_u32 m0, s45, 0x8000
	s_add_u32 s38, s36, s22
	s_addc_u32 s39, s37, s23
	global_load_lds_dwordx4 v179, s[38:39]
	v_mfma_f32_16x16x32_bf16 v[4:7], v[170:173], v[194:197], v[4:7]
	v_mfma_f32_16x16x32_bf16 v[0:3], v[170:173], v[198:201], v[0:3]
	s_add_u32 m0, s45, 0xa000
	s_add_u32 s38, s36, s24
	s_addc_u32 s39, s37, s25
	global_load_lds_dwordx4 v179, s[38:39]
	v_mfma_f32_16x16x32_bf16 v[40:43], v[170:173], v[202:205], v[40:43]
	v_mfma_f32_16x16x32_bf16 v[36:39], v[170:173], v[206:209], v[36:39]
	s_add_u32 m0, s45, 0xc000
	s_add_u32 s38, s36, s26
	s_addc_u32 s39, s37, s27
	global_load_lds_dwordx4 v179, s[38:39]
.Lg11_entry:
	ds_read_b128 v[158:161], v141 offset:8192
	ds_read_b128 v[162:165], v141 offset:10240
	ds_read_b128 v[166:169], v141 offset:12288
	ds_read_b128 v[170:173], v141 offset:14336
	s_waitcnt lgkmcnt(4)
	v_mfma_f32_16x16x32_bf16 v[124:127], v[142:145], v[174:177], v[124:127]
	v_mfma_f32_16x16x32_bf16 v[120:123], v[142:145], v[182:185], v[120:123]
	s_add_u32 m0, s45, 0xe000
	s_add_u32 s38, s36, s28
	s_addc_u32 s39, s37, s29
	global_load_lds_dwordx4 v179, s[38:39]
	v_mfma_f32_16x16x32_bf16 v[116:119], v[142:145], v[186:189], v[116:119]
	v_mfma_f32_16x16x32_bf16 v[112:115], v[142:145], v[190:193], v[112:115]
	v_mfma_f32_16x16x32_bf16 v[108:111], v[146:149], v[174:177], v[108:111]
	v_mfma_f32_16x16x32_bf16 v[104:107], v[146:149], v[182:185], v[104:107]
	v_mfma_f32_16x16x32_bf16 v[100:103], v[146:149], v[186:189], v[100:103]
	v_mfma_f32_16x16x32_bf16 v[96:99], v[146:149], v[190:193], v[96:99]
	v_mfma_f32_16x16x32_bf16 v[92:95], v[150:153], v[174:177], v[92:95]
	v_mfma_f32_16x16x32_bf16 v[88:91], v[150:153], v[182:185], v[88:91]
	v_mfma_f32_16x16x32_bf16 v[84:87], v[150:153], v[186:189], v[84:87]
	v_mfma_f32_16x16x32_bf16 v[80:83], v[150:153], v[190:193], v[80:83]
	v_mfma_f32_16x16x32_bf16 v[76:79], v[154:157], v[174:177], v[76:79]
	v_mfma_f32_16x16x32_bf16 v[72:75], v[154:157], v[182:185], v[72:75]
	v_mfma_f32_16x16x32_bf16 v[68:71], v[154:157], v[186:189], v[68:71]
	v_mfma_f32_16x16x32_bf16 v[64:67], v[154:157], v[190:193], v[64:67]
	ds_read_b128 v[142:145], v180
	ds_read_b128 v[146:149], v180 offset:2048
	ds_read_b128 v[150:153], v180 offset:4096
	ds_read_b128 v[154:157], v180 offset:6144
	ds_read_b128 v[194:197], v211 offset:32768
	ds_read_b128 v[198:201], v211 offset:34816
	ds_read_b128 v[202:205], v211 offset:36864
	ds_read_b128 v[206:209], v211 offset:38912
	s_waitcnt lgkmcnt(8)
	v_mfma_f32_16x16x32_bf16 v[60:63], v[158:161], v[174:177], v[60:63]
	v_mfma_f32_16x16x32_bf16 v[56:59], v[158:161], v[182:185], v[56:59]
	v_mfma_f32_16x16x32_bf16 v[52:55], v[158:161], v[186:189], v[52:55]
	v_mfma_f32_16x16x32_bf16 v[48:51], v[158:161], v[190:193], v[48:51]
	v_mfma_f32_16x16x32_bf16 v[44:47], v[162:165], v[174:177], v[44:47]
	v_mfma_f32_16x16x32_bf16 v[32:35], v[162:165], v[182:185], v[32:35]
	v_mfma_f32_16x16x32_bf16 v[28:31], v[162:165], v[186:189], v[28:31]
	v_mfma_f32_16x16x32_bf16 v[24:27], v[162:165], v[190:193], v[24:27]
	v_mfma_f32_16x16x32_bf16 v[20:23], v[166:169], v[174:177], v[20:23]
	v_mfma_f32_16x16x32_bf16 v[16:19], v[166:169], v[182:185], v[16:19]
	v_mfma_f32_16x16x32_bf16 v[12:15], v[166:169], v[186:189], v[12:15]
	v_mfma_f32_16x16x32_bf16 v[8:11], v[166:169], v[190:193], v[8:11]
	v_mfma_f32_16x16x32_bf16 v[4:7], v[170:173], v[174:177], v[4:7]
	v_mfma_f32_16x16x32_bf16 v[0:3], v[170:173], v[182:185], v[0:3]
	v_mfma_f32_16x16x32_bf16 v[40:43], v[170:173], v[186:189], v[40:43]
	v_mfma_f32_16x16x32_bf16 v[36:39], v[170:173], v[190:193], v[36:39]
	ds_read_b128 v[158:161], v180 offset:8192
	ds_read_b128 v[162:165], v180 offset:10240
	ds_read_b128 v[166:169], v180 offset:12288
	ds_read_b128 v[170:173], v180 offset:14336
	s_waitcnt lgkmcnt(4)
	v_mfma_f32_16x16x32_bf16 v[124:127], v[142:145], v[194:197], v[124:127]
	v_mfma_f32_16x16x32_bf16 v[120:123], v[142:145], v[198:201], v[120:123]
	v_mfma_f32_16x16x32_bf16 v[116:119], v[142:145], v[202:205], v[116:119]
	v_mfma_f32_16x16x32_bf16 v[112:115], v[142:145], v[206:209], v[112:115]
	v_mfma_f32_16x16x32_bf16 v[108:111], v[146:149], v[194:197], v[108:111]
	v_mfma_f32_16x16x32_bf16 v[104:107], v[146:149], v[198:201], v[104:107]
	v_mfma_f32_16x16x32_bf16 v[100:103], v[146:149], v[202:205], v[100:103]
	v_mfma_f32_16x16x32_bf16 v[96:99], v[146:149], v[206:209], v[96:99]
	v_mfma_f32_16x16x32_bf16 v[92:95], v[150:153], v[194:197], v[92:95]
	v_mfma_f32_16x16x32_bf16 v[88:91], v[150:153], v[198:201], v[88:91]
	v_mfma_f32_16x16x32_bf16 v[84:87], v[150:153], v[202:205], v[84:87]
	v_mfma_f32_16x16x32_bf16 v[80:83], v[150:153], v[206:209], v[80:83]
	v_mfma_f32_16x16x32_bf16 v[76:79], v[154:157], v[194:197], v[76:79]
	v_mfma_f32_16x16x32_bf16 v[72:75], v[154:157], v[198:201], v[72:75]
	v_mfma_f32_16x16x32_bf16 v[68:71], v[154:157], v[202:205], v[68:71]
	v_mfma_f32_16x16x32_bf16 v[64:67], v[154:157], v[206:209], v[64:67]
	s_add_u32 s36, s36, 0x80
	s_addc_u32 s37, s37, 0
	s_add_i32 s31, s31, 1
	s_cmp_lt_u32 s31, 31
	s_cbranch_scc0 .Lg11_last
	s_waitcnt lgkmcnt(0)
	v_mfma_f32_16x16x32_bf16 v[60:63], v[158:161], v[194:197], v[60:63]
	v_mfma_f32_16x16x32_bf16 v[56:59], v[158:161], v[198:201], v[56:59]
	v_mfma_f32_16x16x32_bf16 v[52:55], v[158:161], v[202:205], v[52:55]
	v_mfma_f32_16x16x32_bf16 v[48:51], v[158:161], v[206:209], v[48:51]
	s_waitcnt vmcnt(0)
	s_barrier
	s_xor_b32 s45, s45, 0x10000
	s_mov_b32 m0, s45
	s_add_u32 s38, s36, s12
	s_addc_u32 s39, s37, s13
	global_load_lds_dwordx4 v178, s[38:39]
	ds_read_b128 v[142:145], v212
	ds_read_b128 v[146:149], v212 offset:2048
	ds_read_b128 v[150:153], v212 offset:4096
	ds_read_b128 v[154:157], v212 offset:6144
	ds_read_b128 v[174:177], v214 offset:32768
	ds_read_b128 v[182:185], v214 offset:34816
	ds_read_b128 v[186:189], v214 offset:36864
	ds_read_b128 v[190:193], v214 offset:38912
	v_mfma_f32_16x16x32_bf16 v[44:47], v[162:165], v[194:197], v[44:47]
	v_mfma_f32_16x16x32_bf16 v[32:35], v[162:165], v[198:201], v[32:35]
	s_add_u32 m0, s45, 0x2000
	s_add_u32 s38, s36, s14
	s_addc_u32 s39, s37, s15
	global_load_lds_dwordx4 v178, s[38:39]
	v_mfma_f32_16x16x32_bf16 v[28:31], v[162:165], v[202:205], v[28:31]
	v_mfma_f32_16x16x32_bf16 v[24:27], v[162:165], v[206:209], v[24:27]
	s_add_u32 m0, s45, 0x4000
	s_add_u32 s38, s36, s16
	s_addc_u32 s39, s37, s17
	global_load_lds_dwordx4 v178, s[38:39]
	v_mfma_f32_16x16x32_bf16 v[20:23], v[166:169], v[194:197], v[20:23]
	v_mfma_f32_16x16x32_bf16 v[16:19], v[166:169], v[198:201], v[16:19]
	s_add_u32 m0, s45, 0x6000
	s_add_u32 s38, s36, s18
	s_addc_u32 s39, s37, s19
	global_load_lds_dwordx4 v178, s[38:39]
	v_mfma_f32_16x16x32_bf16 v[12:15], v[166:169], v[202:205], v[12:15]
	v_mfma_f32_16x16x32_bf16 v[8:11], v[166:169], v[206:209], v[8:11]
	s_add_u32 m0, s45, 0x8000
	s_add_u32 s38, s36, s22
	s_addc_u32 s39, s37, s23
	global_load_lds_dwordx4 v179, s[38:39]
	v_mfma_f32_16x16x32_bf16 v[4:7], v[170:173], v[194:197], v[4:7]
	v_mfma_f32_16x16x32_bf16 v[0:3], v[170:173], v[198:201], v[0:3]
	s_add_u32 m0, s45, 0xa000
	s_add_u32 s38, s36, s24
	s_addc_u32 s39, s37, s25
	global_load_lds_dwordx4 v179, s[38:39]
	v_mfma_f32_16x16x32_bf16 v[40:43], v[170:173], v[202:205], v[40:43]
	v_mfma_f32_16x16x32_bf16 v[36:39], v[170:173], v[206:209], v[36:39]
	s_add_u32 m0, s45, 0xc000
	s_add_u32 s38, s36, s26
	s_addc_u32 s39, s37, s27
	global_load_lds_dwordx4 v179, s[38:39]
	ds_read_b128 v[158:161], v212 offset:8192
	ds_read_b128 v[162:165], v212 offset:10240
	ds_read_b128 v[166:169], v212 offset:12288
	ds_read_b128 v[170:173], v212 offset:14336
	s_waitcnt lgkmcnt(4)
	v_mfma_f32_16x16x32_bf16 v[124:127], v[142:145], v[174:177], v[124:127]
	v_mfma_f32_16x16x32_bf16 v[120:123], v[142:145], v[182:185], v[120:123]
	s_add_u32 m0, s45, 0xe000
	s_add_u32 s38, s36, s28
	s_addc_u32 s39, s37, s29
	global_load_lds_dwordx4 v179, s[38:39]
	v_mfma_f32_16x16x32_bf16 v[116:119], v[142:145], v[186:189], v[116:119]
	v_mfma_f32_16x16x32_bf16 v[112:115], v[142:145], v[190:193], v[112:115]
	v_mfma_f32_16x16x32_bf16 v[108:111], v[146:149], v[174:177], v[108:111]
	v_mfma_f32_16x16x32_bf16 v[104:107], v[146:149], v[182:185], v[104:107]
	v_mfma_f32_16x16x32_bf16 v[100:103], v[146:149], v[186:189], v[100:103]
	v_mfma_f32_16x16x32_bf16 v[96:99], v[146:149], v[190:193], v[96:99]
	v_mfma_f32_16x16x32_bf16 v[92:95], v[150:153], v[174:177], v[92:95]
	v_mfma_f32_16x16x32_bf16 v[88:91], v[150:153], v[182:185], v[88:91]
	v_mfma_f32_16x16x32_bf16 v[84:87], v[150:153], v[186:189], v[84:87]
	v_mfma_f32_16x16x32_bf16 v[80:83], v[150:153], v[190:193], v[80:83]
	v_mfma_f32_16x16x32_bf16 v[76:79], v[154:157], v[174:177], v[76:79]
	v_mfma_f32_16x16x32_bf16 v[72:75], v[154:157], v[182:185], v[72:75]
	v_mfma_f32_16x16x32_bf16 v[68:71], v[154:157], v[186:189], v[68:71]
	v_mfma_f32_16x16x32_bf16 v[64:67], v[154:157], v[190:193], v[64:67]
	ds_read_b128 v[142:145], v213
	ds_read_b128 v[146:149], v213 offset:2048
	ds_read_b128 v[150:153], v213 offset:4096
	ds_read_b128 v[154:157], v213 offset:6144
	ds_read_b128 v[194:197], v215 offset:32768
	ds_read_b128 v[198:201], v215 offset:34816
	ds_read_b128 v[202:205], v215 offset:36864
	ds_read_b128 v[206:209], v215 offset:38912
	s_waitcnt lgkmcnt(8)
	v_mfma_f32_16x16x32_bf16 v[60:63], v[158:161], v[174:177], v[60:63]
	v_mfma_f32_16x16x32_bf16 v[56:59], v[158:161], v[182:185], v[56:59]
	v_mfma_f32_16x16x32_bf16 v[52:55], v[158:161], v[186:189], v[52:55]
	v_mfma_f32_16x16x32_bf16 v[48:51], v[158:161], v[190:193], v[48:51]
	v_mfma_f32_16x16x32_bf16 v[44:47], v[162:165], v[174:177], v[44:47]
	v_mfma_f32_16x16x32_bf16 v[32:35], v[162:165], v[182:185], v[32:35]
	v_mfma_f32_16x16x32_bf16 v[28:31], v[162:165], v[186:189], v[28:31]
	v_mfma_f32_16x16x32_bf16 v[24:27], v[162:165], v[190:193], v[24:27]
	v_mfma_f32_16x16x32_bf16 v[20:23], v[166:169], v[174:177], v[20:23]
	v_mfma_f32_16x16x32_bf16 v[16:19], v[166:169], v[182:185], v[16:19]
	v_mfma_f32_16x16x32_bf16 v[12:15], v[166:169], v[186:189], v[12:15]
	v_mfma_f32_16x16x32_bf16 v[8:11], v[166:169], v[190:193], v[8:11]
	v_mfma_f32_16x16x32_bf16 v[4:7], v[170:173], v[174:177], v[4:7]
	v_mfma_f32_16x16x32_bf16 v[0:3], v[170:173], v[182:185], v[0:3]
	v_mfma_f32_16x16x32_bf16 v[40:43], v[170:173], v[186:189], v[40:43]
	v_mfma_f32_16x16x32_bf16 v[36:39], v[170:173], v[190:193], v[36:39]
	ds_read_b128 v[158:161], v213 offset:8192
	ds_read_b128 v[162:165], v213 offset:10240
	ds_read_b128 v[166:169], v213 offset:12288
	ds_read_b128 v[170:173], v213 offset:14336
	s_waitcnt lgkmcnt(4)
	v_mfma_f32_16x16x32_bf16 v[124:127], v[142:145], v[194:197], v[124:127]
	v_mfma_f32_16x16x32_bf16 v[120:123], v[142:145], v[198:201], v[120:123]
	v_mfma_f32_16x16x32_bf16 v[116:119], v[142:145], v[202:205], v[116:119]
	v_mfma_f32_16x16x32_bf16 v[112:115], v[142:145], v[206:209], v[112:115]
	v_mfma_f32_16x16x32_bf16 v[108:111], v[146:149], v[194:197], v[108:111]
	v_mfma_f32_16x16x32_bf16 v[104:107], v[146:149], v[198:201], v[104:107]
	v_mfma_f32_16x16x32_bf16 v[100:103], v[146:149], v[202:205], v[100:103]
	v_mfma_f32_16x16x32_bf16 v[96:99], v[146:149], v[206:209], v[96:99]
	v_mfma_f32_16x16x32_bf16 v[92:95], v[150:153], v[194:197], v[92:95]
	v_mfma_f32_16x16x32_bf16 v[88:91], v[150:153], v[198:201], v[88:91]
	v_mfma_f32_16x16x32_bf16 v[84:87], v[150:153], v[202:205], v[84:87]
	v_mfma_f32_16x16x32_bf16 v[80:83], v[150:153], v[206:209], v[80:83]
	v_mfma_f32_16x16x32_bf16 v[76:79], v[154:157], v[194:197], v[76:79]
	v_mfma_f32_16x16x32_bf16 v[72:75], v[154:157], v[198:201], v[72:75]
	v_mfma_f32_16x16x32_bf16 v[68:71], v[154:157], v[202:205], v[68:71]
	v_mfma_f32_16x16x32_bf16 v[64:67], v[154:157], v[206:209], v[64:67]
	s_add_u32 s36, s36, 0x80
	s_addc_u32 s37, s37, 0
	s_add_i32 s31, s31, 1
	s_branch .Lg11_top
.Lg11_last:
	s_waitcnt lgkmcnt(0)
	v_mfma_f32_16x16x32_bf16 v[60:63], v[158:161], v[194:197], v[60:63]
	v_mfma_f32_16x16x32_bf16 v[56:59], v[158:161], v[198:201], v[56:59]
	v_mfma_f32_16x16x32_bf16 v[52:55], v[158:161], v[202:205], v[52:55]
	v_mfma_f32_16x16x32_bf16 v[48:51], v[158:161], v[206:209], v[48:51]
	s_waitcnt vmcnt(0)
	s_barrier
	s_xor_b32 s45, s45, 0x10000
	ds_read_b128 v[142:145], v212
	ds_read_b128 v[146:149], v212 offset:2048
	ds_read_b128 v[150:153], v212 offset:4096
	ds_read_b128 v[154:157], v212 offset:6144
	ds_read_b128 v[174:177], v214 offset:32768
	ds_read_b128 v[182:185], v214 offset:34816
	ds_read_b128 v[186:189], v214 offset:36864
	ds_read_b128 v[190:193], v214 offset:38912
	v_mfma_f32_16x16x32_bf16 v[44:47], v[162:165], v[194:197], v[44:47]
	v_mfma_f32_16x16x32_bf16 v[32:35], v[162:165], v[198:201], v[32:35]
	v_mfma_f32_16x16x32_bf16 v[28:31], v[162:165], v[202:205], v[28:31]
	v_mfma_f32_16x16x32_bf16 v[24:27], v[162:165], v[206:209], v[24:27]
	v_mfma_f32_16x16x32_bf16 v[20:23], v[166:169], v[194:197], v[20:23]
	v_mfma_f32_16x16x32_bf16 v[16:19], v[166:169], v[198:201], v[16:19]
	v_mfma_f32_16x16x32_bf16 v[12:15], v[166:169], v[202:205], v[12:15]
	v_mfma_f32_16x16x32_bf16 v[8:11], v[166:169], v[206:209], v[8:11]
	v_mfma_f32_16x16x32_bf16 v[4:7], v[170:173], v[194:197], v[4:7]
	v_mfma_f32_16x16x32_bf16 v[0:3], v[170:173], v[198:201], v[0:3]
	v_mfma_f32_16x16x32_bf16 v[40:43], v[170:173], v[202:205], v[40:43]
	v_mfma_f32_16x16x32_bf16 v[36:39], v[170:173], v[206:209], v[36:39]
	ds_read_b128 v[158:161], v212 offset:8192
	ds_read_b128 v[162:165], v212 offset:10240
	ds_read_b128 v[166:169], v212 offset:12288
	ds_read_b128 v[170:173], v212 offset:14336
	s_waitcnt lgkmcnt(4)
	v_mfma_f32_16x16x32_bf16 v[124:127], v[142:145], v[174:177], v[124:127]
	v_mfma_f32_16x16x32_bf16 v[120:123], v[142:145], v[182:185], v[120:123]
	v_mfma_f32_16x16x32_bf16 v[116:119], v[142:145], v[186:189], v[116:119]
	v_mfma_f32_16x16x32_bf16 v[112:115], v[142:145], v[190:193], v[112:115]
	v_mfma_f32_16x16x32_bf16 v[108:111], v[146:149], v[174:177], v[108:111]
	v_mfma_f32_16x16x32_bf16 v[104:107], v[146:149], v[182:185], v[104:107]
	v_mfma_f32_16x16x32_bf16 v[100:103], v[146:149], v[186:189], v[100:103]
	v_mfma_f32_16x16x32_bf16 v[96:99], v[146:149], v[190:193], v[96:99]
	v_mfma_f32_16x16x32_bf16 v[92:95], v[150:153], v[174:177], v[92:95]
	v_mfma_f32_16x16x32_bf16 v[88:91], v[150:153], v[182:185], v[88:91]
	v_mfma_f32_16x16x32_bf16 v[84:87], v[150:153], v[186:189], v[84:87]
	v_mfma_f32_16x16x32_bf16 v[80:83], v[150:153], v[190:193], v[80:83]
	v_mfma_f32_16x16x32_bf16 v[76:79], v[154:157], v[174:177], v[76:79]
	v_mfma_f32_16x16x32_bf16 v[72:75], v[154:157], v[182:185], v[72:75]
	v_mfma_f32_16x16x32_bf16 v[68:71], v[154:157], v[186:189], v[68:71]
	v_mfma_f32_16x16x32_bf16 v[64:67], v[154:157], v[190:193], v[64:67]
	ds_read_b128 v[142:145], v213
	ds_read_b128 v[146:149], v213 offset:2048
	ds_read_b128 v[150:153], v213 offset:4096
	ds_read_b128 v[154:157], v213 offset:6144
	ds_read_b128 v[194:197], v215 offset:32768
	ds_read_b128 v[198:201], v215 offset:34816
	ds_read_b128 v[202:205], v215 offset:36864
	ds_read_b128 v[206:209], v215 offset:38912
	s_waitcnt lgkmcnt(8)
	v_mfma_f32_16x16x32_bf16 v[60:63], v[158:161], v[174:177], v[60:63]
	v_mfma_f32_16x16x32_bf16 v[56:59], v[158:161], v[182:185], v[56:59]
	v_mfma_f32_16x16x32_bf16 v[52:55], v[158:161], v[186:189], v[52:55]
	v_mfma_f32_16x16x32_bf16 v[48:51], v[158:161], v[190:193], v[48:51]
	v_mfma_f32_16x16x32_bf16 v[44:47], v[162:165], v[174:177], v[44:47]
	v_mfma_f32_16x16x32_bf16 v[32:35], v[162:165], v[182:185], v[32:35]
	v_mfma_f32_16x16x32_bf16 v[28:31], v[162:165], v[186:189], v[28:31]
	v_mfma_f32_16x16x32_bf16 v[24:27], v[162:165], v[190:193], v[24:27]
	v_mfma_f32_16x16x32_bf16 v[20:23], v[166:169], v[174:177], v[20:23]
	v_mfma_f32_16x16x32_bf16 v[16:19], v[166:169], v[182:185], v[16:19]
	v_mfma_f32_16x16x32_bf16 v[12:15], v[166:169], v[186:189], v[12:15]
	v_mfma_f32_16x16x32_bf16 v[8:11], v[166:169], v[190:193], v[8:11]
	v_mfma_f32_16x16x32_bf16 v[4:7], v[170:173], v[174:177], v[4:7]
	v_mfma_f32_16x16x32_bf16 v[0:3], v[170:173], v[182:185], v[0:3]
	v_mfma_f32_16x16x32_bf16 v[40:43], v[170:173], v[186:189], v[40:43]
	v_mfma_f32_16x16x32_bf16 v[36:39], v[170:173], v[190:193], v[36:39]
	ds_read_b128 v[158:161], v213 offset:8192
	ds_read_b128 v[162:165], v213 offset:10240
	ds_read_b128 v[166:169], v213 offset:12288
	ds_read_b128 v[170:173], v213 offset:14336
	s_waitcnt lgkmcnt(4)
	v_mfma_f32_16x16x32_bf16 v[124:127], v[142:145], v[194:197], v[124:127]
	v_mfma_f32_16x16x32_bf16 v[120:123], v[142:145], v[198:201], v[120:123]
	v_mfma_f32_16x16x32_bf16 v[116:119], v[142:145], v[202:205], v[116:119]
	v_mfma_f32_16x16x32_bf16 v[112:115], v[142:145], v[206:209], v[112:115]
	v_mfma_f32_16x16x32_bf16 v[108:111], v[146:149], v[194:197], v[108:111]
	v_mfma_f32_16x16x32_bf16 v[104:107], v[146:149], v[198:201], v[104:107]
	v_mfma_f32_16x16x32_bf16 v[100:103], v[146:149], v[202:205], v[100:103]
	v_mfma_f32_16x16x32_bf16 v[96:99], v[146:149], v[206:209], v[96:99]
	v_mfma_f32_16x16x32_bf16 v[92:95], v[150:153], v[194:197], v[92:95]
	v_mfma_f32_16x16x32_bf16 v[88:91], v[150:153], v[198:201], v[88:91]
	v_mfma_f32_16x16x32_bf16 v[84:87], v[150:153], v[202:205], v[84:87]
	v_mfma_f32_16x16x32_bf16 v[80:83], v[150:153], v[206:209], v[80:83]
	v_mfma_f32_16x16x32_bf16 v[76:79], v[154:157], v[194:197], v[76:79]
	v_mfma_f32_16x16x32_bf16 v[72:75], v[154:157], v[198:201], v[72:75]
	v_mfma_f32_16x16x32_bf16 v[68:71], v[154:157], v[202:205], v[68:71]
	v_mfma_f32_16x16x32_bf16 v[64:67], v[154:157], v[206:209], v[64:67]
	s_add_u32 s36, s36, 0x80
	s_addc_u32 s37, s37, 0
	s_add_i32 s31, s31, 1
	s_waitcnt lgkmcnt(0)
	s_waitcnt vmcnt(0)
	s_barrier
	v_mfma_f32_16x16x32_bf16 v[60:63], v[158:161], v[194:197], v[60:63]
	v_mfma_f32_16x16x32_bf16 v[56:59], v[158:161], v[198:201], v[56:59]
	v_mfma_f32_16x16x32_bf16 v[52:55], v[158:161], v[202:205], v[52:55]
	v_mfma_f32_16x16x32_bf16 v[48:51], v[158:161], v[206:209], v[48:51]
	v_mfma_f32_16x16x32_bf16 v[44:47], v[162:165], v[194:197], v[44:47]
	v_mfma_f32_16x16x32_bf16 v[32:35], v[162:165], v[198:201], v[32:35]
	v_mfma_f32_16x16x32_bf16 v[28:31], v[162:165], v[202:205], v[28:31]
	v_mfma_f32_16x16x32_bf16 v[24:27], v[162:165], v[206:209], v[24:27]
	v_mfma_f32_16x16x32_bf16 v[20:23], v[166:169], v[194:197], v[20:23]
	v_mfma_f32_16x16x32_bf16 v[16:19], v[166:169], v[198:201], v[16:19]
	v_mfma_f32_16x16x32_bf16 v[12:15], v[166:169], v[202:205], v[12:15]
	v_mfma_f32_16x16x32_bf16 v[8:11], v[166:169], v[206:209], v[8:11]
	v_mfma_f32_16x16x32_bf16 v[4:7], v[170:173], v[194:197], v[4:7]
	v_mfma_f32_16x16x32_bf16 v[0:3], v[170:173], v[198:201], v[0:3]
	v_mfma_f32_16x16x32_bf16 v[40:43], v[170:173], v[202:205], v[40:43]
	v_mfma_f32_16x16x32_bf16 v[36:39], v[170:173], v[206:209], v[36:39]
	s_nop 7
	s_nop 7
	s_sub_u32 s36, s36, s34
	s_subb_u32 s37, s37, s35
	s_mov_b32 s45, 0x100000
	s_mov_b32 s46, 0x100000
	s_mov_b64 s[38:39], 0
	s_mov_b64 vcc, exec
	s_branch .LBB0_1635
